# v136 with low-half workgroups lowering priority after MFMA group 6 instead of 5 (re-tune under guarded barriers)
# speedup vs baseline: 1.0091x; 1.0091x over previous
; #define LWRITE(S, buf) do { bf16_t* sA_ = sbase + (buf) * BUF; bf16_t* sB_ = sA_ + 256 * PITCH; \
;     _Pragma("unroll") for (int i_ = 0; i_ < 4; ++i_) *(u32x4*)(sA_ + (sr + i_ * 64) * PITCH + scv * 8) = ra[S][i_]; \
;     _Pragma("unroll") for (int i_ = 0; i_ < 2; ++i_) *(u32x4*)(sB_ + (sr + i_ * 64) * PITCH + scv * 8) = rb[S][i_]; } while (0)
; template <class Epi>
; DI void gemm_tile(char* smem, const bf16_t* __restrict__ A0, int lda0, int ksplit, const bf16_t* __restrict__ A1, int lda1,
;                   const bf16_t* __restrict__ Bt, int K, int row0, int col0, const Epi& epi, int tid) {
;     ...
;   __syncthreads();
;   {
;     const int last = nk - 1;
;     GLOAD(0, 0);
;     __builtin_amdgcn_sched_barrier(0);
;     GLOAD(1, 1);
;     __builtin_amdgcn_sched_barrier(0);
;     LWRITE(0, 0);
;     __builtin_amdgcn_sched_barrier(0);
;     GLOAD(0, (2 < last ? 2 : last));
;     __builtin_amdgcn_sched_barrier(0);
;     __syncthreads();
;     for (int kt = 0; kt < nk; kt += 2) {
;       LWRITE(1, 1);
;       __builtin_amdgcn_sched_barrier(0);
;       GLOAD(1, (kt + 3 < last ? kt + 3 : last));
;       __builtin_amdgcn_sched_barrier(0);
;       COMPUTE(0);
;       __syncthreads();
;       LWRITE(0, 0);
;       __builtin_amdgcn_sched_barrier(0);
;       GLOAD(0, (kt + 4 < last ? kt + 4 : last));
;       __builtin_amdgcn_sched_barrier(0);
;       COMPUTE(1);
;       __syncthreads();
;     }
.Lg1_kloop:
	s_waitcnt vmcnt(6)
	s_waitcnt lgkmcnt(0)
	s_barrier
	v_add_u32_e32 v232, s31, v230
	v_add_u32_e32 v233, s31, v231
	s_add_u32 s22, s30, s100
	s_setprio 1
	v_mfma_f32_16x16x32_bf16 v[0:3], v[128:131], v[144:147], v[0:3]
	v_mfma_f32_16x16x32_bf16 v[4:7], v[132:135], v[144:147], v[4:7]
	v_mfma_f32_16x16x32_bf16 v[8:11], v[136:139], v[144:147], v[8:11]
	v_mfma_f32_16x16x32_bf16 v[12:15], v[140:143], v[144:147], v[12:15]
	ds_read_b128 v[176:179], v233 offset:0
	ds_read_b128 v[180:183], v233 offset:1024
	s_add_u32 m0, s22, 0
	s_nop 0
	global_load_lds_dwordx4 v224, s[0:1]
	v_mfma_f32_16x16x32_bf16 v[16:19], v[128:131], v[148:151], v[16:19]
	v_mfma_f32_16x16x32_bf16 v[20:23], v[132:135], v[148:151], v[20:23]
	v_mfma_f32_16x16x32_bf16 v[24:27], v[136:139], v[148:151], v[24:27]
	v_mfma_f32_16x16x32_bf16 v[28:31], v[140:143], v[148:151], v[28:31]
	ds_read_b128 v[184:187], v233 offset:2048
	ds_read_b128 v[188:191], v233 offset:3072
	s_add_u32 m0, s22, 4096
	s_nop 0
	global_load_lds_dwordx4 v225, s[0:1]
	v_mfma_f32_16x16x32_bf16 v[32:35], v[128:131], v[152:155], v[32:35]
	v_mfma_f32_16x16x32_bf16 v[36:39], v[132:135], v[152:155], v[36:39]
	v_mfma_f32_16x16x32_bf16 v[40:43], v[136:139], v[152:155], v[40:43]
	v_mfma_f32_16x16x32_bf16 v[44:47], v[140:143], v[152:155], v[44:47]
	ds_read_b128 v[192:195], v232 offset:0
	ds_read_b128 v[196:199], v232 offset:1024
	s_add_u32 m0, s22, 8192
	s_nop 0
	global_load_lds_dwordx4 v226, s[0:1]
	v_mfma_f32_16x16x32_bf16 v[48:51], v[128:131], v[156:159], v[48:51]
	v_mfma_f32_16x16x32_bf16 v[52:55], v[132:135], v[156:159], v[52:55]
	v_mfma_f32_16x16x32_bf16 v[56:59], v[136:139], v[156:159], v[56:59]
	v_mfma_f32_16x16x32_bf16 v[60:63], v[140:143], v[156:159], v[60:63]
	ds_read_b128 v[200:203], v232 offset:2048
	ds_read_b128 v[204:207], v232 offset:3072
	s_add_u32 m0, s22, 12288
	s_nop 0
	global_load_lds_dwordx4 v227, s[0:1]
	v_mfma_f32_16x16x32_bf16 v[64:67], v[128:131], v[160:163], v[64:67]
	v_mfma_f32_16x16x32_bf16 v[68:71], v[132:135], v[160:163], v[68:71]
	v_mfma_f32_16x16x32_bf16 v[72:75], v[136:139], v[160:163], v[72:75]
	v_mfma_f32_16x16x32_bf16 v[76:79], v[140:143], v[160:163], v[76:79]
	ds_read_b128 v[208:211], v232 offset:4096
	s_add_u32 m0, s22, 16384
	s_nop 0
	global_load_lds_dwordx4 v228, s[2:3]
	v_mfma_f32_16x16x32_bf16 v[80:83], v[128:131], v[164:167], v[80:83]
	v_mfma_f32_16x16x32_bf16 v[84:87], v[132:135], v[164:167], v[84:87]
	v_mfma_f32_16x16x32_bf16 v[88:91], v[136:139], v[164:167], v[88:91]
	v_mfma_f32_16x16x32_bf16 v[92:95], v[140:143], v[164:167], v[92:95]
	ds_read_b128 v[212:215], v232 offset:5120
	s_add_u32 m0, s22, 20480
	s_nop 0
	global_load_lds_dwordx4 v229, s[2:3]
	v_mfma_f32_16x16x32_bf16 v[96:99], v[128:131], v[168:171], v[96:99]
	v_mfma_f32_16x16x32_bf16 v[100:103], v[132:135], v[168:171], v[100:103]
	v_mfma_f32_16x16x32_bf16 v[104:107], v[136:139], v[168:171], v[104:107]
	v_mfma_f32_16x16x32_bf16 v[108:111], v[140:143], v[168:171], v[108:111]
	ds_read_b128 v[216:219], v232 offset:6144
	s_cmp_eq_u32 s21, 0
	s_cbranch_scc0 .Lg1_hi0
	s_setprio 0
.Lg1_hi0:
	s_add_u32 s0, s0, 64
	s_addc_u32 s1, s1, 0
	s_add_u32 s2, s2, 64
	s_addc_u32 s3, s3, 0
	s_add_u32 s99, s99, 1
	s_add_u32 s30, s30, 24576
	s_cmp_eq_u32 s30, 73728
	s_cselect_b32 s30, 0, s30
	s_add_u32 s31, s31, 24576
	s_cmp_eq_u32 s31, 73728
	s_cselect_b32 s31, 0, s31
	v_mfma_f32_16x16x32_bf16 v[112:115], v[128:131], v[172:175], v[112:115]
	v_mfma_f32_16x16x32_bf16 v[116:119], v[132:135], v[172:175], v[116:119]
	v_mfma_f32_16x16x32_bf16 v[120:123], v[136:139], v[172:175], v[120:123]
	v_mfma_f32_16x16x32_bf16 v[124:127], v[140:143], v[172:175], v[124:127]
	ds_read_b128 v[220:223], v232 offset:7168
	s_waitcnt vmcnt(6)
	s_waitcnt lgkmcnt(0)
	s_barrier
	v_add_u32_e32 v232, s31, v230
	v_add_u32_e32 v233, s31, v231
	s_add_u32 s22, s30, s100
	s_setprio 1
	v_mfma_f32_16x16x32_bf16 v[0:3], v[176:179], v[192:195], v[0:3]
	v_mfma_f32_16x16x32_bf16 v[4:7], v[180:183], v[192:195], v[4:7]
	v_mfma_f32_16x16x32_bf16 v[8:11], v[184:187], v[192:195], v[8:11]
	v_mfma_f32_16x16x32_bf16 v[12:15], v[188:191], v[192:195], v[12:15]
	ds_read_b128 v[128:131], v233 offset:0
	ds_read_b128 v[132:135], v233 offset:1024
	s_add_u32 m0, s22, 0
	s_nop 0
	global_load_lds_dwordx4 v224, s[0:1]
	v_mfma_f32_16x16x32_bf16 v[16:19], v[176:179], v[196:199], v[16:19]
	v_mfma_f32_16x16x32_bf16 v[20:23], v[180:183], v[196:199], v[20:23]
	v_mfma_f32_16x16x32_bf16 v[24:27], v[184:187], v[196:199], v[24:27]
	v_mfma_f32_16x16x32_bf16 v[28:31], v[188:191], v[196:199], v[28:31]
	ds_read_b128 v[136:139], v233 offset:2048
	ds_read_b128 v[140:143], v233 offset:3072
	s_add_u32 m0, s22, 4096
	s_nop 0
	global_load_lds_dwordx4 v225, s[0:1]
	v_mfma_f32_16x16x32_bf16 v[32:35], v[176:179], v[200:203], v[32:35]
	v_mfma_f32_16x16x32_bf16 v[36:39], v[180:183], v[200:203], v[36:39]
	v_mfma_f32_16x16x32_bf16 v[40:43], v[184:187], v[200:203], v[40:43]
	v_mfma_f32_16x16x32_bf16 v[44:47], v[188:191], v[200:203], v[44:47]
	ds_read_b128 v[144:147], v232 offset:0
	ds_read_b128 v[148:151], v232 offset:1024
	s_add_u32 m0, s22, 8192
	s_nop 0
	global_load_lds_dwordx4 v226, s[0:1]
	v_mfma_f32_16x16x32_bf16 v[48:51], v[176:179], v[204:207], v[48:51]
	v_mfma_f32_16x16x32_bf16 v[52:55], v[180:183], v[204:207], v[52:55]
	v_mfma_f32_16x16x32_bf16 v[56:59], v[184:187], v[204:207], v[56:59]
	v_mfma_f32_16x16x32_bf16 v[60:63], v[188:191], v[204:207], v[60:63]
	ds_read_b128 v[152:155], v232 offset:2048
	ds_read_b128 v[156:159], v232 offset:3072
	s_add_u32 m0, s22, 12288
	s_nop 0
	global_load_lds_dwordx4 v227, s[0:1]
	v_mfma_f32_16x16x32_bf16 v[64:67], v[176:179], v[208:211], v[64:67]
	v_mfma_f32_16x16x32_bf16 v[68:71], v[180:183], v[208:211], v[68:71]
	v_mfma_f32_16x16x32_bf16 v[72:75], v[184:187], v[208:211], v[72:75]
	v_mfma_f32_16x16x32_bf16 v[76:79], v[188:191], v[208:211], v[76:79]
	ds_read_b128 v[160:163], v232 offset:4096
	s_add_u32 m0, s22, 16384
	s_nop 0
	global_load_lds_dwordx4 v228, s[2:3]
	v_mfma_f32_16x16x32_bf16 v[80:83], v[176:179], v[212:215], v[80:83]
	v_mfma_f32_16x16x32_bf16 v[84:87], v[180:183], v[212:215], v[84:87]
	v_mfma_f32_16x16x32_bf16 v[88:91], v[184:187], v[212:215], v[88:91]
	v_mfma_f32_16x16x32_bf16 v[92:95], v[188:191], v[212:215], v[92:95]
	ds_read_b128 v[164:167], v232 offset:5120
	s_add_u32 m0, s22, 20480
	s_nop 0
	global_load_lds_dwordx4 v229, s[2:3]
	v_mfma_f32_16x16x32_bf16 v[96:99], v[176:179], v[216:219], v[96:99]
	v_mfma_f32_16x16x32_bf16 v[100:103], v[180:183], v[216:219], v[100:103]
	v_mfma_f32_16x16x32_bf16 v[104:107], v[184:187], v[216:219], v[104:107]
	v_mfma_f32_16x16x32_bf16 v[108:111], v[188:191], v[216:219], v[108:111]
	ds_read_b128 v[168:171], v232 offset:6144
	s_cmp_eq_u32 s21, 0
	s_cbranch_scc0 .Lg1_hi1
	s_setprio 0
; #define LWRITE(S, buf) do { bf16_t* sA_ = sbase + (buf) * BUF; bf16_t* sB_ = sA_ + 256 * PITCH; \
;     _Pragma("unroll") for (int i_ = 0; i_ < 4; ++i_) *(u32x4*)(sA_ + (sr + i_ * 64) * PITCH + scv * 8) = ra[S][i_]; \
;     _Pragma("unroll") for (int i_ = 0; i_ < 2; ++i_) *(u32x4*)(sB_ + (sr + i_ * 64) * PITCH + scv * 8) = rb[S][i_]; } while (0)
; template <class Epi>
; DI void gemm_tile(char* smem, const bf16_t* __restrict__ A0, int lda0, int ksplit, const bf16_t* __restrict__ A1, int lda1,
;                   const bf16_t* __restrict__ Bt, int K, int row0, int col0, const Epi& epi, int tid) {
;     ...
;   __syncthreads();
;   {
;     const int last = nk - 1;
;     GLOAD(0, 0);
;     __builtin_amdgcn_sched_barrier(0);
;     GLOAD(1, 1);
;     __builtin_amdgcn_sched_barrier(0);
;     LWRITE(0, 0);
;     __builtin_amdgcn_sched_barrier(0);
;     GLOAD(0, (2 < last ? 2 : last));
;     __builtin_amdgcn_sched_barrier(0);
;     __syncthreads();
;     for (int kt = 0; kt < nk; kt += 2) {
;       LWRITE(1, 1);
;       __builtin_amdgcn_sched_barrier(0);
;       GLOAD(1, (kt + 3 < last ? kt + 3 : last));
;       __builtin_amdgcn_sched_barrier(0);
;       COMPUTE(0);
;       __syncthreads();
;       LWRITE(0, 0);
;       __builtin_amdgcn_sched_barrier(0);
;       GLOAD(0, (kt + 4 < last ? kt + 4 : last));
;       __builtin_amdgcn_sched_barrier(0);
;       COMPUTE(1);
;       __syncthreads();
;     }
.Lg1_hi1:
	s_add_u32 s0, s0, 64
	s_addc_u32 s1, s1, 0
	s_add_u32 s2, s2, 64
	s_addc_u32 s3, s3, 0
	s_add_u32 s99, s99, 1
	s_add_u32 s30, s30, 24576
	s_cmp_eq_u32 s30, 73728
	s_cselect_b32 s30, 0, s30
	s_add_u32 s31, s31, 24576
	s_cmp_eq_u32 s31, 73728
	s_cselect_b32 s31, 0, s31
	v_mfma_f32_16x16x32_bf16 v[112:115], v[176:179], v[220:223], v[112:115]
	v_mfma_f32_16x16x32_bf16 v[116:119], v[180:183], v[220:223], v[116:119]
	v_mfma_f32_16x16x32_bf16 v[120:123], v[184:187], v[220:223], v[120:123]
	v_mfma_f32_16x16x32_bf16 v[124:127], v[188:191], v[220:223], v[124:127]
	ds_read_b128 v[172:175], v232 offset:7168
	s_add_u32 s98, s98, 2
	s_cmp_lt_u32 s98, 28
	s_cbranch_scc1 .Lg1_kloop
	s_waitcnt vmcnt(6)
	s_waitcnt lgkmcnt(0)
	s_barrier
	v_add_u32_e32 v232, s31, v230
	v_add_u32_e32 v233, s31, v231
	s_add_u32 s22, s30, s100
	s_setprio 1
	v_mfma_f32_16x16x32_bf16 v[0:3], v[128:131], v[144:147], v[0:3]
	v_mfma_f32_16x16x32_bf16 v[4:7], v[132:135], v[144:147], v[4:7]
	v_mfma_f32_16x16x32_bf16 v[8:11], v[136:139], v[144:147], v[8:11]
	v_mfma_f32_16x16x32_bf16 v[12:15], v[140:143], v[144:147], v[12:15]
	ds_read_b128 v[176:179], v233 offset:0
	ds_read_b128 v[180:183], v233 offset:1024
	s_add_u32 m0, s22, 0
	s_nop 0
	global_load_lds_dwordx4 v224, s[0:1]
	v_mfma_f32_16x16x32_bf16 v[16:19], v[128:131], v[148:151], v[16:19]
	v_mfma_f32_16x16x32_bf16 v[20:23], v[132:135], v[148:151], v[20:23]
	v_mfma_f32_16x16x32_bf16 v[24:27], v[136:139], v[148:151], v[24:27]
	v_mfma_f32_16x16x32_bf16 v[28:31], v[140:143], v[148:151], v[28:31]
	ds_read_b128 v[184:187], v233 offset:2048
	ds_read_b128 v[188:191], v233 offset:3072
	s_add_u32 m0, s22, 4096
	s_nop 0
	global_load_lds_dwordx4 v225, s[0:1]
	v_mfma_f32_16x16x32_bf16 v[32:35], v[128:131], v[152:155], v[32:35]
	v_mfma_f32_16x16x32_bf16 v[36:39], v[132:135], v[152:155], v[36:39]
	v_mfma_f32_16x16x32_bf16 v[40:43], v[136:139], v[152:155], v[40:43]
	v_mfma_f32_16x16x32_bf16 v[44:47], v[140:143], v[152:155], v[44:47]
	ds_read_b128 v[192:195], v232 offset:0
	ds_read_b128 v[196:199], v232 offset:1024
	s_add_u32 m0, s22, 8192
	s_nop 0
	global_load_lds_dwordx4 v226, s[0:1]
	v_mfma_f32_16x16x32_bf16 v[48:51], v[128:131], v[156:159], v[48:51]
	v_mfma_f32_16x16x32_bf16 v[52:55], v[132:135], v[156:159], v[52:55]
	v_mfma_f32_16x16x32_bf16 v[56:59], v[136:139], v[156:159], v[56:59]
	v_mfma_f32_16x16x32_bf16 v[60:63], v[140:143], v[156:159], v[60:63]
	ds_read_b128 v[200:203], v232 offset:2048
	ds_read_b128 v[204:207], v232 offset:3072
	s_add_u32 m0, s22, 12288
	s_nop 0
	global_load_lds_dwordx4 v227, s[0:1]
	v_mfma_f32_16x16x32_bf16 v[64:67], v[128:131], v[160:163], v[64:67]
	v_mfma_f32_16x16x32_bf16 v[68:71], v[132:135], v[160:163], v[68:71]
	v_mfma_f32_16x16x32_bf16 v[72:75], v[136:139], v[160:163], v[72:75]
	v_mfma_f32_16x16x32_bf16 v[76:79], v[140:143], v[160:163], v[76:79]
	ds_read_b128 v[208:211], v232 offset:4096
	s_add_u32 m0, s22, 16384
	s_nop 0
	global_load_lds_dwordx4 v228, s[2:3]
	v_mfma_f32_16x16x32_bf16 v[80:83], v[128:131], v[164:167], v[80:83]
	v_mfma_f32_16x16x32_bf16 v[84:87], v[132:135], v[164:167], v[84:87]
	v_mfma_f32_16x16x32_bf16 v[88:91], v[136:139], v[164:167], v[88:91]
	v_mfma_f32_16x16x32_bf16 v[92:95], v[140:143], v[164:167], v[92:95]
	ds_read_b128 v[212:215], v232 offset:5120
	s_add_u32 m0, s22, 20480
	s_nop 0
	global_load_lds_dwordx4 v229, s[2:3]
	v_mfma_f32_16x16x32_bf16 v[96:99], v[128:131], v[168:171], v[96:99]
	v_mfma_f32_16x16x32_bf16 v[100:103], v[132:135], v[168:171], v[100:103]
	v_mfma_f32_16x16x32_bf16 v[104:107], v[136:139], v[168:171], v[104:107]
	v_mfma_f32_16x16x32_bf16 v[108:111], v[140:143], v[168:171], v[108:111]
	ds_read_b128 v[216:219], v232 offset:6144
	s_cmp_eq_u32 s21, 0
	s_cbranch_scc0 .Lg1_hi2
	s_setprio 0
.Lg1_hi2:
	s_add_u32 s0, s0, 64
	s_addc_u32 s1, s1, 0
	s_add_u32 s2, s2, 64
	s_addc_u32 s3, s3, 0
	s_add_u32 s99, s99, 1
	s_add_u32 s30, s30, 24576
	s_cmp_eq_u32 s30, 73728
	s_cselect_b32 s30, 0, s30
	s_add_u32 s31, s31, 24576
	s_cmp_eq_u32 s31, 73728
	s_cselect_b32 s31, 0, s31
	v_mfma_f32_16x16x32_bf16 v[112:115], v[128:131], v[172:175], v[112:115]
	v_mfma_f32_16x16x32_bf16 v[116:119], v[132:135], v[172:175], v[116:119]
	v_mfma_f32_16x16x32_bf16 v[120:123], v[136:139], v[172:175], v[120:123]
	v_mfma_f32_16x16x32_bf16 v[124:127], v[140:143], v[172:175], v[124:127]
	ds_read_b128 v[220:223], v232 offset:7168
	s_waitcnt vmcnt(6)
	s_waitcnt lgkmcnt(0)
	s_barrier
	v_add_u32_e32 v232, s31, v230
	v_add_u32_e32 v233, s31, v231
	s_setprio 1
	v_mfma_f32_16x16x32_bf16 v[0:3], v[176:179], v[192:195], v[0:3]
	v_mfma_f32_16x16x32_bf16 v[4:7], v[180:183], v[192:195], v[4:7]
	v_mfma_f32_16x16x32_bf16 v[8:11], v[184:187], v[192:195], v[8:11]
	v_mfma_f32_16x16x32_bf16 v[12:15], v[188:191], v[192:195], v[12:15]
	ds_read_b128 v[128:131], v233 offset:0
	ds_read_b128 v[132:135], v233 offset:1024
	v_mfma_f32_16x16x32_bf16 v[16:19], v[176:179], v[196:199], v[16:19]
	v_mfma_f32_16x16x32_bf16 v[20:23], v[180:183], v[196:199], v[20:23]
	v_mfma_f32_16x16x32_bf16 v[24:27], v[184:187], v[196:199], v[24:27]
	v_mfma_f32_16x16x32_bf16 v[28:31], v[188:191], v[196:199], v[28:31]
	ds_read_b128 v[136:139], v233 offset:2048
	ds_read_b128 v[140:143], v233 offset:3072
	v_mfma_f32_16x16x32_bf16 v[32:35], v[176:179], v[200:203], v[32:35]
	v_mfma_f32_16x16x32_bf16 v[36:39], v[180:183], v[200:203], v[36:39]
	v_mfma_f32_16x16x32_bf16 v[40:43], v[184:187], v[200:203], v[40:43]
	v_mfma_f32_16x16x32_bf16 v[44:47], v[188:191], v[200:203], v[44:47]
	ds_read_b128 v[144:147], v232 offset:0
	ds_read_b128 v[148:151], v232 offset:1024
	v_mfma_f32_16x16x32_bf16 v[48:51], v[176:179], v[204:207], v[48:51]
	v_mfma_f32_16x16x32_bf16 v[52:55], v[180:183], v[204:207], v[52:55]
	v_mfma_f32_16x16x32_bf16 v[56:59], v[184:187], v[204:207], v[56:59]
	v_mfma_f32_16x16x32_bf16 v[60:63], v[188:191], v[204:207], v[60:63]
	ds_read_b128 v[152:155], v232 offset:2048
	ds_read_b128 v[156:159], v232 offset:3072
	v_mfma_f32_16x16x32_bf16 v[64:67], v[176:179], v[208:211], v[64:67]
	v_mfma_f32_16x16x32_bf16 v[68:71], v[180:183], v[208:211], v[68:71]
	v_mfma_f32_16x16x32_bf16 v[72:75], v[184:187], v[208:211], v[72:75]
	v_mfma_f32_16x16x32_bf16 v[76:79], v[188:191], v[208:211], v[76:79]
	ds_read_b128 v[160:163], v232 offset:4096
	v_mfma_f32_16x16x32_bf16 v[80:83], v[176:179], v[212:215], v[80:83]
	v_mfma_f32_16x16x32_bf16 v[84:87], v[180:183], v[212:215], v[84:87]
	v_mfma_f32_16x16x32_bf16 v[88:91], v[184:187], v[212:215], v[88:91]
	v_mfma_f32_16x16x32_bf16 v[92:95], v[188:191], v[212:215], v[92:95]
	ds_read_b128 v[164:167], v232 offset:5120
	v_mfma_f32_16x16x32_bf16 v[96:99], v[176:179], v[216:219], v[96:99]
	v_mfma_f32_16x16x32_bf16 v[100:103], v[180:183], v[216:219], v[100:103]
	v_mfma_f32_16x16x32_bf16 v[104:107], v[184:187], v[216:219], v[104:107]
	v_mfma_f32_16x16x32_bf16 v[108:111], v[188:191], v[216:219], v[108:111]
	ds_read_b128 v[168:171], v232 offset:6144
	s_cmp_eq_u32 s21, 0
	s_cbranch_scc0 .Lg1_hi3
	s_setprio 0
; #define LWRITE(S, buf) do { bf16_t* sA_ = sbase + (buf) * BUF; bf16_t* sB_ = sA_ + 256 * PITCH; \
;     _Pragma("unroll") for (int i_ = 0; i_ < 4; ++i_) *(u32x4*)(sA_ + (sr + i_ * 64) * PITCH + scv * 8) = ra[S][i_]; \
;     _Pragma("unroll") for (int i_ = 0; i_ < 2; ++i_) *(u32x4*)(sB_ + (sr + i_ * 64) * PITCH + scv * 8) = rb[S][i_]; } while (0)
; template <class Epi>
; DI void gemm_tile(char* smem, const bf16_t* __restrict__ A0, int lda0, int ksplit, const bf16_t* __restrict__ A1, int lda1,
;                   const bf16_t* __restrict__ Bt, int K, int row0, int col0, const Epi& epi, int tid) {
;     ...
;   __syncthreads();
;   {
;     const int last = nk - 1;
;     GLOAD(0, 0);
;     __builtin_amdgcn_sched_barrier(0);
;     GLOAD(1, 1);
;     __builtin_amdgcn_sched_barrier(0);
;     LWRITE(0, 0);
;     __builtin_amdgcn_sched_barrier(0);
;     GLOAD(0, (2 < last ? 2 : last));
;     __builtin_amdgcn_sched_barrier(0);
;     __syncthreads();
;     for (int kt = 0; kt < nk; kt += 2) {
;       LWRITE(1, 1);
;       __builtin_amdgcn_sched_barrier(0);
;       GLOAD(1, (kt + 3 < last ? kt + 3 : last));
;       __builtin_amdgcn_sched_barrier(0);
;       COMPUTE(0);
;       __syncthreads();
;       LWRITE(0, 0);
;       __builtin_amdgcn_sched_barrier(0);
;       GLOAD(0, (kt + 4 < last ? kt + 4 : last));
;       __builtin_amdgcn_sched_barrier(0);
;       COMPUTE(1);
;       __syncthreads();
;     }
.Lg1_hi3:
	s_add_u32 s31, s31, 24576
	s_cmp_eq_u32 s31, 73728
	s_cselect_b32 s31, 0, s31
	v_mfma_f32_16x16x32_bf16 v[112:115], v[176:179], v[220:223], v[112:115]
	v_mfma_f32_16x16x32_bf16 v[116:119], v[180:183], v[220:223], v[116:119]
	v_mfma_f32_16x16x32_bf16 v[120:123], v[184:187], v[220:223], v[120:123]
	v_mfma_f32_16x16x32_bf16 v[124:127], v[188:191], v[220:223], v[124:127]
	ds_read_b128 v[172:175], v232 offset:7168
	s_waitcnt vmcnt(0)
	s_waitcnt lgkmcnt(0)
	s_barrier
	v_add_u32_e32 v232, s31, v230
	v_add_u32_e32 v233, s31, v231
	s_setprio 1
	v_mfma_f32_16x16x32_bf16 v[0:3], v[128:131], v[144:147], v[0:3]
	v_mfma_f32_16x16x32_bf16 v[4:7], v[132:135], v[144:147], v[4:7]
	v_mfma_f32_16x16x32_bf16 v[8:11], v[136:139], v[144:147], v[8:11]
	v_mfma_f32_16x16x32_bf16 v[12:15], v[140:143], v[144:147], v[12:15]
	ds_read_b128 v[176:179], v233 offset:0
	ds_read_b128 v[180:183], v233 offset:1024
	v_mfma_f32_16x16x32_bf16 v[16:19], v[128:131], v[148:151], v[16:19]
	v_mfma_f32_16x16x32_bf16 v[20:23], v[132:135], v[148:151], v[20:23]
	v_mfma_f32_16x16x32_bf16 v[24:27], v[136:139], v[148:151], v[24:27]
	v_mfma_f32_16x16x32_bf16 v[28:31], v[140:143], v[148:151], v[28:31]
	ds_read_b128 v[184:187], v233 offset:2048
	ds_read_b128 v[188:191], v233 offset:3072
	v_mfma_f32_16x16x32_bf16 v[32:35], v[128:131], v[152:155], v[32:35]
	v_mfma_f32_16x16x32_bf16 v[36:39], v[132:135], v[152:155], v[36:39]
	v_mfma_f32_16x16x32_bf16 v[40:43], v[136:139], v[152:155], v[40:43]
	v_mfma_f32_16x16x32_bf16 v[44:47], v[140:143], v[152:155], v[44:47]
	ds_read_b128 v[192:195], v232 offset:0
	ds_read_b128 v[196:199], v232 offset:1024
	v_mfma_f32_16x16x32_bf16 v[48:51], v[128:131], v[156:159], v[48:51]
	v_mfma_f32_16x16x32_bf16 v[52:55], v[132:135], v[156:159], v[52:55]
	v_mfma_f32_16x16x32_bf16 v[56:59], v[136:139], v[156:159], v[56:59]
	v_mfma_f32_16x16x32_bf16 v[60:63], v[140:143], v[156:159], v[60:63]
	ds_read_b128 v[200:203], v232 offset:2048
	ds_read_b128 v[204:207], v232 offset:3072
	v_mfma_f32_16x16x32_bf16 v[64:67], v[128:131], v[160:163], v[64:67]
	v_mfma_f32_16x16x32_bf16 v[68:71], v[132:135], v[160:163], v[68:71]
	v_mfma_f32_16x16x32_bf16 v[72:75], v[136:139], v[160:163], v[72:75]
	v_mfma_f32_16x16x32_bf16 v[76:79], v[140:143], v[160:163], v[76:79]
	ds_read_b128 v[208:211], v232 offset:4096
	v_mfma_f32_16x16x32_bf16 v[80:83], v[128:131], v[164:167], v[80:83]
	v_mfma_f32_16x16x32_bf16 v[84:87], v[132:135], v[164:167], v[84:87]
	v_mfma_f32_16x16x32_bf16 v[88:91], v[136:139], v[164:167], v[88:91]
	v_mfma_f32_16x16x32_bf16 v[92:95], v[140:143], v[164:167], v[92:95]
	ds_read_b128 v[212:215], v232 offset:5120
	v_mfma_f32_16x16x32_bf16 v[96:99], v[128:131], v[168:171], v[96:99]
	v_mfma_f32_16x16x32_bf16 v[100:103], v[132:135], v[168:171], v[100:103]
	v_mfma_f32_16x16x32_bf16 v[104:107], v[136:139], v[168:171], v[104:107]
	v_mfma_f32_16x16x32_bf16 v[108:111], v[140:143], v[168:171], v[108:111]
	ds_read_b128 v[216:219], v232 offset:6144
	s_cmp_eq_u32 s21, 0
	s_cbranch_scc0 .Lg1_hi4
	s_setprio 0
.Lg1_hi4:
	s_add_u32 s31, s31, 24576
	s_cmp_eq_u32 s31, 73728
	s_cselect_b32 s31, 0, s31
	v_mfma_f32_16x16x32_bf16 v[112:115], v[128:131], v[172:175], v[112:115]
	v_mfma_f32_16x16x32_bf16 v[116:119], v[132:135], v[172:175], v[116:119]
	v_mfma_f32_16x16x32_bf16 v[120:123], v[136:139], v[172:175], v[120:123]
	v_mfma_f32_16x16x32_bf16 v[124:127], v[140:143], v[172:175], v[124:127]
	ds_read_b128 v[220:223], v232 offset:7168
	s_waitcnt lgkmcnt(0)
	s_barrier
	s_setprio 1
	v_mfma_f32_16x16x32_bf16 v[0:3], v[176:179], v[192:195], v[0:3]
	v_mfma_f32_16x16x32_bf16 v[4:7], v[180:183], v[192:195], v[4:7]
	v_mfma_f32_16x16x32_bf16 v[8:11], v[184:187], v[192:195], v[8:11]
	v_mfma_f32_16x16x32_bf16 v[12:15], v[188:191], v[192:195], v[12:15]
	v_mfma_f32_16x16x32_bf16 v[16:19], v[176:179], v[196:199], v[16:19]
	v_mfma_f32_16x16x32_bf16 v[20:23], v[180:183], v[196:199], v[20:23]
	v_mfma_f32_16x16x32_bf16 v[24:27], v[184:187], v[196:199], v[24:27]
	v_mfma_f32_16x16x32_bf16 v[28:31], v[188:191], v[196:199], v[28:31]
	v_mfma_f32_16x16x32_bf16 v[32:35], v[176:179], v[200:203], v[32:35]
	v_mfma_f32_16x16x32_bf16 v[36:39], v[180:183], v[200:203], v[36:39]
	v_mfma_f32_16x16x32_bf16 v[40:43], v[184:187], v[200:203], v[40:43]
	v_mfma_f32_16x16x32_bf16 v[44:47], v[188:191], v[200:203], v[44:47]
	v_mfma_f32_16x16x32_bf16 v[48:51], v[176:179], v[204:207], v[48:51]
	v_mfma_f32_16x16x32_bf16 v[52:55], v[180:183], v[204:207], v[52:55]
	v_mfma_f32_16x16x32_bf16 v[56:59], v[184:187], v[204:207], v[56:59]
	v_mfma_f32_16x16x32_bf16 v[60:63], v[188:191], v[204:207], v[60:63]
	v_mfma_f32_16x16x32_bf16 v[64:67], v[176:179], v[208:211], v[64:67]
	v_mfma_f32_16x16x32_bf16 v[68:71], v[180:183], v[208:211], v[68:71]
	v_mfma_f32_16x16x32_bf16 v[72:75], v[184:187], v[208:211], v[72:75]
	v_mfma_f32_16x16x32_bf16 v[76:79], v[188:191], v[208:211], v[76:79]
	v_mfma_f32_16x16x32_bf16 v[80:83], v[176:179], v[212:215], v[80:83]
	v_mfma_f32_16x16x32_bf16 v[84:87], v[180:183], v[212:215], v[84:87]
	v_mfma_f32_16x16x32_bf16 v[88:91], v[184:187], v[212:215], v[88:91]
	v_mfma_f32_16x16x32_bf16 v[92:95], v[188:191], v[212:215], v[92:95]
	v_mfma_f32_16x16x32_bf16 v[96:99], v[176:179], v[216:219], v[96:99]
	v_mfma_f32_16x16x32_bf16 v[100:103], v[180:183], v[216:219], v[100:103]
	v_mfma_f32_16x16x32_bf16 v[104:107], v[184:187], v[216:219], v[104:107]
	v_mfma_f32_16x16x32_bf16 v[108:111], v[188:191], v[216:219], v[108:111]
	s_cmp_eq_u32 s21, 0
	s_cbranch_scc0 .Lg1_hi5
	s_setprio 0
.Lg1_hi5:
	v_mfma_f32_16x16x32_bf16 v[112:115], v[176:179], v[220:223], v[112:115]
	v_mfma_f32_16x16x32_bf16 v[116:119], v[180:183], v[220:223], v[116:119]
	v_mfma_f32_16x16x32_bf16 v[120:123], v[184:187], v[220:223], v[120:123]
	v_mfma_f32_16x16x32_bf16 v[124:127], v[188:191], v[220:223], v[124:127]
	s_branch .Lg1_epi

; #define LWRITE(S, buf) do { bf16_t* sA_ = sbase + (buf) * BUF; bf16_t* sB_ = sA_ + 256 * PITCH; \
;     _Pragma("unroll") for (int i_ = 0; i_ < 4; ++i_) *(u32x4*)(sA_ + (sr + i_ * 64) * PITCH + scv * 8) = ra[S][i_]; \
;     _Pragma("unroll") for (int i_ = 0; i_ < 2; ++i_) *(u32x4*)(sB_ + (sr + i_ * 64) * PITCH + scv * 8) = rb[S][i_]; } while (0)
; template <class Epi>
; DI void gemm_tile(char* smem, const bf16_t* __restrict__ A0, int lda0, int ksplit, const bf16_t* __restrict__ A1, int lda1,
;                   const bf16_t* __restrict__ Bt, int K, int row0, int col0, const Epi& epi, int tid) {
;     ...
;   __syncthreads();
;   {
;     const int last = nk - 1;
;     GLOAD(0, 0);
;     __builtin_amdgcn_sched_barrier(0);
;     GLOAD(1, 1);
;     __builtin_amdgcn_sched_barrier(0);
;     LWRITE(0, 0);
;     __builtin_amdgcn_sched_barrier(0);
;     GLOAD(0, (2 < last ? 2 : last));
;     __builtin_amdgcn_sched_barrier(0);
;     __syncthreads();
; template <class Epi>
; DI void gemm_phase(char* smem, const bf16_t* A0, int lda0, int ksplit, const bf16_t* A1, int lda1, const bf16_t* Bt, int K, int nN, const Epi& epi, int tid) {
;     ...
;     const int x = blockIdx.x & 7, l = blockIdx.x >> 3, L = G >> 3, per = 8 * nN, tot = 2 * per;
;     for (int q = l; q < tot; q += L) { const int rgl = q / per, rem = q % per, ct = rem >> 3, rt = (x * 2 + rgl) * 8 + (rem & 7);
;       gemm_tile(smem, A0, lda0, ksplit, A1, lda1, Bt, K, rt * 256, ct * 128, epi, tid); }
.Lg3a_tile:
	s_cmpk_ge_u32 s15, 64
	s_cbranch_scc1 .Lg3a_done
	s_cmpk_ge_u32 s15, 32
	s_cselect_b32 s27, 1, 0
	s_cselect_b32 s26, 32, 0
	s_sub_u32 s26, s15, s26
	s_add_u32 s27, s27, s101
	s_lshl_b32 s27, s27, 3
	s_and_b32 s29, s26, 7
	s_add_u32 s29, s29, s27
	s_lshl_b32 s29, s29, 8
	s_lshr_b32 s28, s26, 3
	s_lshl_b32 s28, s28, 7
	s_mul_i32 s27, s29, 512
	s_add_u32 s27, s27, 0x1ea00000
	s_add_u32 s0, s92, s27
	s_addc_u32 s1, s93, 0
	s_mul_i32 s27, s28, 128
	s_add_u32 s27, s27, 0x34a0000
	s_add_u32 s2, s92, s27
	s_addc_u32 s3, s93, 0
	s_waitcnt lgkmcnt(0)
	s_barrier
	s_mov_b32 s99, 0
	s_mov_b32 s30, 0
	s_add_u32 s26, s30, s100
	s_add_u32 m0, s26, 0
	s_nop 0
	global_load_lds_dwordx4 v224, s[0:1]
	s_add_u32 m0, s26, 4096
	s_nop 0
	global_load_lds_dwordx4 v225, s[0:1]
	s_add_u32 m0, s26, 8192
	s_nop 0
	global_load_lds_dwordx4 v226, s[0:1]
	s_add_u32 m0, s26, 12288
	s_nop 0
	global_load_lds_dwordx4 v227, s[0:1]
	s_add_u32 m0, s26, 16384
	s_nop 0
	global_load_lds_dwordx4 v228, s[2:3]
	s_add_u32 m0, s26, 20480
	s_nop 0
	global_load_lds_dwordx4 v229, s[2:3]
	s_add_u32 s0, s0, 64
	s_addc_u32 s1, s1, 0
	s_add_u32 s2, s2, 64
	s_addc_u32 s3, s3, 0
	s_add_u32 s99, s99, 1
	s_add_u32 s30, s30, 24576
	s_cmp_eq_u32 s30, 73728
	s_cselect_b32 s30, 0, s30
	s_add_u32 s26, s30, s100
	s_add_u32 m0, s26, 0
	s_nop 0
	global_load_lds_dwordx4 v224, s[0:1]
	s_add_u32 m0, s26, 4096
	s_nop 0
	global_load_lds_dwordx4 v225, s[0:1]
	s_add_u32 m0, s26, 8192
	s_nop 0
	global_load_lds_dwordx4 v226, s[0:1]
	s_add_u32 m0, s26, 12288
	s_nop 0
	global_load_lds_dwordx4 v227, s[0:1]
	s_add_u32 m0, s26, 16384
	s_nop 0
	global_load_lds_dwordx4 v228, s[2:3]
	s_add_u32 m0, s26, 20480
	s_nop 0
	global_load_lds_dwordx4 v229, s[2:3]
	s_add_u32 s0, s0, 64
	s_addc_u32 s1, s1, 0
	s_add_u32 s2, s2, 64
	s_addc_u32 s3, s3, 0
	s_add_u32 s99, s99, 1
	s_add_u32 s30, s30, 24576
	s_cmp_eq_u32 s30, 73728
	s_cselect_b32 s30, 0, s30
	v_mov_b32_e32 v0, 0
	v_mov_b32_e32 v1, 0
	v_mov_b32_e32 v2, 0
	v_mov_b32_e32 v3, 0
	v_mov_b32_e32 v4, 0
	v_mov_b32_e32 v5, 0
	v_mov_b32_e32 v6, 0
	v_mov_b32_e32 v7, 0
	v_mov_b32_e32 v8, 0
	v_mov_b32_e32 v9, 0
	v_mov_b32_e32 v10, 0
	v_mov_b32_e32 v11, 0
	v_mov_b32_e32 v12, 0
	v_mov_b32_e32 v13, 0
	v_mov_b32_e32 v14, 0
	v_mov_b32_e32 v15, 0
	v_mov_b32_e32 v16, 0
	v_mov_b32_e32 v17, 0
	v_mov_b32_e32 v18, 0
	v_mov_b32_e32 v19, 0
	v_mov_b32_e32 v20, 0
	v_mov_b32_e32 v21, 0
	v_mov_b32_e32 v22, 0
	v_mov_b32_e32 v23, 0
	v_mov_b32_e32 v24, 0
	v_mov_b32_e32 v25, 0
	v_mov_b32_e32 v26, 0
	v_mov_b32_e32 v27, 0
	v_mov_b32_e32 v28, 0
	v_mov_b32_e32 v29, 0
	v_mov_b32_e32 v30, 0
	v_mov_b32_e32 v31, 0
	v_mov_b32_e32 v32, 0
	v_mov_b32_e32 v33, 0
	v_mov_b32_e32 v34, 0
	v_mov_b32_e32 v35, 0
	v_mov_b32_e32 v36, 0
	v_mov_b32_e32 v37, 0
	v_mov_b32_e32 v38, 0
	v_mov_b32_e32 v39, 0
	v_mov_b32_e32 v40, 0
	v_mov_b32_e32 v41, 0
	v_mov_b32_e32 v42, 0
	v_mov_b32_e32 v43, 0
	v_mov_b32_e32 v44, 0
	v_mov_b32_e32 v45, 0
	v_mov_b32_e32 v46, 0
	v_mov_b32_e32 v47, 0
	v_mov_b32_e32 v48, 0
	v_mov_b32_e32 v49, 0
	v_mov_b32_e32 v50, 0
	v_mov_b32_e32 v51, 0
	v_mov_b32_e32 v52, 0
	v_mov_b32_e32 v53, 0
	v_mov_b32_e32 v54, 0
	v_mov_b32_e32 v55, 0
	v_mov_b32_e32 v56, 0
	v_mov_b32_e32 v57, 0
	v_mov_b32_e32 v58, 0
	v_mov_b32_e32 v59, 0
	v_mov_b32_e32 v60, 0
	v_mov_b32_e32 v61, 0
	v_mov_b32_e32 v62, 0
	v_mov_b32_e32 v63, 0
	v_mov_b32_e32 v64, 0
	v_mov_b32_e32 v65, 0
	v_mov_b32_e32 v66, 0
	v_mov_b32_e32 v67, 0
	v_mov_b32_e32 v68, 0
	v_mov_b32_e32 v69, 0
	v_mov_b32_e32 v70, 0
	v_mov_b32_e32 v71, 0
	v_mov_b32_e32 v72, 0
	v_mov_b32_e32 v73, 0
	v_mov_b32_e32 v74, 0
	v_mov_b32_e32 v75, 0
	v_mov_b32_e32 v76, 0
	v_mov_b32_e32 v77, 0
	v_mov_b32_e32 v78, 0
	v_mov_b32_e32 v79, 0
	v_mov_b32_e32 v80, 0
	v_mov_b32_e32 v81, 0
	v_mov_b32_e32 v82, 0
	v_mov_b32_e32 v83, 0
	v_mov_b32_e32 v84, 0
	v_mov_b32_e32 v85, 0
	v_mov_b32_e32 v86, 0
	v_mov_b32_e32 v87, 0
	v_mov_b32_e32 v88, 0
	v_mov_b32_e32 v89, 0
	v_mov_b32_e32 v90, 0
	v_mov_b32_e32 v91, 0
	v_mov_b32_e32 v92, 0
	v_mov_b32_e32 v93, 0
	v_mov_b32_e32 v94, 0
	v_mov_b32_e32 v95, 0
	v_mov_b32_e32 v96, 0
	v_mov_b32_e32 v97, 0
	v_mov_b32_e32 v98, 0
	v_mov_b32_e32 v99, 0
	v_mov_b32_e32 v100, 0
	v_mov_b32_e32 v101, 0
	v_mov_b32_e32 v102, 0
	v_mov_b32_e32 v103, 0
	v_mov_b32_e32 v104, 0
	v_mov_b32_e32 v105, 0
	v_mov_b32_e32 v106, 0
	v_mov_b32_e32 v107, 0
	v_mov_b32_e32 v108, 0
	v_mov_b32_e32 v109, 0
	v_mov_b32_e32 v110, 0
	v_mov_b32_e32 v111, 0
	v_mov_b32_e32 v112, 0
	v_mov_b32_e32 v113, 0
	v_mov_b32_e32 v114, 0
	v_mov_b32_e32 v115, 0
	v_mov_b32_e32 v116, 0
	v_mov_b32_e32 v117, 0
	v_mov_b32_e32 v118, 0
	v_mov_b32_e32 v119, 0
	v_mov_b32_e32 v120, 0
	v_mov_b32_e32 v121, 0
	v_mov_b32_e32 v122, 0
	v_mov_b32_e32 v123, 0
	v_mov_b32_e32 v124, 0
	v_mov_b32_e32 v125, 0
	v_mov_b32_e32 v126, 0
	v_mov_b32_e32 v127, 0
	s_mov_b32 s98, 0
	s_mov_b32 s31, 24576
	s_waitcnt vmcnt(6)
	s_barrier
	ds_read_b128 v[128:131], v231 offset:0
	ds_read_b128 v[132:135], v231 offset:1024
	ds_read_b128 v[136:139], v231 offset:2048
	ds_read_b128 v[140:143], v231 offset:3072
	ds_read_b128 v[144:147], v230 offset:0
	ds_read_b128 v[148:151], v230 offset:1024
	ds_read_b128 v[152:155], v230 offset:2048
	ds_read_b128 v[156:159], v230 offset:3072
	ds_read_b128 v[160:163], v230 offset:4096
	ds_read_b128 v[164:167], v230 offset:5120
	ds_read_b128 v[168:171], v230 offset:6144
	ds_read_b128 v[172:175], v230 offset:7168
	s_waitcnt vmcnt(0)
	s_waitcnt lgkmcnt(0)
	s_barrier
	v_add_u32_e32 v232, s31, v230
	v_add_u32_e32 v233, s31, v231
	s_setprio 1
	v_mfma_f32_16x16x32_bf16 v[0:3], v[128:131], v[144:147], v[0:3]
	v_mfma_f32_16x16x32_bf16 v[4:7], v[132:135], v[144:147], v[4:7]
	v_mfma_f32_16x16x32_bf16 v[8:11], v[136:139], v[144:147], v[8:11]
	v_mfma_f32_16x16x32_bf16 v[12:15], v[140:143], v[144:147], v[12:15]
	ds_read_b128 v[176:179], v233 offset:0
	ds_read_b128 v[180:183], v233 offset:1024
	v_mfma_f32_16x16x32_bf16 v[16:19], v[128:131], v[148:151], v[16:19]
	v_mfma_f32_16x16x32_bf16 v[20:23], v[132:135], v[148:151], v[20:23]
	v_mfma_f32_16x16x32_bf16 v[24:27], v[136:139], v[148:151], v[24:27]
	v_mfma_f32_16x16x32_bf16 v[28:31], v[140:143], v[148:151], v[28:31]
	ds_read_b128 v[184:187], v233 offset:2048
	ds_read_b128 v[188:191], v233 offset:3072
	v_mfma_f32_16x16x32_bf16 v[32:35], v[128:131], v[152:155], v[32:35]
	v_mfma_f32_16x16x32_bf16 v[36:39], v[132:135], v[152:155], v[36:39]
	v_mfma_f32_16x16x32_bf16 v[40:43], v[136:139], v[152:155], v[40:43]
	v_mfma_f32_16x16x32_bf16 v[44:47], v[140:143], v[152:155], v[44:47]
	ds_read_b128 v[192:195], v232 offset:0
	ds_read_b128 v[196:199], v232 offset:1024
	v_mfma_f32_16x16x32_bf16 v[48:51], v[128:131], v[156:159], v[48:51]
	v_mfma_f32_16x16x32_bf16 v[52:55], v[132:135], v[156:159], v[52:55]
	v_mfma_f32_16x16x32_bf16 v[56:59], v[136:139], v[156:159], v[56:59]
	v_mfma_f32_16x16x32_bf16 v[60:63], v[140:143], v[156:159], v[60:63]
	ds_read_b128 v[200:203], v232 offset:2048
	ds_read_b128 v[204:207], v232 offset:3072
	v_mfma_f32_16x16x32_bf16 v[64:67], v[128:131], v[160:163], v[64:67]
	v_mfma_f32_16x16x32_bf16 v[68:71], v[132:135], v[160:163], v[68:71]
	v_mfma_f32_16x16x32_bf16 v[72:75], v[136:139], v[160:163], v[72:75]
	v_mfma_f32_16x16x32_bf16 v[76:79], v[140:143], v[160:163], v[76:79]
	ds_read_b128 v[208:211], v232 offset:4096
	v_mfma_f32_16x16x32_bf16 v[80:83], v[128:131], v[164:167], v[80:83]
	v_mfma_f32_16x16x32_bf16 v[84:87], v[132:135], v[164:167], v[84:87]
	v_mfma_f32_16x16x32_bf16 v[88:91], v[136:139], v[164:167], v[88:91]
	v_mfma_f32_16x16x32_bf16 v[92:95], v[140:143], v[164:167], v[92:95]
	ds_read_b128 v[212:215], v232 offset:5120
	v_mfma_f32_16x16x32_bf16 v[96:99], v[128:131], v[168:171], v[96:99]
	v_mfma_f32_16x16x32_bf16 v[100:103], v[132:135], v[168:171], v[100:103]
	v_mfma_f32_16x16x32_bf16 v[104:107], v[136:139], v[168:171], v[104:107]
	v_mfma_f32_16x16x32_bf16 v[108:111], v[140:143], v[168:171], v[108:111]
	ds_read_b128 v[216:219], v232 offset:6144
	s_cmp_eq_u32 s25, 0
	s_cbranch_scc0 .Lg3a_hi0
	s_setprio 0
.Lg3a_hi0:
	s_add_u32 s31, s31, 24576
	s_cmp_eq_u32 s31, 73728
	s_cselect_b32 s31, 0, s31
	v_mfma_f32_16x16x32_bf16 v[112:115], v[128:131], v[172:175], v[112:115]
	v_mfma_f32_16x16x32_bf16 v[116:119], v[132:135], v[172:175], v[116:119]
	v_mfma_f32_16x16x32_bf16 v[120:123], v[136:139], v[172:175], v[120:123]
	v_mfma_f32_16x16x32_bf16 v[124:127], v[140:143], v[172:175], v[124:127]
	ds_read_b128 v[220:223], v232 offset:7168
	s_waitcnt lgkmcnt(0)
	s_barrier
	s_setprio 1
	v_mfma_f32_16x16x32_bf16 v[0:3], v[176:179], v[192:195], v[0:3]
	v_mfma_f32_16x16x32_bf16 v[4:7], v[180:183], v[192:195], v[4:7]
	v_mfma_f32_16x16x32_bf16 v[8:11], v[184:187], v[192:195], v[8:11]
	v_mfma_f32_16x16x32_bf16 v[12:15], v[188:191], v[192:195], v[12:15]
	v_mfma_f32_16x16x32_bf16 v[16:19], v[176:179], v[196:199], v[16:19]
	v_mfma_f32_16x16x32_bf16 v[20:23], v[180:183], v[196:199], v[20:23]
	v_mfma_f32_16x16x32_bf16 v[24:27], v[184:187], v[196:199], v[24:27]
	v_mfma_f32_16x16x32_bf16 v[28:31], v[188:191], v[196:199], v[28:31]
	v_mfma_f32_16x16x32_bf16 v[32:35], v[176:179], v[200:203], v[32:35]
	v_mfma_f32_16x16x32_bf16 v[36:39], v[180:183], v[200:203], v[36:39]
	v_mfma_f32_16x16x32_bf16 v[40:43], v[184:187], v[200:203], v[40:43]
	v_mfma_f32_16x16x32_bf16 v[44:47], v[188:191], v[200:203], v[44:47]
	v_mfma_f32_16x16x32_bf16 v[48:51], v[176:179], v[204:207], v[48:51]
	v_mfma_f32_16x16x32_bf16 v[52:55], v[180:183], v[204:207], v[52:55]
	v_mfma_f32_16x16x32_bf16 v[56:59], v[184:187], v[204:207], v[56:59]
	v_mfma_f32_16x16x32_bf16 v[60:63], v[188:191], v[204:207], v[60:63]
	v_mfma_f32_16x16x32_bf16 v[64:67], v[176:179], v[208:211], v[64:67]
	v_mfma_f32_16x16x32_bf16 v[68:71], v[180:183], v[208:211], v[68:71]
	v_mfma_f32_16x16x32_bf16 v[72:75], v[184:187], v[208:211], v[72:75]
	v_mfma_f32_16x16x32_bf16 v[76:79], v[188:191], v[208:211], v[76:79]
	v_mfma_f32_16x16x32_bf16 v[80:83], v[176:179], v[212:215], v[80:83]
	v_mfma_f32_16x16x32_bf16 v[84:87], v[180:183], v[212:215], v[84:87]
	v_mfma_f32_16x16x32_bf16 v[88:91], v[184:187], v[212:215], v[88:91]
	v_mfma_f32_16x16x32_bf16 v[92:95], v[188:191], v[212:215], v[92:95]
	v_mfma_f32_16x16x32_bf16 v[96:99], v[176:179], v[216:219], v[96:99]
	v_mfma_f32_16x16x32_bf16 v[100:103], v[180:183], v[216:219], v[100:103]
	v_mfma_f32_16x16x32_bf16 v[104:107], v[184:187], v[216:219], v[104:107]
	v_mfma_f32_16x16x32_bf16 v[108:111], v[188:191], v[216:219], v[108:111]
	s_cmp_eq_u32 s25, 0
	s_cbranch_scc0 .Lg3a_hi1
	s_setprio 0

; #define LWRITE(S, buf) do { bf16_t* sA_ = sbase + (buf) * BUF; bf16_t* sB_ = sA_ + 256 * PITCH; \
;     _Pragma("unroll") for (int i_ = 0; i_ < 4; ++i_) *(u32x4*)(sA_ + (sr + i_ * 64) * PITCH + scv * 8) = ra[S][i_]; \
;     _Pragma("unroll") for (int i_ = 0; i_ < 2; ++i_) *(u32x4*)(sB_ + (sr + i_ * 64) * PITCH + scv * 8) = rb[S][i_]; } while (0)
; template <class Epi>
; DI void gemm_tile(char* smem, const bf16_t* __restrict__ A0, int lda0, int ksplit, const bf16_t* __restrict__ A1, int lda1,
;                   const bf16_t* __restrict__ Bt, int K, int row0, int col0, const Epi& epi, int tid) {
;     ...
;   __syncthreads();
;   {
;     const int last = nk - 1;
;     GLOAD(0, 0);
;     __builtin_amdgcn_sched_barrier(0);
;     GLOAD(1, 1);
;     __builtin_amdgcn_sched_barrier(0);
;     LWRITE(0, 0);
;     __builtin_amdgcn_sched_barrier(0);
;     GLOAD(0, (2 < last ? 2 : last));
;     __builtin_amdgcn_sched_barrier(0);
;     __syncthreads();
; template <class Epi>
; DI void gemm_phase(char* smem, const bf16_t* A0, int lda0, int ksplit, const bf16_t* A1, int lda1, const bf16_t* Bt, int K, int nN, const Epi& epi, int tid) {
;     ...
;     const int x = blockIdx.x & 7, l = blockIdx.x >> 3, L = G >> 3, per = 8 * nN, tot = 2 * per;
;     for (int q = l; q < tot; q += L) { const int rgl = q / per, rem = q % per, ct = rem >> 3, rt = (x * 2 + rgl) * 8 + (rem & 7);
;       gemm_tile(smem, A0, lda0, ksplit, A1, lda1, Bt, K, rt * 256, ct * 128, epi, tid); }
.Lg3b_tile:
	s_cmpk_ge_u32 s15, 64
	s_cbranch_scc1 .Lg3b_done
	s_cmpk_ge_u32 s15, 32
	s_cselect_b32 s27, 1, 0
	s_cselect_b32 s26, 32, 0
	s_sub_u32 s26, s15, s26
	s_add_u32 s27, s27, s101
	s_lshl_b32 s27, s27, 3
	s_and_b32 s29, s26, 7
	s_add_u32 s29, s29, s27
	s_lshl_b32 s29, s29, 8
	s_lshr_b32 s28, s26, 3
	s_lshl_b32 s28, s28, 7
	s_mul_i32 s27, s29, 512
	s_add_u32 s27, s27, 0x1ea00000
	s_add_u32 s0, s92, s27
	s_addc_u32 s1, s93, 0
	s_mul_i32 s27, s28, 128
	s_add_u32 s27, s27, 0x34b0000
	s_add_u32 s2, s92, s27
	s_addc_u32 s3, s93, 0
	s_waitcnt lgkmcnt(0)
	s_barrier
	s_mov_b32 s99, 0
	s_mov_b32 s30, 0
	s_add_u32 s26, s30, s100
	s_add_u32 m0, s26, 0
	s_nop 0
	global_load_lds_dwordx4 v224, s[0:1]
	s_add_u32 m0, s26, 4096
	s_nop 0
	global_load_lds_dwordx4 v225, s[0:1]
	s_add_u32 m0, s26, 8192
	s_nop 0
	global_load_lds_dwordx4 v226, s[0:1]
	s_add_u32 m0, s26, 12288
	s_nop 0
	global_load_lds_dwordx4 v227, s[0:1]
	s_add_u32 m0, s26, 16384
	s_nop 0
	global_load_lds_dwordx4 v228, s[2:3]
	s_add_u32 m0, s26, 20480
	s_nop 0
	global_load_lds_dwordx4 v229, s[2:3]
	s_add_u32 s0, s0, 64
	s_addc_u32 s1, s1, 0
	s_add_u32 s2, s2, 64
	s_addc_u32 s3, s3, 0
	s_add_u32 s99, s99, 1
	s_add_u32 s30, s30, 24576
	s_cmp_eq_u32 s30, 73728
	s_cselect_b32 s30, 0, s30
	s_add_u32 s26, s30, s100
	s_add_u32 m0, s26, 0
	s_nop 0
	global_load_lds_dwordx4 v224, s[0:1]
	s_add_u32 m0, s26, 4096
	s_nop 0
	global_load_lds_dwordx4 v225, s[0:1]
	s_add_u32 m0, s26, 8192
	s_nop 0
	global_load_lds_dwordx4 v226, s[0:1]
	s_add_u32 m0, s26, 12288
	s_nop 0
	global_load_lds_dwordx4 v227, s[0:1]
	s_add_u32 m0, s26, 16384
	s_nop 0
	global_load_lds_dwordx4 v228, s[2:3]
	s_add_u32 m0, s26, 20480
	s_nop 0
	global_load_lds_dwordx4 v229, s[2:3]
	s_add_u32 s0, s0, 64
	s_addc_u32 s1, s1, 0
	s_add_u32 s2, s2, 64
	s_addc_u32 s3, s3, 0
	s_add_u32 s99, s99, 1
	s_add_u32 s30, s30, 24576
	s_cmp_eq_u32 s30, 73728
	s_cselect_b32 s30, 0, s30
	v_mov_b32_e32 v0, 0
	v_mov_b32_e32 v1, 0
	v_mov_b32_e32 v2, 0
	v_mov_b32_e32 v3, 0
	v_mov_b32_e32 v4, 0
	v_mov_b32_e32 v5, 0
	v_mov_b32_e32 v6, 0
	v_mov_b32_e32 v7, 0
	v_mov_b32_e32 v8, 0
	v_mov_b32_e32 v9, 0
	v_mov_b32_e32 v10, 0
	v_mov_b32_e32 v11, 0
	v_mov_b32_e32 v12, 0
	v_mov_b32_e32 v13, 0
	v_mov_b32_e32 v14, 0
	v_mov_b32_e32 v15, 0
	v_mov_b32_e32 v16, 0
	v_mov_b32_e32 v17, 0
	v_mov_b32_e32 v18, 0
	v_mov_b32_e32 v19, 0
	v_mov_b32_e32 v20, 0
	v_mov_b32_e32 v21, 0
	v_mov_b32_e32 v22, 0
	v_mov_b32_e32 v23, 0
	v_mov_b32_e32 v24, 0
	v_mov_b32_e32 v25, 0
	v_mov_b32_e32 v26, 0
	v_mov_b32_e32 v27, 0
	v_mov_b32_e32 v28, 0
	v_mov_b32_e32 v29, 0
	v_mov_b32_e32 v30, 0
	v_mov_b32_e32 v31, 0
	v_mov_b32_e32 v32, 0
	v_mov_b32_e32 v33, 0
	v_mov_b32_e32 v34, 0
	v_mov_b32_e32 v35, 0
	v_mov_b32_e32 v36, 0
	v_mov_b32_e32 v37, 0
	v_mov_b32_e32 v38, 0
	v_mov_b32_e32 v39, 0
	v_mov_b32_e32 v40, 0
	v_mov_b32_e32 v41, 0
	v_mov_b32_e32 v42, 0
	v_mov_b32_e32 v43, 0
	v_mov_b32_e32 v44, 0
	v_mov_b32_e32 v45, 0
	v_mov_b32_e32 v46, 0
	v_mov_b32_e32 v47, 0
	v_mov_b32_e32 v48, 0
	v_mov_b32_e32 v49, 0
	v_mov_b32_e32 v50, 0
	v_mov_b32_e32 v51, 0
	v_mov_b32_e32 v52, 0
	v_mov_b32_e32 v53, 0
	v_mov_b32_e32 v54, 0
	v_mov_b32_e32 v55, 0
	v_mov_b32_e32 v56, 0
	v_mov_b32_e32 v57, 0
	v_mov_b32_e32 v58, 0
	v_mov_b32_e32 v59, 0
	v_mov_b32_e32 v60, 0
	v_mov_b32_e32 v61, 0
	v_mov_b32_e32 v62, 0
	v_mov_b32_e32 v63, 0
	v_mov_b32_e32 v64, 0
	v_mov_b32_e32 v65, 0
	v_mov_b32_e32 v66, 0
	v_mov_b32_e32 v67, 0
	v_mov_b32_e32 v68, 0
	v_mov_b32_e32 v69, 0
	v_mov_b32_e32 v70, 0
	v_mov_b32_e32 v71, 0
	v_mov_b32_e32 v72, 0
	v_mov_b32_e32 v73, 0
	v_mov_b32_e32 v74, 0
	v_mov_b32_e32 v75, 0
	v_mov_b32_e32 v76, 0
	v_mov_b32_e32 v77, 0
	v_mov_b32_e32 v78, 0
	v_mov_b32_e32 v79, 0
	v_mov_b32_e32 v80, 0
	v_mov_b32_e32 v81, 0
	v_mov_b32_e32 v82, 0
	v_mov_b32_e32 v83, 0
	v_mov_b32_e32 v84, 0
	v_mov_b32_e32 v85, 0
	v_mov_b32_e32 v86, 0
	v_mov_b32_e32 v87, 0
	v_mov_b32_e32 v88, 0
	v_mov_b32_e32 v89, 0
	v_mov_b32_e32 v90, 0
	v_mov_b32_e32 v91, 0
	v_mov_b32_e32 v92, 0
	v_mov_b32_e32 v93, 0
	v_mov_b32_e32 v94, 0
	v_mov_b32_e32 v95, 0
	v_mov_b32_e32 v96, 0
	v_mov_b32_e32 v97, 0
	v_mov_b32_e32 v98, 0
	v_mov_b32_e32 v99, 0
	v_mov_b32_e32 v100, 0
	v_mov_b32_e32 v101, 0
	v_mov_b32_e32 v102, 0
	v_mov_b32_e32 v103, 0
	v_mov_b32_e32 v104, 0
	v_mov_b32_e32 v105, 0
	v_mov_b32_e32 v106, 0
	v_mov_b32_e32 v107, 0
	v_mov_b32_e32 v108, 0
	v_mov_b32_e32 v109, 0
	v_mov_b32_e32 v110, 0
	v_mov_b32_e32 v111, 0
	v_mov_b32_e32 v112, 0
	v_mov_b32_e32 v113, 0
	v_mov_b32_e32 v114, 0
	v_mov_b32_e32 v115, 0
	v_mov_b32_e32 v116, 0
	v_mov_b32_e32 v117, 0
	v_mov_b32_e32 v118, 0
	v_mov_b32_e32 v119, 0
	v_mov_b32_e32 v120, 0
	v_mov_b32_e32 v121, 0
	v_mov_b32_e32 v122, 0
	v_mov_b32_e32 v123, 0
	v_mov_b32_e32 v124, 0
	v_mov_b32_e32 v125, 0
	v_mov_b32_e32 v126, 0
	v_mov_b32_e32 v127, 0
	s_mov_b32 s98, 0
	s_mov_b32 s31, 24576
	s_waitcnt vmcnt(6)
	s_barrier
	ds_read_b128 v[128:131], v231 offset:0
	ds_read_b128 v[132:135], v231 offset:1024
	ds_read_b128 v[136:139], v231 offset:2048
	ds_read_b128 v[140:143], v231 offset:3072
	ds_read_b128 v[144:147], v230 offset:0
	ds_read_b128 v[148:151], v230 offset:1024
	ds_read_b128 v[152:155], v230 offset:2048
	ds_read_b128 v[156:159], v230 offset:3072
	ds_read_b128 v[160:163], v230 offset:4096
	ds_read_b128 v[164:167], v230 offset:5120
	ds_read_b128 v[168:171], v230 offset:6144
	ds_read_b128 v[172:175], v230 offset:7168
	s_waitcnt vmcnt(0)
	s_waitcnt lgkmcnt(0)
	s_barrier
	v_add_u32_e32 v232, s31, v230
	v_add_u32_e32 v233, s31, v231
	s_setprio 1
	v_mfma_f32_16x16x32_bf16 v[0:3], v[128:131], v[144:147], v[0:3]
	v_mfma_f32_16x16x32_bf16 v[4:7], v[132:135], v[144:147], v[4:7]
	v_mfma_f32_16x16x32_bf16 v[8:11], v[136:139], v[144:147], v[8:11]
	v_mfma_f32_16x16x32_bf16 v[12:15], v[140:143], v[144:147], v[12:15]
	ds_read_b128 v[176:179], v233 offset:0
	ds_read_b128 v[180:183], v233 offset:1024
	v_mfma_f32_16x16x32_bf16 v[16:19], v[128:131], v[148:151], v[16:19]
	v_mfma_f32_16x16x32_bf16 v[20:23], v[132:135], v[148:151], v[20:23]
	v_mfma_f32_16x16x32_bf16 v[24:27], v[136:139], v[148:151], v[24:27]
	v_mfma_f32_16x16x32_bf16 v[28:31], v[140:143], v[148:151], v[28:31]
	ds_read_b128 v[184:187], v233 offset:2048
	ds_read_b128 v[188:191], v233 offset:3072
	v_mfma_f32_16x16x32_bf16 v[32:35], v[128:131], v[152:155], v[32:35]
	v_mfma_f32_16x16x32_bf16 v[36:39], v[132:135], v[152:155], v[36:39]
	v_mfma_f32_16x16x32_bf16 v[40:43], v[136:139], v[152:155], v[40:43]
	v_mfma_f32_16x16x32_bf16 v[44:47], v[140:143], v[152:155], v[44:47]
	ds_read_b128 v[192:195], v232 offset:0
	ds_read_b128 v[196:199], v232 offset:1024
	v_mfma_f32_16x16x32_bf16 v[48:51], v[128:131], v[156:159], v[48:51]
	v_mfma_f32_16x16x32_bf16 v[52:55], v[132:135], v[156:159], v[52:55]
	v_mfma_f32_16x16x32_bf16 v[56:59], v[136:139], v[156:159], v[56:59]
	v_mfma_f32_16x16x32_bf16 v[60:63], v[140:143], v[156:159], v[60:63]
	ds_read_b128 v[200:203], v232 offset:2048
	ds_read_b128 v[204:207], v232 offset:3072
	v_mfma_f32_16x16x32_bf16 v[64:67], v[128:131], v[160:163], v[64:67]
	v_mfma_f32_16x16x32_bf16 v[68:71], v[132:135], v[160:163], v[68:71]
	v_mfma_f32_16x16x32_bf16 v[72:75], v[136:139], v[160:163], v[72:75]
	v_mfma_f32_16x16x32_bf16 v[76:79], v[140:143], v[160:163], v[76:79]
	ds_read_b128 v[208:211], v232 offset:4096
	v_mfma_f32_16x16x32_bf16 v[80:83], v[128:131], v[164:167], v[80:83]
	v_mfma_f32_16x16x32_bf16 v[84:87], v[132:135], v[164:167], v[84:87]
	v_mfma_f32_16x16x32_bf16 v[88:91], v[136:139], v[164:167], v[88:91]
	v_mfma_f32_16x16x32_bf16 v[92:95], v[140:143], v[164:167], v[92:95]
	ds_read_b128 v[212:215], v232 offset:5120
	v_mfma_f32_16x16x32_bf16 v[96:99], v[128:131], v[168:171], v[96:99]
	v_mfma_f32_16x16x32_bf16 v[100:103], v[132:135], v[168:171], v[100:103]
	v_mfma_f32_16x16x32_bf16 v[104:107], v[136:139], v[168:171], v[104:107]
	v_mfma_f32_16x16x32_bf16 v[108:111], v[140:143], v[168:171], v[108:111]
	ds_read_b128 v[216:219], v232 offset:6144
	s_cmp_eq_u32 s25, 0
	s_cbranch_scc0 .Lg3b_hi0
	s_setprio 0

; #define LWRITE(S, buf) do { bf16_t* sA_ = sbase + (buf) * BUF; bf16_t* sB_ = sA_ + 256 * PITCH; \
;     _Pragma("unroll") for (int i_ = 0; i_ < 4; ++i_) *(u32x4*)(sA_ + (sr + i_ * 64) * PITCH + scv * 8) = ra[S][i_]; \
;     _Pragma("unroll") for (int i_ = 0; i_ < 2; ++i_) *(u32x4*)(sB_ + (sr + i_ * 64) * PITCH + scv * 8) = rb[S][i_]; } while (0)
; template <class Epi>
; DI void gemm_tile(char* smem, const bf16_t* __restrict__ A0, int lda0, int ksplit, const bf16_t* __restrict__ A1, int lda1,
;                   const bf16_t* __restrict__ Bt, int K, int row0, int col0, const Epi& epi, int tid) {
;     ...
;   __syncthreads();
;   {
;     const int last = nk - 1;
;     GLOAD(0, 0);
;     __builtin_amdgcn_sched_barrier(0);
;     GLOAD(1, 1);
;     __builtin_amdgcn_sched_barrier(0);
;     LWRITE(0, 0);
;     __builtin_amdgcn_sched_barrier(0);
;     GLOAD(0, (2 < last ? 2 : last));
;     __builtin_amdgcn_sched_barrier(0);
;     __syncthreads();
; template <class Epi>
; DI void gemm_phase(char* smem, const bf16_t* A0, int lda0, int ksplit, const bf16_t* A1, int lda1, const bf16_t* Bt, int K, int nN, const Epi& epi, int tid) {
;     ...
;     const int x = blockIdx.x & 7, l = blockIdx.x >> 3, L = G >> 3, per = 8 * nN, tot = 2 * per;
;     for (int q = l; q < tot; q += L) { const int rgl = q / per, rem = q % per, ct = rem >> 3, rt = (x * 2 + rgl) * 8 + (rem & 7);
;       gemm_tile(smem, A0, lda0, ksplit, A1, lda1, Bt, K, rt * 256, ct * 128, epi, tid); }
.Lg3c_tile:
	s_cmpk_ge_u32 s15, 64
	s_cbranch_scc1 .Lg3c_done
	s_cmpk_ge_u32 s15, 32
	s_cselect_b32 s27, 1, 0
	s_cselect_b32 s26, 32, 0
	s_sub_u32 s26, s15, s26
	s_add_u32 s27, s27, s101
	s_lshl_b32 s27, s27, 3
	s_and_b32 s29, s26, 7
	s_add_u32 s29, s29, s27
	s_lshl_b32 s29, s29, 8
	s_lshr_b32 s28, s26, 3
	s_lshl_b32 s28, s28, 7
	s_mul_i32 s27, s29, 512
	s_add_u32 s27, s27, 0x1ea00080
	s_add_u32 s0, s92, s27
	s_addc_u32 s1, s93, 0
	s_mul_i32 s27, s28, 128
	s_add_u32 s27, s27, 0x34c0000
	s_add_u32 s2, s92, s27
	s_addc_u32 s3, s93, 0
	s_waitcnt lgkmcnt(0)
	s_barrier
	s_mov_b32 s99, 0
	s_mov_b32 s30, 0
	s_add_u32 s26, s30, s100
	s_add_u32 m0, s26, 0
	s_nop 0
	global_load_lds_dwordx4 v224, s[0:1]
	s_add_u32 m0, s26, 4096
	s_nop 0
	global_load_lds_dwordx4 v225, s[0:1]
	s_add_u32 m0, s26, 8192
	s_nop 0
	global_load_lds_dwordx4 v226, s[0:1]
	s_add_u32 m0, s26, 12288
	s_nop 0
	global_load_lds_dwordx4 v227, s[0:1]
	s_add_u32 m0, s26, 16384
	s_nop 0
	global_load_lds_dwordx4 v228, s[2:3]
	s_add_u32 m0, s26, 20480
	s_nop 0
	global_load_lds_dwordx4 v229, s[2:3]
	s_add_u32 s0, s0, 64
	s_addc_u32 s1, s1, 0
	s_add_u32 s2, s2, 64
	s_addc_u32 s3, s3, 0
	s_add_u32 s99, s99, 1
	s_add_u32 s30, s30, 24576
	s_cmp_eq_u32 s30, 73728
	s_cselect_b32 s30, 0, s30
	s_add_u32 s26, s30, s100
	s_add_u32 m0, s26, 0
	s_nop 0
	global_load_lds_dwordx4 v224, s[0:1]
	s_add_u32 m0, s26, 4096
	s_nop 0
	global_load_lds_dwordx4 v225, s[0:1]
	s_add_u32 m0, s26, 8192
	s_nop 0
	global_load_lds_dwordx4 v226, s[0:1]
	s_add_u32 m0, s26, 12288
	s_nop 0
	global_load_lds_dwordx4 v227, s[0:1]
	s_add_u32 m0, s26, 16384
	s_nop 0
	global_load_lds_dwordx4 v228, s[2:3]
	s_add_u32 m0, s26, 20480
	s_nop 0
	global_load_lds_dwordx4 v229, s[2:3]
	s_add_u32 s0, s0, 64
	s_addc_u32 s1, s1, 0
	s_add_u32 s2, s2, 64
	s_addc_u32 s3, s3, 0
	s_add_u32 s99, s99, 1
	s_add_u32 s30, s30, 24576
	s_cmp_eq_u32 s30, 73728
	s_cselect_b32 s30, 0, s30
	v_mov_b32_e32 v0, 0
	v_mov_b32_e32 v1, 0
	v_mov_b32_e32 v2, 0
	v_mov_b32_e32 v3, 0
	v_mov_b32_e32 v4, 0
	v_mov_b32_e32 v5, 0
	v_mov_b32_e32 v6, 0
	v_mov_b32_e32 v7, 0
	v_mov_b32_e32 v8, 0
	v_mov_b32_e32 v9, 0
	v_mov_b32_e32 v10, 0
	v_mov_b32_e32 v11, 0
	v_mov_b32_e32 v12, 0
	v_mov_b32_e32 v13, 0
	v_mov_b32_e32 v14, 0
	v_mov_b32_e32 v15, 0
	v_mov_b32_e32 v16, 0
	v_mov_b32_e32 v17, 0
	v_mov_b32_e32 v18, 0
	v_mov_b32_e32 v19, 0
	v_mov_b32_e32 v20, 0
	v_mov_b32_e32 v21, 0
	v_mov_b32_e32 v22, 0
	v_mov_b32_e32 v23, 0
	v_mov_b32_e32 v24, 0
	v_mov_b32_e32 v25, 0
	v_mov_b32_e32 v26, 0
	v_mov_b32_e32 v27, 0
	v_mov_b32_e32 v28, 0
	v_mov_b32_e32 v29, 0
	v_mov_b32_e32 v30, 0
	v_mov_b32_e32 v31, 0
	v_mov_b32_e32 v32, 0
	v_mov_b32_e32 v33, 0
	v_mov_b32_e32 v34, 0
	v_mov_b32_e32 v35, 0
	v_mov_b32_e32 v36, 0
	v_mov_b32_e32 v37, 0
	v_mov_b32_e32 v38, 0
	v_mov_b32_e32 v39, 0
	v_mov_b32_e32 v40, 0
	v_mov_b32_e32 v41, 0
	v_mov_b32_e32 v42, 0
	v_mov_b32_e32 v43, 0
	v_mov_b32_e32 v44, 0
	v_mov_b32_e32 v45, 0
	v_mov_b32_e32 v46, 0
	v_mov_b32_e32 v47, 0
	v_mov_b32_e32 v48, 0
	v_mov_b32_e32 v49, 0
	v_mov_b32_e32 v50, 0
	v_mov_b32_e32 v51, 0
	v_mov_b32_e32 v52, 0
	v_mov_b32_e32 v53, 0
	v_mov_b32_e32 v54, 0
	v_mov_b32_e32 v55, 0
	v_mov_b32_e32 v56, 0
	v_mov_b32_e32 v57, 0
	v_mov_b32_e32 v58, 0
	v_mov_b32_e32 v59, 0
	v_mov_b32_e32 v60, 0
	v_mov_b32_e32 v61, 0
	v_mov_b32_e32 v62, 0
	v_mov_b32_e32 v63, 0
	v_mov_b32_e32 v64, 0
	v_mov_b32_e32 v65, 0
	v_mov_b32_e32 v66, 0
	v_mov_b32_e32 v67, 0
	v_mov_b32_e32 v68, 0
	v_mov_b32_e32 v69, 0
	v_mov_b32_e32 v70, 0
	v_mov_b32_e32 v71, 0
	v_mov_b32_e32 v72, 0
	v_mov_b32_e32 v73, 0
	v_mov_b32_e32 v74, 0
	v_mov_b32_e32 v75, 0
	v_mov_b32_e32 v76, 0
	v_mov_b32_e32 v77, 0
	v_mov_b32_e32 v78, 0
	v_mov_b32_e32 v79, 0
	v_mov_b32_e32 v80, 0
	v_mov_b32_e32 v81, 0
	v_mov_b32_e32 v82, 0
	v_mov_b32_e32 v83, 0
	v_mov_b32_e32 v84, 0
	v_mov_b32_e32 v85, 0
	v_mov_b32_e32 v86, 0
	v_mov_b32_e32 v87, 0
	v_mov_b32_e32 v88, 0
	v_mov_b32_e32 v89, 0
	v_mov_b32_e32 v90, 0
	v_mov_b32_e32 v91, 0
	v_mov_b32_e32 v92, 0
	v_mov_b32_e32 v93, 0
	v_mov_b32_e32 v94, 0
	v_mov_b32_e32 v95, 0
	v_mov_b32_e32 v96, 0
	v_mov_b32_e32 v97, 0
	v_mov_b32_e32 v98, 0
	v_mov_b32_e32 v99, 0
	v_mov_b32_e32 v100, 0
	v_mov_b32_e32 v101, 0
	v_mov_b32_e32 v102, 0
	v_mov_b32_e32 v103, 0
	v_mov_b32_e32 v104, 0
	v_mov_b32_e32 v105, 0
	v_mov_b32_e32 v106, 0
	v_mov_b32_e32 v107, 0
	v_mov_b32_e32 v108, 0
	v_mov_b32_e32 v109, 0
	v_mov_b32_e32 v110, 0
	v_mov_b32_e32 v111, 0
	v_mov_b32_e32 v112, 0
	v_mov_b32_e32 v113, 0
	v_mov_b32_e32 v114, 0
	v_mov_b32_e32 v115, 0
	v_mov_b32_e32 v116, 0
	v_mov_b32_e32 v117, 0
	v_mov_b32_e32 v118, 0
	v_mov_b32_e32 v119, 0
	v_mov_b32_e32 v120, 0
	v_mov_b32_e32 v121, 0
	v_mov_b32_e32 v122, 0
	v_mov_b32_e32 v123, 0
	v_mov_b32_e32 v124, 0
	v_mov_b32_e32 v125, 0
	v_mov_b32_e32 v126, 0
	v_mov_b32_e32 v127, 0
	s_mov_b32 s98, 0
	s_mov_b32 s31, 24576
	s_waitcnt vmcnt(6)
	s_barrier
	ds_read_b128 v[128:131], v231 offset:0
	ds_read_b128 v[132:135], v231 offset:1024
	ds_read_b128 v[136:139], v231 offset:2048
	ds_read_b128 v[140:143], v231 offset:3072
	ds_read_b128 v[144:147], v230 offset:0
	ds_read_b128 v[148:151], v230 offset:1024
	ds_read_b128 v[152:155], v230 offset:2048
	ds_read_b128 v[156:159], v230 offset:3072
	ds_read_b128 v[160:163], v230 offset:4096
	ds_read_b128 v[164:167], v230 offset:5120
	ds_read_b128 v[168:171], v230 offset:6144
	ds_read_b128 v[172:175], v230 offset:7168
	s_waitcnt vmcnt(0)
	s_waitcnt lgkmcnt(0)
	s_barrier
	v_add_u32_e32 v232, s31, v230
	v_add_u32_e32 v233, s31, v231
	s_setprio 1
	v_mfma_f32_16x16x32_bf16 v[0:3], v[128:131], v[144:147], v[0:3]
	v_mfma_f32_16x16x32_bf16 v[4:7], v[132:135], v[144:147], v[4:7]
	v_mfma_f32_16x16x32_bf16 v[8:11], v[136:139], v[144:147], v[8:11]
	v_mfma_f32_16x16x32_bf16 v[12:15], v[140:143], v[144:147], v[12:15]
	ds_read_b128 v[176:179], v233 offset:0
	ds_read_b128 v[180:183], v233 offset:1024
	v_mfma_f32_16x16x32_bf16 v[16:19], v[128:131], v[148:151], v[16:19]
	v_mfma_f32_16x16x32_bf16 v[20:23], v[132:135], v[148:151], v[20:23]
	v_mfma_f32_16x16x32_bf16 v[24:27], v[136:139], v[148:151], v[24:27]
	v_mfma_f32_16x16x32_bf16 v[28:31], v[140:143], v[148:151], v[28:31]
	ds_read_b128 v[184:187], v233 offset:2048
	ds_read_b128 v[188:191], v233 offset:3072
	v_mfma_f32_16x16x32_bf16 v[32:35], v[128:131], v[152:155], v[32:35]
	v_mfma_f32_16x16x32_bf16 v[36:39], v[132:135], v[152:155], v[36:39]
	v_mfma_f32_16x16x32_bf16 v[40:43], v[136:139], v[152:155], v[40:43]
	v_mfma_f32_16x16x32_bf16 v[44:47], v[140:143], v[152:155], v[44:47]
	ds_read_b128 v[192:195], v232 offset:0
	ds_read_b128 v[196:199], v232 offset:1024
	v_mfma_f32_16x16x32_bf16 v[48:51], v[128:131], v[156:159], v[48:51]
	v_mfma_f32_16x16x32_bf16 v[52:55], v[132:135], v[156:159], v[52:55]
	v_mfma_f32_16x16x32_bf16 v[56:59], v[136:139], v[156:159], v[56:59]
	v_mfma_f32_16x16x32_bf16 v[60:63], v[140:143], v[156:159], v[60:63]
	ds_read_b128 v[200:203], v232 offset:2048
	ds_read_b128 v[204:207], v232 offset:3072
	v_mfma_f32_16x16x32_bf16 v[64:67], v[128:131], v[160:163], v[64:67]
	v_mfma_f32_16x16x32_bf16 v[68:71], v[132:135], v[160:163], v[68:71]
	v_mfma_f32_16x16x32_bf16 v[72:75], v[136:139], v[160:163], v[72:75]
	v_mfma_f32_16x16x32_bf16 v[76:79], v[140:143], v[160:163], v[76:79]
	ds_read_b128 v[208:211], v232 offset:4096
	v_mfma_f32_16x16x32_bf16 v[80:83], v[128:131], v[164:167], v[80:83]
	v_mfma_f32_16x16x32_bf16 v[84:87], v[132:135], v[164:167], v[84:87]
	v_mfma_f32_16x16x32_bf16 v[88:91], v[136:139], v[164:167], v[88:91]
	v_mfma_f32_16x16x32_bf16 v[92:95], v[140:143], v[164:167], v[92:95]
	ds_read_b128 v[212:215], v232 offset:5120
	v_mfma_f32_16x16x32_bf16 v[96:99], v[128:131], v[168:171], v[96:99]
	v_mfma_f32_16x16x32_bf16 v[100:103], v[132:135], v[168:171], v[100:103]
	v_mfma_f32_16x16x32_bf16 v[104:107], v[136:139], v[168:171], v[104:107]
	v_mfma_f32_16x16x32_bf16 v[108:111], v[140:143], v[168:171], v[108:111]
	ds_read_b128 v[216:219], v232 offset:6144
	s_cmp_eq_u32 s25, 0
	s_cbranch_scc0 .Lg3c_hi0
	s_setprio 0

; #define LWRITE(S, buf) do { bf16_t* sA_ = sbase + (buf) * BUF; bf16_t* sB_ = sA_ + 256 * PITCH; \
;     _Pragma("unroll") for (int i_ = 0; i_ < 4; ++i_) *(u32x4*)(sA_ + (sr + i_ * 64) * PITCH + scv * 8) = ra[S][i_]; \
;     _Pragma("unroll") for (int i_ = 0; i_ < 2; ++i_) *(u32x4*)(sB_ + (sr + i_ * 64) * PITCH + scv * 8) = rb[S][i_]; } while (0)
; template <class Epi>
; DI void gemm_tile(char* smem, const bf16_t* __restrict__ A0, int lda0, int ksplit, const bf16_t* __restrict__ A1, int lda1,
;                   const bf16_t* __restrict__ Bt, int K, int row0, int col0, const Epi& epi, int tid) {
;     ...
;   __syncthreads();
;   {
;     const int last = nk - 1;
;     GLOAD(0, 0);
;     __builtin_amdgcn_sched_barrier(0);
;     GLOAD(1, 1);
;     __builtin_amdgcn_sched_barrier(0);
;     LWRITE(0, 0);
;     __builtin_amdgcn_sched_barrier(0);
;     GLOAD(0, (2 < last ? 2 : last));
;     __builtin_amdgcn_sched_barrier(0);
;     __syncthreads();
; template <class Epi>
; DI void gemm_phase(char* smem, const bf16_t* A0, int lda0, int ksplit, const bf16_t* A1, int lda1, const bf16_t* Bt, int K, int nN, const Epi& epi, int tid) {
;     ...
;     const int x = blockIdx.x & 7, l = blockIdx.x >> 3, L = G >> 3, per = 8 * nN, tot = 2 * per;
;     for (int q = l; q < tot; q += L) { const int rgl = q / per, rem = q % per, ct = rem >> 3, rt = (x * 2 + rgl) * 8 + (rem & 7);
;       gemm_tile(smem, A0, lda0, ksplit, A1, lda1, Bt, K, rt * 256, ct * 128, epi, tid); }
.Lg3d_tile:
	s_cmpk_ge_u32 s15, 64
	s_cbranch_scc1 .Lg3d_done
	s_cmpk_ge_u32 s15, 32
	s_cselect_b32 s27, 1, 0
	s_cselect_b32 s26, 32, 0
	s_sub_u32 s26, s15, s26
	s_add_u32 s27, s27, s101
	s_lshl_b32 s27, s27, 3
	s_and_b32 s29, s26, 7
	s_add_u32 s29, s29, s27
	s_lshl_b32 s29, s29, 8
	s_lshr_b32 s28, s26, 3
	s_lshl_b32 s28, s28, 7
	s_mul_i32 s27, s29, 512
	s_add_u32 s27, s27, 0x1ea00100
	s_add_u32 s0, s92, s27
	s_addc_u32 s1, s93, 0
	s_mul_i32 s27, s28, 256
	s_add_u32 s27, s27, 0x3480000
	s_add_u32 s2, s92, s27
	s_addc_u32 s3, s93, 0
	s_waitcnt lgkmcnt(0)
	s_barrier
	s_mov_b32 s99, 0
	s_mov_b32 s30, 0
	s_add_u32 s26, s30, s100
	s_add_u32 m0, s26, 0
	s_nop 0
	global_load_lds_dwordx4 v224, s[0:1]
	s_add_u32 m0, s26, 4096
	s_nop 0
	global_load_lds_dwordx4 v225, s[0:1]
	s_add_u32 m0, s26, 8192
	s_nop 0
	global_load_lds_dwordx4 v226, s[0:1]
	s_add_u32 m0, s26, 12288
	s_nop 0
	global_load_lds_dwordx4 v227, s[0:1]
	s_add_u32 m0, s26, 16384
	s_nop 0
	global_load_lds_dwordx4 v228, s[2:3]
	s_add_u32 m0, s26, 20480
	s_nop 0
	global_load_lds_dwordx4 v229, s[2:3]
	s_add_u32 s0, s0, 64
	s_addc_u32 s1, s1, 0
	s_add_u32 s2, s2, 64
	s_addc_u32 s3, s3, 0
	s_add_u32 s99, s99, 1
	s_add_u32 s30, s30, 24576
	s_cmp_eq_u32 s30, 73728
	s_cselect_b32 s30, 0, s30
	s_add_u32 s26, s30, s100
	s_add_u32 m0, s26, 0
	s_nop 0
	global_load_lds_dwordx4 v224, s[0:1]
	s_add_u32 m0, s26, 4096
	s_nop 0
	global_load_lds_dwordx4 v225, s[0:1]
	s_add_u32 m0, s26, 8192
	s_nop 0
	global_load_lds_dwordx4 v226, s[0:1]
	s_add_u32 m0, s26, 12288
	s_nop 0
	global_load_lds_dwordx4 v227, s[0:1]
	s_add_u32 m0, s26, 16384
	s_nop 0
	global_load_lds_dwordx4 v228, s[2:3]
	s_add_u32 m0, s26, 20480
	s_nop 0
	global_load_lds_dwordx4 v229, s[2:3]
	s_add_u32 s0, s0, 64
	s_addc_u32 s1, s1, 0
	s_add_u32 s2, s2, 64
	s_addc_u32 s3, s3, 0
	s_add_u32 s99, s99, 1
	s_add_u32 s30, s30, 24576
	s_cmp_eq_u32 s30, 73728
	s_cselect_b32 s30, 0, s30
	s_add_u32 s26, s30, s100
	s_add_u32 m0, s26, 0
	s_nop 0
	global_load_lds_dwordx4 v224, s[0:1]
	s_add_u32 m0, s26, 4096
	s_nop 0
	global_load_lds_dwordx4 v225, s[0:1]
	s_add_u32 m0, s26, 8192
	s_nop 0
	global_load_lds_dwordx4 v226, s[0:1]
	s_add_u32 m0, s26, 12288
	s_nop 0
	global_load_lds_dwordx4 v227, s[0:1]
	s_add_u32 m0, s26, 16384
	s_nop 0
	global_load_lds_dwordx4 v228, s[2:3]
	s_add_u32 m0, s26, 20480
	s_nop 0
	global_load_lds_dwordx4 v229, s[2:3]
	s_add_u32 s0, s0, 64
	s_addc_u32 s1, s1, 0
	s_add_u32 s2, s2, 64
	s_addc_u32 s3, s3, 0
	s_add_u32 s99, s99, 1
	s_add_u32 s30, s30, 24576
	s_cmp_eq_u32 s30, 73728
	s_cselect_b32 s30, 0, s30
	v_mov_b32_e32 v0, 0
	v_mov_b32_e32 v1, 0
	v_mov_b32_e32 v2, 0
	v_mov_b32_e32 v3, 0
	v_mov_b32_e32 v4, 0
	v_mov_b32_e32 v5, 0
	v_mov_b32_e32 v6, 0
	v_mov_b32_e32 v7, 0
	v_mov_b32_e32 v8, 0
	v_mov_b32_e32 v9, 0
	v_mov_b32_e32 v10, 0
	v_mov_b32_e32 v11, 0
	v_mov_b32_e32 v12, 0
	v_mov_b32_e32 v13, 0
	v_mov_b32_e32 v14, 0
	v_mov_b32_e32 v15, 0
	v_mov_b32_e32 v16, 0
	v_mov_b32_e32 v17, 0
	v_mov_b32_e32 v18, 0
	v_mov_b32_e32 v19, 0
	v_mov_b32_e32 v20, 0
	v_mov_b32_e32 v21, 0
	v_mov_b32_e32 v22, 0
	v_mov_b32_e32 v23, 0
	v_mov_b32_e32 v24, 0
	v_mov_b32_e32 v25, 0
	v_mov_b32_e32 v26, 0
	v_mov_b32_e32 v27, 0
	v_mov_b32_e32 v28, 0
	v_mov_b32_e32 v29, 0
	v_mov_b32_e32 v30, 0
	v_mov_b32_e32 v31, 0
	v_mov_b32_e32 v32, 0
	v_mov_b32_e32 v33, 0
	v_mov_b32_e32 v34, 0
	v_mov_b32_e32 v35, 0
	v_mov_b32_e32 v36, 0
	v_mov_b32_e32 v37, 0
	v_mov_b32_e32 v38, 0
	v_mov_b32_e32 v39, 0
	v_mov_b32_e32 v40, 0
	v_mov_b32_e32 v41, 0
	v_mov_b32_e32 v42, 0
	v_mov_b32_e32 v43, 0
	v_mov_b32_e32 v44, 0
	v_mov_b32_e32 v45, 0
	v_mov_b32_e32 v46, 0
	v_mov_b32_e32 v47, 0
	v_mov_b32_e32 v48, 0
	v_mov_b32_e32 v49, 0
	v_mov_b32_e32 v50, 0
	v_mov_b32_e32 v51, 0
	v_mov_b32_e32 v52, 0
	v_mov_b32_e32 v53, 0
	v_mov_b32_e32 v54, 0
	v_mov_b32_e32 v55, 0
	v_mov_b32_e32 v56, 0
	v_mov_b32_e32 v57, 0
	v_mov_b32_e32 v58, 0
	v_mov_b32_e32 v59, 0
	v_mov_b32_e32 v60, 0
	v_mov_b32_e32 v61, 0
	v_mov_b32_e32 v62, 0
	v_mov_b32_e32 v63, 0
	v_mov_b32_e32 v64, 0
	v_mov_b32_e32 v65, 0
	v_mov_b32_e32 v66, 0
	v_mov_b32_e32 v67, 0
	v_mov_b32_e32 v68, 0
	v_mov_b32_e32 v69, 0
	v_mov_b32_e32 v70, 0
	v_mov_b32_e32 v71, 0
	v_mov_b32_e32 v72, 0
	v_mov_b32_e32 v73, 0
	v_mov_b32_e32 v74, 0
	v_mov_b32_e32 v75, 0
	v_mov_b32_e32 v76, 0
	v_mov_b32_e32 v77, 0
	v_mov_b32_e32 v78, 0
	v_mov_b32_e32 v79, 0
	v_mov_b32_e32 v80, 0
	v_mov_b32_e32 v81, 0
	v_mov_b32_e32 v82, 0
	v_mov_b32_e32 v83, 0
	v_mov_b32_e32 v84, 0
	v_mov_b32_e32 v85, 0
	v_mov_b32_e32 v86, 0
	v_mov_b32_e32 v87, 0
	v_mov_b32_e32 v88, 0
	v_mov_b32_e32 v89, 0
	v_mov_b32_e32 v90, 0
	v_mov_b32_e32 v91, 0
	v_mov_b32_e32 v92, 0
	v_mov_b32_e32 v93, 0
	v_mov_b32_e32 v94, 0
	v_mov_b32_e32 v95, 0
	v_mov_b32_e32 v96, 0
	v_mov_b32_e32 v97, 0
	v_mov_b32_e32 v98, 0
	v_mov_b32_e32 v99, 0
	v_mov_b32_e32 v100, 0
	v_mov_b32_e32 v101, 0
	v_mov_b32_e32 v102, 0
	v_mov_b32_e32 v103, 0
	v_mov_b32_e32 v104, 0
	v_mov_b32_e32 v105, 0
	v_mov_b32_e32 v106, 0
	v_mov_b32_e32 v107, 0
	v_mov_b32_e32 v108, 0
	v_mov_b32_e32 v109, 0
	v_mov_b32_e32 v110, 0
	v_mov_b32_e32 v111, 0
	v_mov_b32_e32 v112, 0
	v_mov_b32_e32 v113, 0
	v_mov_b32_e32 v114, 0
	v_mov_b32_e32 v115, 0
	v_mov_b32_e32 v116, 0
	v_mov_b32_e32 v117, 0
	v_mov_b32_e32 v118, 0
	v_mov_b32_e32 v119, 0
	v_mov_b32_e32 v120, 0
	v_mov_b32_e32 v121, 0
	v_mov_b32_e32 v122, 0
	v_mov_b32_e32 v123, 0
	v_mov_b32_e32 v124, 0
	v_mov_b32_e32 v125, 0
	v_mov_b32_e32 v126, 0
	v_mov_b32_e32 v127, 0
	s_mov_b32 s98, 0
	s_mov_b32 s31, 24576
	s_waitcnt vmcnt(12)
	s_barrier
; #define LWRITE(S, buf) do { bf16_t* sA_ = sbase + (buf) * BUF; bf16_t* sB_ = sA_ + 256 * PITCH; \
;     _Pragma("unroll") for (int i_ = 0; i_ < 4; ++i_) *(u32x4*)(sA_ + (sr + i_ * 64) * PITCH + scv * 8) = ra[S][i_]; \
;     _Pragma("unroll") for (int i_ = 0; i_ < 2; ++i_) *(u32x4*)(sB_ + (sr + i_ * 64) * PITCH + scv * 8) = rb[S][i_]; } while (0)
; template <class Epi>
; DI void gemm_tile(char* smem, const bf16_t* __restrict__ A0, int lda0, int ksplit, const bf16_t* __restrict__ A1, int lda1,
;                   const bf16_t* __restrict__ Bt, int K, int row0, int col0, const Epi& epi, int tid) {
;     ...
;     for (int kt = 0; kt < nk; kt += 2) {
;       LWRITE(1, 1);
;       __builtin_amdgcn_sched_barrier(0);
;       GLOAD(1, (kt + 3 < last ? kt + 3 : last));
;       __builtin_amdgcn_sched_barrier(0);
;       COMPUTE(0);
;       __syncthreads();
;       LWRITE(0, 0);
;       __builtin_amdgcn_sched_barrier(0);
;       GLOAD(0, (kt + 4 < last ? kt + 4 : last));
;       __builtin_amdgcn_sched_barrier(0);
	ds_read_b128 v[128:131], v231 offset:0
	ds_read_b128 v[132:135], v231 offset:1024
	ds_read_b128 v[136:139], v231 offset:2048
	ds_read_b128 v[140:143], v231 offset:3072
	ds_read_b128 v[144:147], v230 offset:0
	ds_read_b128 v[148:151], v230 offset:1024
	ds_read_b128 v[152:155], v230 offset:2048
	ds_read_b128 v[156:159], v230 offset:3072
	ds_read_b128 v[160:163], v230 offset:4096
	ds_read_b128 v[164:167], v230 offset:5120
	ds_read_b128 v[168:171], v230 offset:6144
	ds_read_b128 v[172:175], v230 offset:7168
	s_waitcnt vmcnt(6)
	s_waitcnt lgkmcnt(0)
	s_barrier
	v_add_u32_e32 v232, s31, v230
	v_add_u32_e32 v233, s31, v231
	s_add_u32 s26, s30, s100
	s_setprio 1
	v_mfma_f32_16x16x32_bf16 v[0:3], v[128:131], v[144:147], v[0:3]
	v_mfma_f32_16x16x32_bf16 v[4:7], v[132:135], v[144:147], v[4:7]
	v_mfma_f32_16x16x32_bf16 v[8:11], v[136:139], v[144:147], v[8:11]
	v_mfma_f32_16x16x32_bf16 v[12:15], v[140:143], v[144:147], v[12:15]
	ds_read_b128 v[176:179], v233 offset:0
	ds_read_b128 v[180:183], v233 offset:1024
	s_add_u32 m0, s26, 0
	s_nop 0
	global_load_lds_dwordx4 v224, s[0:1]
	v_mfma_f32_16x16x32_bf16 v[16:19], v[128:131], v[148:151], v[16:19]
	v_mfma_f32_16x16x32_bf16 v[20:23], v[132:135], v[148:151], v[20:23]
	v_mfma_f32_16x16x32_bf16 v[24:27], v[136:139], v[148:151], v[24:27]
	v_mfma_f32_16x16x32_bf16 v[28:31], v[140:143], v[148:151], v[28:31]
	ds_read_b128 v[184:187], v233 offset:2048
	ds_read_b128 v[188:191], v233 offset:3072
	s_add_u32 m0, s26, 4096
	s_nop 0
	global_load_lds_dwordx4 v225, s[0:1]
	v_mfma_f32_16x16x32_bf16 v[32:35], v[128:131], v[152:155], v[32:35]
	v_mfma_f32_16x16x32_bf16 v[36:39], v[132:135], v[152:155], v[36:39]
	v_mfma_f32_16x16x32_bf16 v[40:43], v[136:139], v[152:155], v[40:43]
	v_mfma_f32_16x16x32_bf16 v[44:47], v[140:143], v[152:155], v[44:47]
	ds_read_b128 v[192:195], v232 offset:0
	ds_read_b128 v[196:199], v232 offset:1024
	s_add_u32 m0, s26, 8192
	s_nop 0
	global_load_lds_dwordx4 v226, s[0:1]
	v_mfma_f32_16x16x32_bf16 v[48:51], v[128:131], v[156:159], v[48:51]
	v_mfma_f32_16x16x32_bf16 v[52:55], v[132:135], v[156:159], v[52:55]
	v_mfma_f32_16x16x32_bf16 v[56:59], v[136:139], v[156:159], v[56:59]
	v_mfma_f32_16x16x32_bf16 v[60:63], v[140:143], v[156:159], v[60:63]
	ds_read_b128 v[200:203], v232 offset:2048
	ds_read_b128 v[204:207], v232 offset:3072
	s_add_u32 m0, s26, 12288
	s_nop 0
	global_load_lds_dwordx4 v227, s[0:1]
	v_mfma_f32_16x16x32_bf16 v[64:67], v[128:131], v[160:163], v[64:67]
	v_mfma_f32_16x16x32_bf16 v[68:71], v[132:135], v[160:163], v[68:71]
	v_mfma_f32_16x16x32_bf16 v[72:75], v[136:139], v[160:163], v[72:75]
	v_mfma_f32_16x16x32_bf16 v[76:79], v[140:143], v[160:163], v[76:79]
	ds_read_b128 v[208:211], v232 offset:4096
	s_add_u32 m0, s26, 16384
	s_nop 0
	global_load_lds_dwordx4 v228, s[2:3]
	v_mfma_f32_16x16x32_bf16 v[80:83], v[128:131], v[164:167], v[80:83]
	v_mfma_f32_16x16x32_bf16 v[84:87], v[132:135], v[164:167], v[84:87]
	v_mfma_f32_16x16x32_bf16 v[88:91], v[136:139], v[164:167], v[88:91]
	v_mfma_f32_16x16x32_bf16 v[92:95], v[140:143], v[164:167], v[92:95]
	ds_read_b128 v[212:215], v232 offset:5120
	s_add_u32 m0, s26, 20480
	s_nop 0
	global_load_lds_dwordx4 v229, s[2:3]
	v_mfma_f32_16x16x32_bf16 v[96:99], v[128:131], v[168:171], v[96:99]
	v_mfma_f32_16x16x32_bf16 v[100:103], v[132:135], v[168:171], v[100:103]
	v_mfma_f32_16x16x32_bf16 v[104:107], v[136:139], v[168:171], v[104:107]
	v_mfma_f32_16x16x32_bf16 v[108:111], v[140:143], v[168:171], v[108:111]
	ds_read_b128 v[216:219], v232 offset:6144
	s_cmp_eq_u32 s25, 0
	s_cbranch_scc0 .Lg3d_hi0
	s_setprio 0
; #define LWRITE(S, buf) do { bf16_t* sA_ = sbase + (buf) * BUF; bf16_t* sB_ = sA_ + 256 * PITCH; \
;     _Pragma("unroll") for (int i_ = 0; i_ < 4; ++i_) *(u32x4*)(sA_ + (sr + i_ * 64) * PITCH + scv * 8) = ra[S][i_]; \
;     _Pragma("unroll") for (int i_ = 0; i_ < 2; ++i_) *(u32x4*)(sB_ + (sr + i_ * 64) * PITCH + scv * 8) = rb[S][i_]; } while (0)
; template <class Epi>
; DI void gemm_tile(char* smem, const bf16_t* __restrict__ A0, int lda0, int ksplit, const bf16_t* __restrict__ A1, int lda1,
;                   const bf16_t* __restrict__ Bt, int K, int row0, int col0, const Epi& epi, int tid) {
;     ...
;     for (int kt = 0; kt < nk; kt += 2) {
;       LWRITE(1, 1);
;       __builtin_amdgcn_sched_barrier(0);
;       GLOAD(1, (kt + 3 < last ? kt + 3 : last));
;       __builtin_amdgcn_sched_barrier(0);
;       COMPUTE(0);
;       __syncthreads();
;       LWRITE(0, 0);
;       __builtin_amdgcn_sched_barrier(0);
;       GLOAD(0, (kt + 4 < last ? kt + 4 : last));
;       __builtin_amdgcn_sched_barrier(0);
;       COMPUTE(1);
;       __syncthreads();
;     }
.Lg3d_hi0:
	s_add_u32 s0, s0, 64
	s_addc_u32 s1, s1, 0
	s_add_u32 s2, s2, 64
	s_addc_u32 s3, s3, 0
	s_add_u32 s99, s99, 1
	s_add_u32 s30, s30, 24576
	s_cmp_eq_u32 s30, 73728
	s_cselect_b32 s30, 0, s30
	s_add_u32 s31, s31, 24576
	s_cmp_eq_u32 s31, 73728
	s_cselect_b32 s31, 0, s31
	v_mfma_f32_16x16x32_bf16 v[112:115], v[128:131], v[172:175], v[112:115]
	v_mfma_f32_16x16x32_bf16 v[116:119], v[132:135], v[172:175], v[116:119]
	v_mfma_f32_16x16x32_bf16 v[120:123], v[136:139], v[172:175], v[120:123]
	v_mfma_f32_16x16x32_bf16 v[124:127], v[140:143], v[172:175], v[124:127]
	ds_read_b128 v[220:223], v232 offset:7168
	s_waitcnt vmcnt(6)
	s_waitcnt lgkmcnt(0)
	s_barrier
	v_add_u32_e32 v232, s31, v230
	v_add_u32_e32 v233, s31, v231
	s_setprio 1
	v_mfma_f32_16x16x32_bf16 v[0:3], v[176:179], v[192:195], v[0:3]
	v_mfma_f32_16x16x32_bf16 v[4:7], v[180:183], v[192:195], v[4:7]
	v_mfma_f32_16x16x32_bf16 v[8:11], v[184:187], v[192:195], v[8:11]
	v_mfma_f32_16x16x32_bf16 v[12:15], v[188:191], v[192:195], v[12:15]
	ds_read_b128 v[128:131], v233 offset:0
	ds_read_b128 v[132:135], v233 offset:1024
	v_mfma_f32_16x16x32_bf16 v[16:19], v[176:179], v[196:199], v[16:19]
	v_mfma_f32_16x16x32_bf16 v[20:23], v[180:183], v[196:199], v[20:23]
	v_mfma_f32_16x16x32_bf16 v[24:27], v[184:187], v[196:199], v[24:27]
	v_mfma_f32_16x16x32_bf16 v[28:31], v[188:191], v[196:199], v[28:31]
	ds_read_b128 v[136:139], v233 offset:2048
	ds_read_b128 v[140:143], v233 offset:3072
	v_mfma_f32_16x16x32_bf16 v[32:35], v[176:179], v[200:203], v[32:35]
	v_mfma_f32_16x16x32_bf16 v[36:39], v[180:183], v[200:203], v[36:39]
	v_mfma_f32_16x16x32_bf16 v[40:43], v[184:187], v[200:203], v[40:43]
	v_mfma_f32_16x16x32_bf16 v[44:47], v[188:191], v[200:203], v[44:47]
	ds_read_b128 v[144:147], v232 offset:0
	ds_read_b128 v[148:151], v232 offset:1024
	v_mfma_f32_16x16x32_bf16 v[48:51], v[176:179], v[204:207], v[48:51]
	v_mfma_f32_16x16x32_bf16 v[52:55], v[180:183], v[204:207], v[52:55]
	v_mfma_f32_16x16x32_bf16 v[56:59], v[184:187], v[204:207], v[56:59]
	v_mfma_f32_16x16x32_bf16 v[60:63], v[188:191], v[204:207], v[60:63]
	ds_read_b128 v[152:155], v232 offset:2048
	ds_read_b128 v[156:159], v232 offset:3072
	v_mfma_f32_16x16x32_bf16 v[64:67], v[176:179], v[208:211], v[64:67]
	v_mfma_f32_16x16x32_bf16 v[68:71], v[180:183], v[208:211], v[68:71]
	v_mfma_f32_16x16x32_bf16 v[72:75], v[184:187], v[208:211], v[72:75]
	v_mfma_f32_16x16x32_bf16 v[76:79], v[188:191], v[208:211], v[76:79]
	ds_read_b128 v[160:163], v232 offset:4096
	v_mfma_f32_16x16x32_bf16 v[80:83], v[176:179], v[212:215], v[80:83]
	v_mfma_f32_16x16x32_bf16 v[84:87], v[180:183], v[212:215], v[84:87]
	v_mfma_f32_16x16x32_bf16 v[88:91], v[184:187], v[212:215], v[88:91]
	v_mfma_f32_16x16x32_bf16 v[92:95], v[188:191], v[212:215], v[92:95]
	ds_read_b128 v[164:167], v232 offset:5120
	v_mfma_f32_16x16x32_bf16 v[96:99], v[176:179], v[216:219], v[96:99]
	v_mfma_f32_16x16x32_bf16 v[100:103], v[180:183], v[216:219], v[100:103]
	v_mfma_f32_16x16x32_bf16 v[104:107], v[184:187], v[216:219], v[104:107]
	v_mfma_f32_16x16x32_bf16 v[108:111], v[188:191], v[216:219], v[108:111]
	ds_read_b128 v[168:171], v232 offset:6144
	s_cmp_eq_u32 s25, 0
	s_cbranch_scc0 .Lg3d_hi1
	s_setprio 0
.Lg3d_hi1:
	s_add_u32 s31, s31, 24576
	s_cmp_eq_u32 s31, 73728
	s_cselect_b32 s31, 0, s31
	v_mfma_f32_16x16x32_bf16 v[112:115], v[176:179], v[220:223], v[112:115]
	v_mfma_f32_16x16x32_bf16 v[116:119], v[180:183], v[220:223], v[116:119]
	v_mfma_f32_16x16x32_bf16 v[120:123], v[184:187], v[220:223], v[120:123]
	v_mfma_f32_16x16x32_bf16 v[124:127], v[188:191], v[220:223], v[124:127]
	ds_read_b128 v[172:175], v232 offset:7168
	s_waitcnt vmcnt(0)
	s_waitcnt lgkmcnt(0)
	s_barrier
	v_add_u32_e32 v232, s31, v230
	v_add_u32_e32 v233, s31, v231
	s_setprio 1
	v_mfma_f32_16x16x32_bf16 v[0:3], v[128:131], v[144:147], v[0:3]
	v_mfma_f32_16x16x32_bf16 v[4:7], v[132:135], v[144:147], v[4:7]
	v_mfma_f32_16x16x32_bf16 v[8:11], v[136:139], v[144:147], v[8:11]
	v_mfma_f32_16x16x32_bf16 v[12:15], v[140:143], v[144:147], v[12:15]
	ds_read_b128 v[176:179], v233 offset:0
	ds_read_b128 v[180:183], v233 offset:1024
	v_mfma_f32_16x16x32_bf16 v[16:19], v[128:131], v[148:151], v[16:19]
	v_mfma_f32_16x16x32_bf16 v[20:23], v[132:135], v[148:151], v[20:23]
	v_mfma_f32_16x16x32_bf16 v[24:27], v[136:139], v[148:151], v[24:27]
	v_mfma_f32_16x16x32_bf16 v[28:31], v[140:143], v[148:151], v[28:31]
	ds_read_b128 v[184:187], v233 offset:2048
	ds_read_b128 v[188:191], v233 offset:3072
	v_mfma_f32_16x16x32_bf16 v[32:35], v[128:131], v[152:155], v[32:35]
	v_mfma_f32_16x16x32_bf16 v[36:39], v[132:135], v[152:155], v[36:39]
	v_mfma_f32_16x16x32_bf16 v[40:43], v[136:139], v[152:155], v[40:43]
	v_mfma_f32_16x16x32_bf16 v[44:47], v[140:143], v[152:155], v[44:47]
	ds_read_b128 v[192:195], v232 offset:0
	ds_read_b128 v[196:199], v232 offset:1024
	v_mfma_f32_16x16x32_bf16 v[48:51], v[128:131], v[156:159], v[48:51]
	v_mfma_f32_16x16x32_bf16 v[52:55], v[132:135], v[156:159], v[52:55]
	v_mfma_f32_16x16x32_bf16 v[56:59], v[136:139], v[156:159], v[56:59]
	v_mfma_f32_16x16x32_bf16 v[60:63], v[140:143], v[156:159], v[60:63]
	ds_read_b128 v[200:203], v232 offset:2048
	ds_read_b128 v[204:207], v232 offset:3072
	v_mfma_f32_16x16x32_bf16 v[64:67], v[128:131], v[160:163], v[64:67]
	v_mfma_f32_16x16x32_bf16 v[68:71], v[132:135], v[160:163], v[68:71]
	v_mfma_f32_16x16x32_bf16 v[72:75], v[136:139], v[160:163], v[72:75]
	v_mfma_f32_16x16x32_bf16 v[76:79], v[140:143], v[160:163], v[76:79]
	ds_read_b128 v[208:211], v232 offset:4096
	v_mfma_f32_16x16x32_bf16 v[80:83], v[128:131], v[164:167], v[80:83]
	v_mfma_f32_16x16x32_bf16 v[84:87], v[132:135], v[164:167], v[84:87]
	v_mfma_f32_16x16x32_bf16 v[88:91], v[136:139], v[164:167], v[88:91]
	v_mfma_f32_16x16x32_bf16 v[92:95], v[140:143], v[164:167], v[92:95]
	ds_read_b128 v[212:215], v232 offset:5120
	v_mfma_f32_16x16x32_bf16 v[96:99], v[128:131], v[168:171], v[96:99]
	v_mfma_f32_16x16x32_bf16 v[100:103], v[132:135], v[168:171], v[100:103]
	v_mfma_f32_16x16x32_bf16 v[104:107], v[136:139], v[168:171], v[104:107]
	v_mfma_f32_16x16x32_bf16 v[108:111], v[140:143], v[168:171], v[108:111]
	ds_read_b128 v[216:219], v232 offset:6144
	s_cmp_eq_u32 s25, 0
	s_cbranch_scc0 .Lg3d_hi2
	s_setprio 0

; #define LWRITE(S, buf) do { bf16_t* sA_ = sbase + (buf) * BUF; bf16_t* sB_ = sA_ + 256 * PITCH; \
;     _Pragma("unroll") for (int i_ = 0; i_ < 4; ++i_) *(u32x4*)(sA_ + (sr + i_ * 64) * PITCH + scv * 8) = ra[S][i_]; \
;     _Pragma("unroll") for (int i_ = 0; i_ < 2; ++i_) *(u32x4*)(sB_ + (sr + i_ * 64) * PITCH + scv * 8) = rb[S][i_]; } while (0)
; template <class Epi>
; DI void gemm_tile(char* smem, const bf16_t* __restrict__ A0, int lda0, int ksplit, const bf16_t* __restrict__ A1, int lda1,
;                   const bf16_t* __restrict__ Bt, int K, int row0, int col0, const Epi& epi, int tid) {
;     ...
;     for (int kt = 0; kt < nk; kt += 2) {
;       LWRITE(1, 1);
;       __builtin_amdgcn_sched_barrier(0);
;       GLOAD(1, (kt + 3 < last ? kt + 3 : last));
;       __builtin_amdgcn_sched_barrier(0);
;       COMPUTE(0);
;       __syncthreads();
;       LWRITE(0, 0);
;       __builtin_amdgcn_sched_barrier(0);
;       GLOAD(0, (kt + 4 < last ? kt + 4 : last));
;       __builtin_amdgcn_sched_barrier(0);
;       COMPUTE(1);
;       __syncthreads();
;     }
.Lg6_swb0:
	s_waitcnt vmcnt(6)
	s_waitcnt lgkmcnt(0)
	s_barrier
	v_add_u32_e32 v232, s100, v230
	v_add_u32_e32 v233, s100, v231
	s_add_u32 s19, s99, s13
	s_setprio 1
	v_mfma_f32_16x16x32_bf16 v[0:3], v[128:131], v[144:147], v[0:3]
	v_mfma_f32_16x16x32_bf16 v[4:7], v[132:135], v[144:147], v[4:7]
	v_mfma_f32_16x16x32_bf16 v[8:11], v[136:139], v[144:147], v[8:11]
	v_mfma_f32_16x16x32_bf16 v[12:15], v[140:143], v[144:147], v[12:15]
	ds_read_b128 v[176:179], v233 offset:0
	ds_read_b128 v[180:183], v233 offset:1024
	s_add_u32 m0, s19, 0
	s_nop 0
	global_load_lds_dwordx4 v224, s[0:1]
	v_mfma_f32_16x16x32_bf16 v[16:19], v[128:131], v[148:151], v[16:19]
	v_mfma_f32_16x16x32_bf16 v[20:23], v[132:135], v[148:151], v[20:23]
	v_mfma_f32_16x16x32_bf16 v[24:27], v[136:139], v[148:151], v[24:27]
	v_mfma_f32_16x16x32_bf16 v[28:31], v[140:143], v[148:151], v[28:31]
	ds_read_b128 v[184:187], v233 offset:2048
	ds_read_b128 v[188:191], v233 offset:3072
	s_add_u32 m0, s19, 4096
	s_nop 0
	global_load_lds_dwordx4 v225, s[0:1]
	v_mfma_f32_16x16x32_bf16 v[32:35], v[128:131], v[152:155], v[32:35]
	v_mfma_f32_16x16x32_bf16 v[36:39], v[132:135], v[152:155], v[36:39]
	v_mfma_f32_16x16x32_bf16 v[40:43], v[136:139], v[152:155], v[40:43]
	v_mfma_f32_16x16x32_bf16 v[44:47], v[140:143], v[152:155], v[44:47]
	ds_read_b128 v[192:195], v232 offset:0
	ds_read_b128 v[196:199], v232 offset:1024
	s_add_u32 m0, s19, 8192
	s_nop 0
	global_load_lds_dwordx4 v226, s[0:1]
	v_mfma_f32_16x16x32_bf16 v[48:51], v[128:131], v[156:159], v[48:51]
	v_mfma_f32_16x16x32_bf16 v[52:55], v[132:135], v[156:159], v[52:55]
	v_mfma_f32_16x16x32_bf16 v[56:59], v[136:139], v[156:159], v[56:59]
	v_mfma_f32_16x16x32_bf16 v[60:63], v[140:143], v[156:159], v[60:63]
	ds_read_b128 v[200:203], v232 offset:2048
	ds_read_b128 v[204:207], v232 offset:3072
	s_add_u32 m0, s19, 12288
	s_nop 0
	global_load_lds_dwordx4 v227, s[0:1]
	v_mfma_f32_16x16x32_bf16 v[64:67], v[128:131], v[160:163], v[64:67]
	v_mfma_f32_16x16x32_bf16 v[68:71], v[132:135], v[160:163], v[68:71]
	v_mfma_f32_16x16x32_bf16 v[72:75], v[136:139], v[160:163], v[72:75]
	v_mfma_f32_16x16x32_bf16 v[76:79], v[140:143], v[160:163], v[76:79]
	ds_read_b128 v[208:211], v232 offset:4096
	s_add_u32 m0, s19, 16384
	s_nop 0
	global_load_lds_dwordx4 v228, s[2:3]
	v_mfma_f32_16x16x32_bf16 v[80:83], v[128:131], v[164:167], v[80:83]
	v_mfma_f32_16x16x32_bf16 v[84:87], v[132:135], v[164:167], v[84:87]
	v_mfma_f32_16x16x32_bf16 v[88:91], v[136:139], v[164:167], v[88:91]
	v_mfma_f32_16x16x32_bf16 v[92:95], v[140:143], v[164:167], v[92:95]
	ds_read_b128 v[212:215], v232 offset:5120
	s_add_u32 m0, s19, 20480
	s_nop 0
	global_load_lds_dwordx4 v229, s[2:3]
	v_mfma_f32_16x16x32_bf16 v[96:99], v[128:131], v[168:171], v[96:99]
	v_mfma_f32_16x16x32_bf16 v[100:103], v[132:135], v[168:171], v[100:103]
	v_mfma_f32_16x16x32_bf16 v[104:107], v[136:139], v[168:171], v[104:107]
	v_mfma_f32_16x16x32_bf16 v[108:111], v[140:143], v[168:171], v[108:111]
	ds_read_b128 v[216:219], v232 offset:6144
	s_cmp_eq_u32 s18, 0
	s_cbranch_scc0 .Lg6_hi0
	s_setprio 0
.Lg6_hi0:
	s_add_u32 s0, s0, 64
	s_addc_u32 s1, s1, 0
	s_add_u32 s2, s2, 64
	s_addc_u32 s3, s3, 0
	s_add_u32 s22, s22, 1
	s_add_u32 s99, s99, 24576
	s_cmp_eq_u32 s99, 73728
	s_cselect_b32 s99, 0, s99
	s_add_u32 s100, s100, 24576
	s_cmp_eq_u32 s100, 73728
	s_cselect_b32 s100, 0, s100
	v_mfma_f32_16x16x32_bf16 v[112:115], v[128:131], v[172:175], v[112:115]
	v_mfma_f32_16x16x32_bf16 v[116:119], v[132:135], v[172:175], v[116:119]
	v_mfma_f32_16x16x32_bf16 v[120:123], v[136:139], v[172:175], v[120:123]
	v_mfma_f32_16x16x32_bf16 v[124:127], v[140:143], v[172:175], v[124:127]
	ds_read_b128 v[220:223], v232 offset:7168
	s_cmp_eq_u32 s22, 16
	s_cbranch_scc1 .Lg6_sw1
; #define LWRITE(S, buf) do { bf16_t* sA_ = sbase + (buf) * BUF; bf16_t* sB_ = sA_ + 256 * PITCH; \
;     _Pragma("unroll") for (int i_ = 0; i_ < 4; ++i_) *(u32x4*)(sA_ + (sr + i_ * 64) * PITCH + scv * 8) = ra[S][i_]; \
;     _Pragma("unroll") for (int i_ = 0; i_ < 2; ++i_) *(u32x4*)(sB_ + (sr + i_ * 64) * PITCH + scv * 8) = rb[S][i_]; } while (0)
; template <class Epi>
; DI void gemm_tile(char* smem, const bf16_t* __restrict__ A0, int lda0, int ksplit, const bf16_t* __restrict__ A1, int lda1,
;                   const bf16_t* __restrict__ Bt, int K, int row0, int col0, const Epi& epi, int tid) {
;     ...
;     for (int kt = 0; kt < nk; kt += 2) {
;       LWRITE(1, 1);
;       __builtin_amdgcn_sched_barrier(0);
;       GLOAD(1, (kt + 3 < last ? kt + 3 : last));
;       __builtin_amdgcn_sched_barrier(0);
;       COMPUTE(0);
;       __syncthreads();
;       LWRITE(0, 0);
;       __builtin_amdgcn_sched_barrier(0);
;       GLOAD(0, (kt + 4 < last ? kt + 4 : last));
;       __builtin_amdgcn_sched_barrier(0);
;       COMPUTE(1);
;       __syncthreads();
;     }
.Lg6_swb1:
	s_waitcnt vmcnt(6)
	s_waitcnt lgkmcnt(0)
	s_barrier
	v_add_u32_e32 v232, s100, v230
	v_add_u32_e32 v233, s100, v231
	s_add_u32 s19, s99, s13
	s_setprio 1
	v_mfma_f32_16x16x32_bf16 v[0:3], v[176:179], v[192:195], v[0:3]
	v_mfma_f32_16x16x32_bf16 v[4:7], v[180:183], v[192:195], v[4:7]
	v_mfma_f32_16x16x32_bf16 v[8:11], v[184:187], v[192:195], v[8:11]
	v_mfma_f32_16x16x32_bf16 v[12:15], v[188:191], v[192:195], v[12:15]
	ds_read_b128 v[128:131], v233 offset:0
	ds_read_b128 v[132:135], v233 offset:1024
	s_add_u32 m0, s19, 0
	s_nop 0
	global_load_lds_dwordx4 v224, s[0:1]
	v_mfma_f32_16x16x32_bf16 v[16:19], v[176:179], v[196:199], v[16:19]
	v_mfma_f32_16x16x32_bf16 v[20:23], v[180:183], v[196:199], v[20:23]
	v_mfma_f32_16x16x32_bf16 v[24:27], v[184:187], v[196:199], v[24:27]
	v_mfma_f32_16x16x32_bf16 v[28:31], v[188:191], v[196:199], v[28:31]
	ds_read_b128 v[136:139], v233 offset:2048
	ds_read_b128 v[140:143], v233 offset:3072
	s_add_u32 m0, s19, 4096
	s_nop 0
	global_load_lds_dwordx4 v225, s[0:1]
	v_mfma_f32_16x16x32_bf16 v[32:35], v[176:179], v[200:203], v[32:35]
	v_mfma_f32_16x16x32_bf16 v[36:39], v[180:183], v[200:203], v[36:39]
	v_mfma_f32_16x16x32_bf16 v[40:43], v[184:187], v[200:203], v[40:43]
	v_mfma_f32_16x16x32_bf16 v[44:47], v[188:191], v[200:203], v[44:47]
	ds_read_b128 v[144:147], v232 offset:0
	ds_read_b128 v[148:151], v232 offset:1024
	s_add_u32 m0, s19, 8192
	s_nop 0
	global_load_lds_dwordx4 v226, s[0:1]
	v_mfma_f32_16x16x32_bf16 v[48:51], v[176:179], v[204:207], v[48:51]
	v_mfma_f32_16x16x32_bf16 v[52:55], v[180:183], v[204:207], v[52:55]
	v_mfma_f32_16x16x32_bf16 v[56:59], v[184:187], v[204:207], v[56:59]
	v_mfma_f32_16x16x32_bf16 v[60:63], v[188:191], v[204:207], v[60:63]
	ds_read_b128 v[152:155], v232 offset:2048
	ds_read_b128 v[156:159], v232 offset:3072
	s_add_u32 m0, s19, 12288
	s_nop 0
	global_load_lds_dwordx4 v227, s[0:1]
	v_mfma_f32_16x16x32_bf16 v[64:67], v[176:179], v[208:211], v[64:67]
	v_mfma_f32_16x16x32_bf16 v[68:71], v[180:183], v[208:211], v[68:71]
	v_mfma_f32_16x16x32_bf16 v[72:75], v[184:187], v[208:211], v[72:75]
	v_mfma_f32_16x16x32_bf16 v[76:79], v[188:191], v[208:211], v[76:79]
	ds_read_b128 v[160:163], v232 offset:4096
	s_add_u32 m0, s19, 16384
	s_nop 0
	global_load_lds_dwordx4 v228, s[2:3]
	v_mfma_f32_16x16x32_bf16 v[80:83], v[176:179], v[212:215], v[80:83]
	v_mfma_f32_16x16x32_bf16 v[84:87], v[180:183], v[212:215], v[84:87]
	v_mfma_f32_16x16x32_bf16 v[88:91], v[184:187], v[212:215], v[88:91]
	v_mfma_f32_16x16x32_bf16 v[92:95], v[188:191], v[212:215], v[92:95]
	ds_read_b128 v[164:167], v232 offset:5120
	s_add_u32 m0, s19, 20480
	s_nop 0
	global_load_lds_dwordx4 v229, s[2:3]
	v_mfma_f32_16x16x32_bf16 v[96:99], v[176:179], v[216:219], v[96:99]
	v_mfma_f32_16x16x32_bf16 v[100:103], v[180:183], v[216:219], v[100:103]
	v_mfma_f32_16x16x32_bf16 v[104:107], v[184:187], v[216:219], v[104:107]
	v_mfma_f32_16x16x32_bf16 v[108:111], v[188:191], v[216:219], v[108:111]
	ds_read_b128 v[168:171], v232 offset:6144
	s_cmp_eq_u32 s18, 0
	s_cbranch_scc0 .Lg6_hi1
	s_setprio 0
.Lg6_hi1:
	s_add_u32 s0, s0, 64
	s_addc_u32 s1, s1, 0
	s_add_u32 s2, s2, 64
	s_addc_u32 s3, s3, 0
	s_add_u32 s22, s22, 1
	s_add_u32 s99, s99, 24576
	s_cmp_eq_u32 s99, 73728
	s_cselect_b32 s99, 0, s99
	s_add_u32 s100, s100, 24576
	s_cmp_eq_u32 s100, 73728
	s_cselect_b32 s100, 0, s100
	v_mfma_f32_16x16x32_bf16 v[112:115], v[176:179], v[220:223], v[112:115]
	v_mfma_f32_16x16x32_bf16 v[116:119], v[180:183], v[220:223], v[116:119]
	v_mfma_f32_16x16x32_bf16 v[120:123], v[184:187], v[220:223], v[120:123]
	v_mfma_f32_16x16x32_bf16 v[124:127], v[188:191], v[220:223], v[124:127]
	ds_read_b128 v[172:175], v232 offset:7168
	s_add_u32 s101, s101, 2
	s_cmp_lt_u32 s101, 44
	s_cbranch_scc1 .Lg6_kloop
	s_cmp_eq_u32 s22, 16
	s_cbranch_scc1 .Lg6_sw2

; #define LWRITE(S, buf) do { bf16_t* sA_ = sbase + (buf) * BUF; bf16_t* sB_ = sA_ + 256 * PITCH; \
;     _Pragma("unroll") for (int i_ = 0; i_ < 4; ++i_) *(u32x4*)(sA_ + (sr + i_ * 64) * PITCH + scv * 8) = ra[S][i_]; \
;     _Pragma("unroll") for (int i_ = 0; i_ < 2; ++i_) *(u32x4*)(sB_ + (sr + i_ * 64) * PITCH + scv * 8) = rb[S][i_]; } while (0)
; template <class Epi>
; DI void gemm_tile(char* smem, const bf16_t* __restrict__ A0, int lda0, int ksplit, const bf16_t* __restrict__ A1, int lda1,
;                   const bf16_t* __restrict__ Bt, int K, int row0, int col0, const Epi& epi, int tid) {
;     ...
;     for (int kt = 0; kt < nk; kt += 2) {
;       LWRITE(1, 1);
;       __builtin_amdgcn_sched_barrier(0);
;       GLOAD(1, (kt + 3 < last ? kt + 3 : last));
;       __builtin_amdgcn_sched_barrier(0);
;       COMPUTE(0);
;       __syncthreads();
;       LWRITE(0, 0);
;       __builtin_amdgcn_sched_barrier(0);
;       GLOAD(0, (kt + 4 < last ? kt + 4 : last));
;       __builtin_amdgcn_sched_barrier(0);
;       COMPUTE(1);
;       __syncthreads();
;     }
.Lg6_hi2:
	s_add_u32 s0, s0, 64
	s_addc_u32 s1, s1, 0
	s_add_u32 s2, s2, 64
	s_addc_u32 s3, s3, 0
	s_add_u32 s22, s22, 1
	s_add_u32 s99, s99, 24576
	s_cmp_eq_u32 s99, 73728
	s_cselect_b32 s99, 0, s99
	s_add_u32 s100, s100, 24576
	s_cmp_eq_u32 s100, 73728
	s_cselect_b32 s100, 0, s100
	v_mfma_f32_16x16x32_bf16 v[112:115], v[128:131], v[172:175], v[112:115]
	v_mfma_f32_16x16x32_bf16 v[116:119], v[132:135], v[172:175], v[116:119]
	v_mfma_f32_16x16x32_bf16 v[120:123], v[136:139], v[172:175], v[120:123]
	v_mfma_f32_16x16x32_bf16 v[124:127], v[140:143], v[172:175], v[124:127]
	ds_read_b128 v[220:223], v232 offset:7168
	s_waitcnt vmcnt(6)
	s_waitcnt lgkmcnt(0)
	s_barrier
	v_add_u32_e32 v232, s100, v230
	v_add_u32_e32 v233, s100, v231
	s_setprio 1
	v_mfma_f32_16x16x32_bf16 v[0:3], v[176:179], v[192:195], v[0:3]
	v_mfma_f32_16x16x32_bf16 v[4:7], v[180:183], v[192:195], v[4:7]
	v_mfma_f32_16x16x32_bf16 v[8:11], v[184:187], v[192:195], v[8:11]
	v_mfma_f32_16x16x32_bf16 v[12:15], v[188:191], v[192:195], v[12:15]
	ds_read_b128 v[128:131], v233 offset:0
	ds_read_b128 v[132:135], v233 offset:1024
	v_mfma_f32_16x16x32_bf16 v[16:19], v[176:179], v[196:199], v[16:19]
	v_mfma_f32_16x16x32_bf16 v[20:23], v[180:183], v[196:199], v[20:23]
	v_mfma_f32_16x16x32_bf16 v[24:27], v[184:187], v[196:199], v[24:27]
	v_mfma_f32_16x16x32_bf16 v[28:31], v[188:191], v[196:199], v[28:31]
	ds_read_b128 v[136:139], v233 offset:2048
	ds_read_b128 v[140:143], v233 offset:3072
	v_mfma_f32_16x16x32_bf16 v[32:35], v[176:179], v[200:203], v[32:35]
	v_mfma_f32_16x16x32_bf16 v[36:39], v[180:183], v[200:203], v[36:39]
	v_mfma_f32_16x16x32_bf16 v[40:43], v[184:187], v[200:203], v[40:43]
	v_mfma_f32_16x16x32_bf16 v[44:47], v[188:191], v[200:203], v[44:47]
	ds_read_b128 v[144:147], v232 offset:0
	ds_read_b128 v[148:151], v232 offset:1024
	v_mfma_f32_16x16x32_bf16 v[48:51], v[176:179], v[204:207], v[48:51]
	v_mfma_f32_16x16x32_bf16 v[52:55], v[180:183], v[204:207], v[52:55]
	v_mfma_f32_16x16x32_bf16 v[56:59], v[184:187], v[204:207], v[56:59]
	v_mfma_f32_16x16x32_bf16 v[60:63], v[188:191], v[204:207], v[60:63]
	ds_read_b128 v[152:155], v232 offset:2048
	ds_read_b128 v[156:159], v232 offset:3072
	v_mfma_f32_16x16x32_bf16 v[64:67], v[176:179], v[208:211], v[64:67]
	v_mfma_f32_16x16x32_bf16 v[68:71], v[180:183], v[208:211], v[68:71]
	v_mfma_f32_16x16x32_bf16 v[72:75], v[184:187], v[208:211], v[72:75]
	v_mfma_f32_16x16x32_bf16 v[76:79], v[188:191], v[208:211], v[76:79]
	ds_read_b128 v[160:163], v232 offset:4096
	v_mfma_f32_16x16x32_bf16 v[80:83], v[176:179], v[212:215], v[80:83]
	v_mfma_f32_16x16x32_bf16 v[84:87], v[180:183], v[212:215], v[84:87]
	v_mfma_f32_16x16x32_bf16 v[88:91], v[184:187], v[212:215], v[88:91]
	v_mfma_f32_16x16x32_bf16 v[92:95], v[188:191], v[212:215], v[92:95]
	ds_read_b128 v[164:167], v232 offset:5120
	v_mfma_f32_16x16x32_bf16 v[96:99], v[176:179], v[216:219], v[96:99]
	v_mfma_f32_16x16x32_bf16 v[100:103], v[180:183], v[216:219], v[100:103]
	v_mfma_f32_16x16x32_bf16 v[104:107], v[184:187], v[216:219], v[104:107]
	v_mfma_f32_16x16x32_bf16 v[108:111], v[188:191], v[216:219], v[108:111]
	ds_read_b128 v[168:171], v232 offset:6144
	s_cmp_eq_u32 s18, 0
	s_cbranch_scc0 .Lg6_hi3
	s_setprio 0
.Lg6_hi3:
	s_add_u32 s100, s100, 24576
	s_cmp_eq_u32 s100, 73728
	s_cselect_b32 s100, 0, s100
	v_mfma_f32_16x16x32_bf16 v[112:115], v[176:179], v[220:223], v[112:115]
	v_mfma_f32_16x16x32_bf16 v[116:119], v[180:183], v[220:223], v[116:119]
	v_mfma_f32_16x16x32_bf16 v[120:123], v[184:187], v[220:223], v[120:123]
	v_mfma_f32_16x16x32_bf16 v[124:127], v[188:191], v[220:223], v[124:127]
	ds_read_b128 v[172:175], v232 offset:7168
	s_waitcnt vmcnt(0)
	s_waitcnt lgkmcnt(0)
	s_barrier
	v_add_u32_e32 v232, s100, v230
	v_add_u32_e32 v233, s100, v231
	s_setprio 1
	v_mfma_f32_16x16x32_bf16 v[0:3], v[128:131], v[144:147], v[0:3]
	v_mfma_f32_16x16x32_bf16 v[4:7], v[132:135], v[144:147], v[4:7]
	v_mfma_f32_16x16x32_bf16 v[8:11], v[136:139], v[144:147], v[8:11]
	v_mfma_f32_16x16x32_bf16 v[12:15], v[140:143], v[144:147], v[12:15]
	ds_read_b128 v[176:179], v233 offset:0
	ds_read_b128 v[180:183], v233 offset:1024
	v_mfma_f32_16x16x32_bf16 v[16:19], v[128:131], v[148:151], v[16:19]
	v_mfma_f32_16x16x32_bf16 v[20:23], v[132:135], v[148:151], v[20:23]
	v_mfma_f32_16x16x32_bf16 v[24:27], v[136:139], v[148:151], v[24:27]
	v_mfma_f32_16x16x32_bf16 v[28:31], v[140:143], v[148:151], v[28:31]
	ds_read_b128 v[184:187], v233 offset:2048
	ds_read_b128 v[188:191], v233 offset:3072
	v_mfma_f32_16x16x32_bf16 v[32:35], v[128:131], v[152:155], v[32:35]
	v_mfma_f32_16x16x32_bf16 v[36:39], v[132:135], v[152:155], v[36:39]
	v_mfma_f32_16x16x32_bf16 v[40:43], v[136:139], v[152:155], v[40:43]
	v_mfma_f32_16x16x32_bf16 v[44:47], v[140:143], v[152:155], v[44:47]
	ds_read_b128 v[192:195], v232 offset:0
	ds_read_b128 v[196:199], v232 offset:1024
	v_mfma_f32_16x16x32_bf16 v[48:51], v[128:131], v[156:159], v[48:51]
	v_mfma_f32_16x16x32_bf16 v[52:55], v[132:135], v[156:159], v[52:55]
	v_mfma_f32_16x16x32_bf16 v[56:59], v[136:139], v[156:159], v[56:59]
	v_mfma_f32_16x16x32_bf16 v[60:63], v[140:143], v[156:159], v[60:63]
	ds_read_b128 v[200:203], v232 offset:2048
	ds_read_b128 v[204:207], v232 offset:3072
	v_mfma_f32_16x16x32_bf16 v[64:67], v[128:131], v[160:163], v[64:67]
	v_mfma_f32_16x16x32_bf16 v[68:71], v[132:135], v[160:163], v[68:71]
	v_mfma_f32_16x16x32_bf16 v[72:75], v[136:139], v[160:163], v[72:75]
	v_mfma_f32_16x16x32_bf16 v[76:79], v[140:143], v[160:163], v[76:79]
	ds_read_b128 v[208:211], v232 offset:4096
	v_mfma_f32_16x16x32_bf16 v[80:83], v[128:131], v[164:167], v[80:83]
	v_mfma_f32_16x16x32_bf16 v[84:87], v[132:135], v[164:167], v[84:87]
	v_mfma_f32_16x16x32_bf16 v[88:91], v[136:139], v[164:167], v[88:91]
	v_mfma_f32_16x16x32_bf16 v[92:95], v[140:143], v[164:167], v[92:95]
	ds_read_b128 v[212:215], v232 offset:5120
	v_mfma_f32_16x16x32_bf16 v[96:99], v[128:131], v[168:171], v[96:99]
	v_mfma_f32_16x16x32_bf16 v[100:103], v[132:135], v[168:171], v[100:103]
	v_mfma_f32_16x16x32_bf16 v[104:107], v[136:139], v[168:171], v[104:107]
	v_mfma_f32_16x16x32_bf16 v[108:111], v[140:143], v[168:171], v[108:111]
	ds_read_b128 v[216:219], v232 offset:6144
	s_cmp_eq_u32 s18, 0
	s_cbranch_scc0 .Lg6_hi4
	s_setprio 0
.Lg6_hi4:
	s_add_u32 s100, s100, 24576
	s_cmp_eq_u32 s100, 73728
	s_cselect_b32 s100, 0, s100
	v_mfma_f32_16x16x32_bf16 v[112:115], v[128:131], v[172:175], v[112:115]
	v_mfma_f32_16x16x32_bf16 v[116:119], v[132:135], v[172:175], v[116:119]
	v_mfma_f32_16x16x32_bf16 v[120:123], v[136:139], v[172:175], v[120:123]
	v_mfma_f32_16x16x32_bf16 v[124:127], v[140:143], v[172:175], v[124:127]
	ds_read_b128 v[220:223], v232 offset:7168
	s_waitcnt lgkmcnt(0)
	s_barrier
	s_setprio 1
	v_mfma_f32_16x16x32_bf16 v[0:3], v[176:179], v[192:195], v[0:3]
	v_mfma_f32_16x16x32_bf16 v[4:7], v[180:183], v[192:195], v[4:7]
	v_mfma_f32_16x16x32_bf16 v[8:11], v[184:187], v[192:195], v[8:11]
	v_mfma_f32_16x16x32_bf16 v[12:15], v[188:191], v[192:195], v[12:15]
	v_mfma_f32_16x16x32_bf16 v[16:19], v[176:179], v[196:199], v[16:19]
	v_mfma_f32_16x16x32_bf16 v[20:23], v[180:183], v[196:199], v[20:23]
	v_mfma_f32_16x16x32_bf16 v[24:27], v[184:187], v[196:199], v[24:27]
	v_mfma_f32_16x16x32_bf16 v[28:31], v[188:191], v[196:199], v[28:31]
	v_mfma_f32_16x16x32_bf16 v[32:35], v[176:179], v[200:203], v[32:35]
	v_mfma_f32_16x16x32_bf16 v[36:39], v[180:183], v[200:203], v[36:39]
	v_mfma_f32_16x16x32_bf16 v[40:43], v[184:187], v[200:203], v[40:43]
	v_mfma_f32_16x16x32_bf16 v[44:47], v[188:191], v[200:203], v[44:47]
	v_mfma_f32_16x16x32_bf16 v[48:51], v[176:179], v[204:207], v[48:51]
	v_mfma_f32_16x16x32_bf16 v[52:55], v[180:183], v[204:207], v[52:55]
	v_mfma_f32_16x16x32_bf16 v[56:59], v[184:187], v[204:207], v[56:59]
	v_mfma_f32_16x16x32_bf16 v[60:63], v[188:191], v[204:207], v[60:63]
	v_mfma_f32_16x16x32_bf16 v[64:67], v[176:179], v[208:211], v[64:67]
	v_mfma_f32_16x16x32_bf16 v[68:71], v[180:183], v[208:211], v[68:71]
	v_mfma_f32_16x16x32_bf16 v[72:75], v[184:187], v[208:211], v[72:75]
	v_mfma_f32_16x16x32_bf16 v[76:79], v[188:191], v[208:211], v[76:79]
	v_mfma_f32_16x16x32_bf16 v[80:83], v[176:179], v[212:215], v[80:83]
	v_mfma_f32_16x16x32_bf16 v[84:87], v[180:183], v[212:215], v[84:87]
	v_mfma_f32_16x16x32_bf16 v[88:91], v[184:187], v[212:215], v[88:91]
	v_mfma_f32_16x16x32_bf16 v[92:95], v[188:191], v[212:215], v[92:95]
	v_mfma_f32_16x16x32_bf16 v[96:99], v[176:179], v[216:219], v[96:99]
	v_mfma_f32_16x16x32_bf16 v[100:103], v[180:183], v[216:219], v[100:103]
	v_mfma_f32_16x16x32_bf16 v[104:107], v[184:187], v[216:219], v[104:107]
	v_mfma_f32_16x16x32_bf16 v[108:111], v[188:191], v[216:219], v[108:111]
	s_cmp_eq_u32 s18, 0
	s_cbranch_scc0 .Lg6_hi5
	s_setprio 0

; #define LWRITE(S, buf) do { bf16_t* sA_ = sbase + (buf) * BUF; bf16_t* sB_ = sA_ + 256 * PITCH; \
;     _Pragma("unroll") for (int i_ = 0; i_ < 4; ++i_) *(u32x4*)(sA_ + (sr + i_ * 64) * PITCH + scv * 8) = ra[S][i_]; \
;     _Pragma("unroll") for (int i_ = 0; i_ < 2; ++i_) *(u32x4*)(sB_ + (sr + i_ * 64) * PITCH + scv * 8) = rb[S][i_]; } while (0)
; template <class Epi>
; DI void gemm_tile(char* smem, const bf16_t* __restrict__ A0, int lda0, int ksplit, const bf16_t* __restrict__ A1, int lda1,
;                   const bf16_t* __restrict__ Bt, int K, int row0, int col0, const Epi& epi, int tid) {
;     ...
;     for (int kt = 0; kt < nk; kt += 2) {
;       LWRITE(1, 1);
;       __builtin_amdgcn_sched_barrier(0);
;       GLOAD(1, (kt + 3 < last ? kt + 3 : last));
;       __builtin_amdgcn_sched_barrier(0);
;       COMPUTE(0);
;       __syncthreads();
;       LWRITE(0, 0);
;       __builtin_amdgcn_sched_barrier(0);
;       GLOAD(0, (kt + 4 < last ? kt + 4 : last));
;       __builtin_amdgcn_sched_barrier(0);
;       COMPUTE(1);
;       __syncthreads();
;     }
.Lg8_kloop:
	s_waitcnt vmcnt(6)
	s_waitcnt lgkmcnt(0)
	s_barrier
	v_add_u32_e32 v232, s98, v230
	v_add_u32_e32 v233, s98, v231
	s_add_u32 s11, s19, s101
	s_setprio 1
	v_mfma_f32_16x16x32_bf16 v[0:3], v[128:131], v[144:147], v[0:3]
	v_mfma_f32_16x16x32_bf16 v[4:7], v[132:135], v[144:147], v[4:7]
	v_mfma_f32_16x16x32_bf16 v[8:11], v[136:139], v[144:147], v[8:11]
	v_mfma_f32_16x16x32_bf16 v[12:15], v[140:143], v[144:147], v[12:15]
	ds_read_b128 v[176:179], v233 offset:0
	ds_read_b128 v[180:183], v233 offset:1024
	s_add_u32 m0, s11, 0
	s_nop 0
	global_load_lds_dwordx4 v224, s[0:1]
	v_mfma_f32_16x16x32_bf16 v[16:19], v[128:131], v[148:151], v[16:19]
	v_mfma_f32_16x16x32_bf16 v[20:23], v[132:135], v[148:151], v[20:23]
	v_mfma_f32_16x16x32_bf16 v[24:27], v[136:139], v[148:151], v[24:27]
	v_mfma_f32_16x16x32_bf16 v[28:31], v[140:143], v[148:151], v[28:31]
	ds_read_b128 v[184:187], v233 offset:2048
	ds_read_b128 v[188:191], v233 offset:3072
	s_add_u32 m0, s11, 4096
	s_nop 0
	global_load_lds_dwordx4 v225, s[0:1]
	v_mfma_f32_16x16x32_bf16 v[32:35], v[128:131], v[152:155], v[32:35]
	v_mfma_f32_16x16x32_bf16 v[36:39], v[132:135], v[152:155], v[36:39]
	v_mfma_f32_16x16x32_bf16 v[40:43], v[136:139], v[152:155], v[40:43]
	v_mfma_f32_16x16x32_bf16 v[44:47], v[140:143], v[152:155], v[44:47]
	ds_read_b128 v[192:195], v232 offset:0
	ds_read_b128 v[196:199], v232 offset:1024
	s_add_u32 m0, s11, 8192
	s_nop 0
	global_load_lds_dwordx4 v226, s[0:1]
	v_mfma_f32_16x16x32_bf16 v[48:51], v[128:131], v[156:159], v[48:51]
	v_mfma_f32_16x16x32_bf16 v[52:55], v[132:135], v[156:159], v[52:55]
	v_mfma_f32_16x16x32_bf16 v[56:59], v[136:139], v[156:159], v[56:59]
	v_mfma_f32_16x16x32_bf16 v[60:63], v[140:143], v[156:159], v[60:63]
	ds_read_b128 v[200:203], v232 offset:2048
	ds_read_b128 v[204:207], v232 offset:3072
	s_add_u32 m0, s11, 12288
	s_nop 0
	global_load_lds_dwordx4 v227, s[0:1]
	v_mfma_f32_16x16x32_bf16 v[64:67], v[128:131], v[160:163], v[64:67]
	v_mfma_f32_16x16x32_bf16 v[68:71], v[132:135], v[160:163], v[68:71]
	v_mfma_f32_16x16x32_bf16 v[72:75], v[136:139], v[160:163], v[72:75]
	v_mfma_f32_16x16x32_bf16 v[76:79], v[140:143], v[160:163], v[76:79]
	ds_read_b128 v[208:211], v232 offset:4096
	s_add_u32 m0, s11, 16384
	s_nop 0
	global_load_lds_dwordx4 v228, s[2:3]
	v_mfma_f32_16x16x32_bf16 v[80:83], v[128:131], v[164:167], v[80:83]
	v_mfma_f32_16x16x32_bf16 v[84:87], v[132:135], v[164:167], v[84:87]
	v_mfma_f32_16x16x32_bf16 v[88:91], v[136:139], v[164:167], v[88:91]
	v_mfma_f32_16x16x32_bf16 v[92:95], v[140:143], v[164:167], v[92:95]
	ds_read_b128 v[212:215], v232 offset:5120
	s_add_u32 m0, s11, 20480
	s_nop 0
	global_load_lds_dwordx4 v229, s[2:3]
	v_mfma_f32_16x16x32_bf16 v[96:99], v[128:131], v[168:171], v[96:99]
	v_mfma_f32_16x16x32_bf16 v[100:103], v[132:135], v[168:171], v[100:103]
	v_mfma_f32_16x16x32_bf16 v[104:107], v[136:139], v[168:171], v[104:107]
	v_mfma_f32_16x16x32_bf16 v[108:111], v[140:143], v[168:171], v[108:111]
	ds_read_b128 v[216:219], v232 offset:6144
	s_cmp_eq_u32 s10, 0
	s_cbranch_scc0 .Lg8_hi0
	s_setprio 0
.Lg8_hi0:
	s_add_u32 s0, s0, 64
	s_addc_u32 s1, s1, 0
	s_add_u32 s2, s2, 64
	s_addc_u32 s3, s3, 0
	s_add_u32 s100, s100, 1
	s_add_u32 s19, s19, 24576
	s_cmp_eq_u32 s19, 73728
	s_cselect_b32 s19, 0, s19
	s_add_u32 s98, s98, 24576
	s_cmp_eq_u32 s98, 73728
	s_cselect_b32 s98, 0, s98
	v_mfma_f32_16x16x32_bf16 v[112:115], v[128:131], v[172:175], v[112:115]
	v_mfma_f32_16x16x32_bf16 v[116:119], v[132:135], v[172:175], v[116:119]
	v_mfma_f32_16x16x32_bf16 v[120:123], v[136:139], v[172:175], v[120:123]
	v_mfma_f32_16x16x32_bf16 v[124:127], v[140:143], v[172:175], v[124:127]
	ds_read_b128 v[220:223], v232 offset:7168
	s_waitcnt vmcnt(6)
	s_waitcnt lgkmcnt(0)
	s_barrier
	v_add_u32_e32 v232, s98, v230
	v_add_u32_e32 v233, s98, v231
	s_add_u32 s11, s19, s101
	s_setprio 1
	v_mfma_f32_16x16x32_bf16 v[0:3], v[176:179], v[192:195], v[0:3]
	v_mfma_f32_16x16x32_bf16 v[4:7], v[180:183], v[192:195], v[4:7]
	v_mfma_f32_16x16x32_bf16 v[8:11], v[184:187], v[192:195], v[8:11]
	v_mfma_f32_16x16x32_bf16 v[12:15], v[188:191], v[192:195], v[12:15]
	ds_read_b128 v[128:131], v233 offset:0
	ds_read_b128 v[132:135], v233 offset:1024
	s_add_u32 m0, s11, 0
	s_nop 0
	global_load_lds_dwordx4 v224, s[0:1]
	v_mfma_f32_16x16x32_bf16 v[16:19], v[176:179], v[196:199], v[16:19]
	v_mfma_f32_16x16x32_bf16 v[20:23], v[180:183], v[196:199], v[20:23]
	v_mfma_f32_16x16x32_bf16 v[24:27], v[184:187], v[196:199], v[24:27]
	v_mfma_f32_16x16x32_bf16 v[28:31], v[188:191], v[196:199], v[28:31]
	ds_read_b128 v[136:139], v233 offset:2048
	ds_read_b128 v[140:143], v233 offset:3072
	s_add_u32 m0, s11, 4096
	s_nop 0
	global_load_lds_dwordx4 v225, s[0:1]
	v_mfma_f32_16x16x32_bf16 v[32:35], v[176:179], v[200:203], v[32:35]
	v_mfma_f32_16x16x32_bf16 v[36:39], v[180:183], v[200:203], v[36:39]
	v_mfma_f32_16x16x32_bf16 v[40:43], v[184:187], v[200:203], v[40:43]
	v_mfma_f32_16x16x32_bf16 v[44:47], v[188:191], v[200:203], v[44:47]
	ds_read_b128 v[144:147], v232 offset:0
	ds_read_b128 v[148:151], v232 offset:1024
	s_add_u32 m0, s11, 8192
	s_nop 0
	global_load_lds_dwordx4 v226, s[0:1]
	v_mfma_f32_16x16x32_bf16 v[48:51], v[176:179], v[204:207], v[48:51]
	v_mfma_f32_16x16x32_bf16 v[52:55], v[180:183], v[204:207], v[52:55]
	v_mfma_f32_16x16x32_bf16 v[56:59], v[184:187], v[204:207], v[56:59]
	v_mfma_f32_16x16x32_bf16 v[60:63], v[188:191], v[204:207], v[60:63]
	ds_read_b128 v[152:155], v232 offset:2048
	ds_read_b128 v[156:159], v232 offset:3072
	s_add_u32 m0, s11, 12288
	s_nop 0
	global_load_lds_dwordx4 v227, s[0:1]
	v_mfma_f32_16x16x32_bf16 v[64:67], v[176:179], v[208:211], v[64:67]
	v_mfma_f32_16x16x32_bf16 v[68:71], v[180:183], v[208:211], v[68:71]
	v_mfma_f32_16x16x32_bf16 v[72:75], v[184:187], v[208:211], v[72:75]
	v_mfma_f32_16x16x32_bf16 v[76:79], v[188:191], v[208:211], v[76:79]
	ds_read_b128 v[160:163], v232 offset:4096
	s_add_u32 m0, s11, 16384
	s_nop 0
	global_load_lds_dwordx4 v228, s[2:3]
	v_mfma_f32_16x16x32_bf16 v[80:83], v[176:179], v[212:215], v[80:83]
	v_mfma_f32_16x16x32_bf16 v[84:87], v[180:183], v[212:215], v[84:87]
	v_mfma_f32_16x16x32_bf16 v[88:91], v[184:187], v[212:215], v[88:91]
	v_mfma_f32_16x16x32_bf16 v[92:95], v[188:191], v[212:215], v[92:95]
	ds_read_b128 v[164:167], v232 offset:5120
	s_add_u32 m0, s11, 20480
	s_nop 0
	global_load_lds_dwordx4 v229, s[2:3]
	v_mfma_f32_16x16x32_bf16 v[96:99], v[176:179], v[216:219], v[96:99]
	v_mfma_f32_16x16x32_bf16 v[100:103], v[180:183], v[216:219], v[100:103]
	v_mfma_f32_16x16x32_bf16 v[104:107], v[184:187], v[216:219], v[104:107]
	v_mfma_f32_16x16x32_bf16 v[108:111], v[188:191], v[216:219], v[108:111]
	ds_read_b128 v[168:171], v232 offset:6144
	s_cmp_eq_u32 s10, 0
	s_cbranch_scc0 .Lg8_hi1
	s_setprio 0
; #define LWRITE(S, buf) do { bf16_t* sA_ = sbase + (buf) * BUF; bf16_t* sB_ = sA_ + 256 * PITCH; \
;     _Pragma("unroll") for (int i_ = 0; i_ < 4; ++i_) *(u32x4*)(sA_ + (sr + i_ * 64) * PITCH + scv * 8) = ra[S][i_]; \
;     _Pragma("unroll") for (int i_ = 0; i_ < 2; ++i_) *(u32x4*)(sB_ + (sr + i_ * 64) * PITCH + scv * 8) = rb[S][i_]; } while (0)
; template <class Epi>
; DI void gemm_tile(char* smem, const bf16_t* __restrict__ A0, int lda0, int ksplit, const bf16_t* __restrict__ A1, int lda1,
;                   const bf16_t* __restrict__ Bt, int K, int row0, int col0, const Epi& epi, int tid) {
;     ...
;     for (int kt = 0; kt < nk; kt += 2) {
;       LWRITE(1, 1);
;       __builtin_amdgcn_sched_barrier(0);
;       GLOAD(1, (kt + 3 < last ? kt + 3 : last));
;       __builtin_amdgcn_sched_barrier(0);
;       COMPUTE(0);
;       __syncthreads();
;       LWRITE(0, 0);
;       __builtin_amdgcn_sched_barrier(0);
;       GLOAD(0, (kt + 4 < last ? kt + 4 : last));
;       __builtin_amdgcn_sched_barrier(0);
;       COMPUTE(1);
;       __syncthreads();
;     }
.Lg8_hi1:
	s_add_u32 s0, s0, 64
	s_addc_u32 s1, s1, 0
	s_add_u32 s2, s2, 64
	s_addc_u32 s3, s3, 0
	s_add_u32 s100, s100, 1
	s_add_u32 s19, s19, 24576
	s_cmp_eq_u32 s19, 73728
	s_cselect_b32 s19, 0, s19
	s_add_u32 s98, s98, 24576
	s_cmp_eq_u32 s98, 73728
	s_cselect_b32 s98, 0, s98
	v_mfma_f32_16x16x32_bf16 v[112:115], v[176:179], v[220:223], v[112:115]
	v_mfma_f32_16x16x32_bf16 v[116:119], v[180:183], v[220:223], v[116:119]
	v_mfma_f32_16x16x32_bf16 v[120:123], v[184:187], v[220:223], v[120:123]
	v_mfma_f32_16x16x32_bf16 v[124:127], v[188:191], v[220:223], v[124:127]
	ds_read_b128 v[172:175], v232 offset:7168
	s_add_u32 s99, s99, 2
	s_cmp_lt_u32 s99, 28
	s_cbranch_scc1 .Lg8_kloop
	s_waitcnt vmcnt(6)
	s_waitcnt lgkmcnt(0)
	s_barrier
	v_add_u32_e32 v232, s98, v230
	v_add_u32_e32 v233, s98, v231
	s_add_u32 s11, s19, s101
	s_setprio 1
	v_mfma_f32_16x16x32_bf16 v[0:3], v[128:131], v[144:147], v[0:3]
	v_mfma_f32_16x16x32_bf16 v[4:7], v[132:135], v[144:147], v[4:7]
	v_mfma_f32_16x16x32_bf16 v[8:11], v[136:139], v[144:147], v[8:11]
	v_mfma_f32_16x16x32_bf16 v[12:15], v[140:143], v[144:147], v[12:15]
	ds_read_b128 v[176:179], v233 offset:0
	ds_read_b128 v[180:183], v233 offset:1024
	s_add_u32 m0, s11, 0
	s_nop 0
	global_load_lds_dwordx4 v224, s[0:1]
	v_mfma_f32_16x16x32_bf16 v[16:19], v[128:131], v[148:151], v[16:19]
	v_mfma_f32_16x16x32_bf16 v[20:23], v[132:135], v[148:151], v[20:23]
	v_mfma_f32_16x16x32_bf16 v[24:27], v[136:139], v[148:151], v[24:27]
	v_mfma_f32_16x16x32_bf16 v[28:31], v[140:143], v[148:151], v[28:31]
	ds_read_b128 v[184:187], v233 offset:2048
	ds_read_b128 v[188:191], v233 offset:3072
	s_add_u32 m0, s11, 4096
	s_nop 0
	global_load_lds_dwordx4 v225, s[0:1]
	v_mfma_f32_16x16x32_bf16 v[32:35], v[128:131], v[152:155], v[32:35]
	v_mfma_f32_16x16x32_bf16 v[36:39], v[132:135], v[152:155], v[36:39]
	v_mfma_f32_16x16x32_bf16 v[40:43], v[136:139], v[152:155], v[40:43]
	v_mfma_f32_16x16x32_bf16 v[44:47], v[140:143], v[152:155], v[44:47]
	ds_read_b128 v[192:195], v232 offset:0
	ds_read_b128 v[196:199], v232 offset:1024
	s_add_u32 m0, s11, 8192
	s_nop 0
	global_load_lds_dwordx4 v226, s[0:1]
	v_mfma_f32_16x16x32_bf16 v[48:51], v[128:131], v[156:159], v[48:51]
	v_mfma_f32_16x16x32_bf16 v[52:55], v[132:135], v[156:159], v[52:55]
	v_mfma_f32_16x16x32_bf16 v[56:59], v[136:139], v[156:159], v[56:59]
	v_mfma_f32_16x16x32_bf16 v[60:63], v[140:143], v[156:159], v[60:63]
	ds_read_b128 v[200:203], v232 offset:2048
	ds_read_b128 v[204:207], v232 offset:3072
	s_add_u32 m0, s11, 12288
	s_nop 0
	global_load_lds_dwordx4 v227, s[0:1]
	v_mfma_f32_16x16x32_bf16 v[64:67], v[128:131], v[160:163], v[64:67]
	v_mfma_f32_16x16x32_bf16 v[68:71], v[132:135], v[160:163], v[68:71]
	v_mfma_f32_16x16x32_bf16 v[72:75], v[136:139], v[160:163], v[72:75]
	v_mfma_f32_16x16x32_bf16 v[76:79], v[140:143], v[160:163], v[76:79]
	ds_read_b128 v[208:211], v232 offset:4096
	s_add_u32 m0, s11, 16384
	s_nop 0
	global_load_lds_dwordx4 v228, s[2:3]
	v_mfma_f32_16x16x32_bf16 v[80:83], v[128:131], v[164:167], v[80:83]
	v_mfma_f32_16x16x32_bf16 v[84:87], v[132:135], v[164:167], v[84:87]
	v_mfma_f32_16x16x32_bf16 v[88:91], v[136:139], v[164:167], v[88:91]
	v_mfma_f32_16x16x32_bf16 v[92:95], v[140:143], v[164:167], v[92:95]
	ds_read_b128 v[212:215], v232 offset:5120
	s_add_u32 m0, s11, 20480
	s_nop 0
	global_load_lds_dwordx4 v229, s[2:3]
	v_mfma_f32_16x16x32_bf16 v[96:99], v[128:131], v[168:171], v[96:99]
	v_mfma_f32_16x16x32_bf16 v[100:103], v[132:135], v[168:171], v[100:103]
	v_mfma_f32_16x16x32_bf16 v[104:107], v[136:139], v[168:171], v[104:107]
	v_mfma_f32_16x16x32_bf16 v[108:111], v[140:143], v[168:171], v[108:111]
	ds_read_b128 v[216:219], v232 offset:6144
	s_cmp_eq_u32 s10, 0
	s_cbranch_scc0 .Lg8_hi2
	s_setprio 0
.Lg8_hi2:
	s_add_u32 s0, s0, 64
	s_addc_u32 s1, s1, 0
	s_add_u32 s2, s2, 64
	s_addc_u32 s3, s3, 0
	s_add_u32 s100, s100, 1
	s_add_u32 s19, s19, 24576
	s_cmp_eq_u32 s19, 73728
	s_cselect_b32 s19, 0, s19
	s_add_u32 s98, s98, 24576
	s_cmp_eq_u32 s98, 73728
	s_cselect_b32 s98, 0, s98
	v_mfma_f32_16x16x32_bf16 v[112:115], v[128:131], v[172:175], v[112:115]
	v_mfma_f32_16x16x32_bf16 v[116:119], v[132:135], v[172:175], v[116:119]
	v_mfma_f32_16x16x32_bf16 v[120:123], v[136:139], v[172:175], v[120:123]
	v_mfma_f32_16x16x32_bf16 v[124:127], v[140:143], v[172:175], v[124:127]
	ds_read_b128 v[220:223], v232 offset:7168
	s_waitcnt vmcnt(6)
	s_waitcnt lgkmcnt(0)
	s_barrier
	v_add_u32_e32 v232, s98, v230
	v_add_u32_e32 v233, s98, v231
	s_setprio 1
	v_mfma_f32_16x16x32_bf16 v[0:3], v[176:179], v[192:195], v[0:3]
	v_mfma_f32_16x16x32_bf16 v[4:7], v[180:183], v[192:195], v[4:7]
	v_mfma_f32_16x16x32_bf16 v[8:11], v[184:187], v[192:195], v[8:11]
	v_mfma_f32_16x16x32_bf16 v[12:15], v[188:191], v[192:195], v[12:15]
	ds_read_b128 v[128:131], v233 offset:0
	ds_read_b128 v[132:135], v233 offset:1024
	v_mfma_f32_16x16x32_bf16 v[16:19], v[176:179], v[196:199], v[16:19]
	v_mfma_f32_16x16x32_bf16 v[20:23], v[180:183], v[196:199], v[20:23]
	v_mfma_f32_16x16x32_bf16 v[24:27], v[184:187], v[196:199], v[24:27]
	v_mfma_f32_16x16x32_bf16 v[28:31], v[188:191], v[196:199], v[28:31]
	ds_read_b128 v[136:139], v233 offset:2048
	ds_read_b128 v[140:143], v233 offset:3072
	v_mfma_f32_16x16x32_bf16 v[32:35], v[176:179], v[200:203], v[32:35]
	v_mfma_f32_16x16x32_bf16 v[36:39], v[180:183], v[200:203], v[36:39]
	v_mfma_f32_16x16x32_bf16 v[40:43], v[184:187], v[200:203], v[40:43]
	v_mfma_f32_16x16x32_bf16 v[44:47], v[188:191], v[200:203], v[44:47]
	ds_read_b128 v[144:147], v232 offset:0
	ds_read_b128 v[148:151], v232 offset:1024
	v_mfma_f32_16x16x32_bf16 v[48:51], v[176:179], v[204:207], v[48:51]
	v_mfma_f32_16x16x32_bf16 v[52:55], v[180:183], v[204:207], v[52:55]
	v_mfma_f32_16x16x32_bf16 v[56:59], v[184:187], v[204:207], v[56:59]
	v_mfma_f32_16x16x32_bf16 v[60:63], v[188:191], v[204:207], v[60:63]
	ds_read_b128 v[152:155], v232 offset:2048
	ds_read_b128 v[156:159], v232 offset:3072
	v_mfma_f32_16x16x32_bf16 v[64:67], v[176:179], v[208:211], v[64:67]
	v_mfma_f32_16x16x32_bf16 v[68:71], v[180:183], v[208:211], v[68:71]
	v_mfma_f32_16x16x32_bf16 v[72:75], v[184:187], v[208:211], v[72:75]
	v_mfma_f32_16x16x32_bf16 v[76:79], v[188:191], v[208:211], v[76:79]
	ds_read_b128 v[160:163], v232 offset:4096
	v_mfma_f32_16x16x32_bf16 v[80:83], v[176:179], v[212:215], v[80:83]
	v_mfma_f32_16x16x32_bf16 v[84:87], v[180:183], v[212:215], v[84:87]
	v_mfma_f32_16x16x32_bf16 v[88:91], v[184:187], v[212:215], v[88:91]
	v_mfma_f32_16x16x32_bf16 v[92:95], v[188:191], v[212:215], v[92:95]
	ds_read_b128 v[164:167], v232 offset:5120
	v_mfma_f32_16x16x32_bf16 v[96:99], v[176:179], v[216:219], v[96:99]
	v_mfma_f32_16x16x32_bf16 v[100:103], v[180:183], v[216:219], v[100:103]
	v_mfma_f32_16x16x32_bf16 v[104:107], v[184:187], v[216:219], v[104:107]
	v_mfma_f32_16x16x32_bf16 v[108:111], v[188:191], v[216:219], v[108:111]
	ds_read_b128 v[168:171], v232 offset:6144
	s_cmp_eq_u32 s10, 0
	s_cbranch_scc0 .Lg8_hi3
	s_setprio 0
.Lg8_hi3:
	s_add_u32 s98, s98, 24576
	s_cmp_eq_u32 s98, 73728
	s_cselect_b32 s98, 0, s98
	v_mfma_f32_16x16x32_bf16 v[112:115], v[176:179], v[220:223], v[112:115]
	v_mfma_f32_16x16x32_bf16 v[116:119], v[180:183], v[220:223], v[116:119]
	v_mfma_f32_16x16x32_bf16 v[120:123], v[184:187], v[220:223], v[120:123]
	v_mfma_f32_16x16x32_bf16 v[124:127], v[188:191], v[220:223], v[124:127]
	ds_read_b128 v[172:175], v232 offset:7168
	s_waitcnt vmcnt(0)
	s_waitcnt lgkmcnt(0)
	s_barrier
	v_add_u32_e32 v232, s98, v230
	v_add_u32_e32 v233, s98, v231
	s_setprio 1
	v_mfma_f32_16x16x32_bf16 v[0:3], v[128:131], v[144:147], v[0:3]
	v_mfma_f32_16x16x32_bf16 v[4:7], v[132:135], v[144:147], v[4:7]
	v_mfma_f32_16x16x32_bf16 v[8:11], v[136:139], v[144:147], v[8:11]
	v_mfma_f32_16x16x32_bf16 v[12:15], v[140:143], v[144:147], v[12:15]
	ds_read_b128 v[176:179], v233 offset:0
	ds_read_b128 v[180:183], v233 offset:1024
	v_mfma_f32_16x16x32_bf16 v[16:19], v[128:131], v[148:151], v[16:19]
	v_mfma_f32_16x16x32_bf16 v[20:23], v[132:135], v[148:151], v[20:23]
	v_mfma_f32_16x16x32_bf16 v[24:27], v[136:139], v[148:151], v[24:27]
	v_mfma_f32_16x16x32_bf16 v[28:31], v[140:143], v[148:151], v[28:31]
	ds_read_b128 v[184:187], v233 offset:2048
	ds_read_b128 v[188:191], v233 offset:3072
	v_mfma_f32_16x16x32_bf16 v[32:35], v[128:131], v[152:155], v[32:35]
	v_mfma_f32_16x16x32_bf16 v[36:39], v[132:135], v[152:155], v[36:39]
	v_mfma_f32_16x16x32_bf16 v[40:43], v[136:139], v[152:155], v[40:43]
	v_mfma_f32_16x16x32_bf16 v[44:47], v[140:143], v[152:155], v[44:47]
	ds_read_b128 v[192:195], v232 offset:0
	ds_read_b128 v[196:199], v232 offset:1024
	v_mfma_f32_16x16x32_bf16 v[48:51], v[128:131], v[156:159], v[48:51]
	v_mfma_f32_16x16x32_bf16 v[52:55], v[132:135], v[156:159], v[52:55]
	v_mfma_f32_16x16x32_bf16 v[56:59], v[136:139], v[156:159], v[56:59]
	v_mfma_f32_16x16x32_bf16 v[60:63], v[140:143], v[156:159], v[60:63]
	ds_read_b128 v[200:203], v232 offset:2048
	ds_read_b128 v[204:207], v232 offset:3072
	v_mfma_f32_16x16x32_bf16 v[64:67], v[128:131], v[160:163], v[64:67]
	v_mfma_f32_16x16x32_bf16 v[68:71], v[132:135], v[160:163], v[68:71]
	v_mfma_f32_16x16x32_bf16 v[72:75], v[136:139], v[160:163], v[72:75]
	v_mfma_f32_16x16x32_bf16 v[76:79], v[140:143], v[160:163], v[76:79]
	ds_read_b128 v[208:211], v232 offset:4096
	v_mfma_f32_16x16x32_bf16 v[80:83], v[128:131], v[164:167], v[80:83]
	v_mfma_f32_16x16x32_bf16 v[84:87], v[132:135], v[164:167], v[84:87]
	v_mfma_f32_16x16x32_bf16 v[88:91], v[136:139], v[164:167], v[88:91]
	v_mfma_f32_16x16x32_bf16 v[92:95], v[140:143], v[164:167], v[92:95]
	ds_read_b128 v[212:215], v232 offset:5120
	v_mfma_f32_16x16x32_bf16 v[96:99], v[128:131], v[168:171], v[96:99]
	v_mfma_f32_16x16x32_bf16 v[100:103], v[132:135], v[168:171], v[100:103]
	v_mfma_f32_16x16x32_bf16 v[104:107], v[136:139], v[168:171], v[104:107]
	v_mfma_f32_16x16x32_bf16 v[108:111], v[140:143], v[168:171], v[108:111]
	ds_read_b128 v[216:219], v232 offset:6144
	s_cmp_eq_u32 s10, 0
	s_cbranch_scc0 .Lg8_hi4
	s_setprio 0
.Lg8_hi4:
	s_add_u32 s98, s98, 24576
	s_cmp_eq_u32 s98, 73728
	s_cselect_b32 s98, 0, s98
	v_mfma_f32_16x16x32_bf16 v[112:115], v[128:131], v[172:175], v[112:115]
	v_mfma_f32_16x16x32_bf16 v[116:119], v[132:135], v[172:175], v[116:119]
	v_mfma_f32_16x16x32_bf16 v[120:123], v[136:139], v[172:175], v[120:123]
	v_mfma_f32_16x16x32_bf16 v[124:127], v[140:143], v[172:175], v[124:127]
	ds_read_b128 v[220:223], v232 offset:7168
	s_waitcnt lgkmcnt(0)
	s_barrier
	s_setprio 1
	v_mfma_f32_16x16x32_bf16 v[0:3], v[176:179], v[192:195], v[0:3]
	v_mfma_f32_16x16x32_bf16 v[4:7], v[180:183], v[192:195], v[4:7]
	v_mfma_f32_16x16x32_bf16 v[8:11], v[184:187], v[192:195], v[8:11]
	v_mfma_f32_16x16x32_bf16 v[12:15], v[188:191], v[192:195], v[12:15]
	v_mfma_f32_16x16x32_bf16 v[16:19], v[176:179], v[196:199], v[16:19]
	v_mfma_f32_16x16x32_bf16 v[20:23], v[180:183], v[196:199], v[20:23]
	v_mfma_f32_16x16x32_bf16 v[24:27], v[184:187], v[196:199], v[24:27]
	v_mfma_f32_16x16x32_bf16 v[28:31], v[188:191], v[196:199], v[28:31]
	v_mfma_f32_16x16x32_bf16 v[32:35], v[176:179], v[200:203], v[32:35]
	v_mfma_f32_16x16x32_bf16 v[36:39], v[180:183], v[200:203], v[36:39]
	v_mfma_f32_16x16x32_bf16 v[40:43], v[184:187], v[200:203], v[40:43]
	v_mfma_f32_16x16x32_bf16 v[44:47], v[188:191], v[200:203], v[44:47]
	v_mfma_f32_16x16x32_bf16 v[48:51], v[176:179], v[204:207], v[48:51]
	v_mfma_f32_16x16x32_bf16 v[52:55], v[180:183], v[204:207], v[52:55]
	v_mfma_f32_16x16x32_bf16 v[56:59], v[184:187], v[204:207], v[56:59]
	v_mfma_f32_16x16x32_bf16 v[60:63], v[188:191], v[204:207], v[60:63]
	v_mfma_f32_16x16x32_bf16 v[64:67], v[176:179], v[208:211], v[64:67]
	v_mfma_f32_16x16x32_bf16 v[68:71], v[180:183], v[208:211], v[68:71]
	v_mfma_f32_16x16x32_bf16 v[72:75], v[184:187], v[208:211], v[72:75]
	v_mfma_f32_16x16x32_bf16 v[76:79], v[188:191], v[208:211], v[76:79]
	v_mfma_f32_16x16x32_bf16 v[80:83], v[176:179], v[212:215], v[80:83]
	v_mfma_f32_16x16x32_bf16 v[84:87], v[180:183], v[212:215], v[84:87]
	v_mfma_f32_16x16x32_bf16 v[88:91], v[184:187], v[212:215], v[88:91]
	v_mfma_f32_16x16x32_bf16 v[92:95], v[188:191], v[212:215], v[92:95]
	v_mfma_f32_16x16x32_bf16 v[96:99], v[176:179], v[216:219], v[96:99]
	v_mfma_f32_16x16x32_bf16 v[100:103], v[180:183], v[216:219], v[100:103]
	v_mfma_f32_16x16x32_bf16 v[104:107], v[184:187], v[216:219], v[104:107]
	v_mfma_f32_16x16x32_bf16 v[108:111], v[188:191], v[216:219], v[108:111]
	s_cmp_eq_u32 s10, 0
	s_cbranch_scc0 .Lg8_hi5
	s_setprio 0

; #define LWRITE(S, buf) do { bf16_t* sA_ = sbase + (buf) * BUF; bf16_t* sB_ = sA_ + 256 * PITCH; \
;     _Pragma("unroll") for (int i_ = 0; i_ < 4; ++i_) *(u32x4*)(sA_ + (sr + i_ * 64) * PITCH + scv * 8) = ra[S][i_]; \
;     _Pragma("unroll") for (int i_ = 0; i_ < 2; ++i_) *(u32x4*)(sB_ + (sr + i_ * 64) * PITCH + scv * 8) = rb[S][i_]; } while (0)
; template <class Epi>
; DI void gemm_tile(char* smem, const bf16_t* __restrict__ A0, int lda0, int ksplit, const bf16_t* __restrict__ A1, int lda1,
;                   const bf16_t* __restrict__ Bt, int K, int row0, int col0, const Epi& epi, int tid) {
;     ...
;     for (int kt = 0; kt < nk; kt += 2) {
;       LWRITE(1, 1);
;       __builtin_amdgcn_sched_barrier(0);
;       GLOAD(1, (kt + 3 < last ? kt + 3 : last));
;       __builtin_amdgcn_sched_barrier(0);
;       COMPUTE(0);
;       __syncthreads();
;       LWRITE(0, 0);
;       __builtin_amdgcn_sched_barrier(0);
;       GLOAD(0, (kt + 4 < last ? kt + 4 : last));
;       __builtin_amdgcn_sched_barrier(0);
;       COMPUTE(1);
;       __syncthreads();
;     }
.Lg9_kloop:
	s_waitcnt vmcnt(6)
	s_waitcnt lgkmcnt(0)
	s_barrier
	v_add_u32_e32 v232, s98, v230
	v_add_u32_e32 v233, s98, v231
	s_add_u32 s9, s17, s101
	s_setprio 1
	v_mfma_f32_16x16x32_bf16 v[0:3], v[128:131], v[144:147], v[0:3]
	v_mfma_f32_16x16x32_bf16 v[4:7], v[132:135], v[144:147], v[4:7]
	v_mfma_f32_16x16x32_bf16 v[8:11], v[136:139], v[144:147], v[8:11]
	v_mfma_f32_16x16x32_bf16 v[12:15], v[140:143], v[144:147], v[12:15]
	ds_read_b128 v[176:179], v233 offset:0
	ds_read_b128 v[180:183], v233 offset:1024
	s_add_u32 m0, s9, 0
	s_nop 0
	global_load_lds_dwordx4 v224, s[0:1]
	v_mfma_f32_16x16x32_bf16 v[16:19], v[128:131], v[148:151], v[16:19]
	v_mfma_f32_16x16x32_bf16 v[20:23], v[132:135], v[148:151], v[20:23]
	v_mfma_f32_16x16x32_bf16 v[24:27], v[136:139], v[148:151], v[24:27]
	v_mfma_f32_16x16x32_bf16 v[28:31], v[140:143], v[148:151], v[28:31]
	ds_read_b128 v[184:187], v233 offset:2048
	ds_read_b128 v[188:191], v233 offset:3072
	s_add_u32 m0, s9, 4096
	s_nop 0
	global_load_lds_dwordx4 v225, s[0:1]
	v_mfma_f32_16x16x32_bf16 v[32:35], v[128:131], v[152:155], v[32:35]
	v_mfma_f32_16x16x32_bf16 v[36:39], v[132:135], v[152:155], v[36:39]
	v_mfma_f32_16x16x32_bf16 v[40:43], v[136:139], v[152:155], v[40:43]
	v_mfma_f32_16x16x32_bf16 v[44:47], v[140:143], v[152:155], v[44:47]
	ds_read_b128 v[192:195], v232 offset:0
	ds_read_b128 v[196:199], v232 offset:1024
	s_add_u32 m0, s9, 8192
	s_nop 0
	global_load_lds_dwordx4 v226, s[0:1]
	v_mfma_f32_16x16x32_bf16 v[48:51], v[128:131], v[156:159], v[48:51]
	v_mfma_f32_16x16x32_bf16 v[52:55], v[132:135], v[156:159], v[52:55]
	v_mfma_f32_16x16x32_bf16 v[56:59], v[136:139], v[156:159], v[56:59]
	v_mfma_f32_16x16x32_bf16 v[60:63], v[140:143], v[156:159], v[60:63]
	ds_read_b128 v[200:203], v232 offset:2048
	ds_read_b128 v[204:207], v232 offset:3072
	s_add_u32 m0, s9, 12288
	s_nop 0
	global_load_lds_dwordx4 v227, s[0:1]
	v_mfma_f32_16x16x32_bf16 v[64:67], v[128:131], v[160:163], v[64:67]
	v_mfma_f32_16x16x32_bf16 v[68:71], v[132:135], v[160:163], v[68:71]
	v_mfma_f32_16x16x32_bf16 v[72:75], v[136:139], v[160:163], v[72:75]
	v_mfma_f32_16x16x32_bf16 v[76:79], v[140:143], v[160:163], v[76:79]
	ds_read_b128 v[208:211], v232 offset:4096
	s_add_u32 m0, s9, 16384
	s_nop 0
	global_load_lds_dwordx4 v228, s[2:3]
	v_mfma_f32_16x16x32_bf16 v[80:83], v[128:131], v[164:167], v[80:83]
	v_mfma_f32_16x16x32_bf16 v[84:87], v[132:135], v[164:167], v[84:87]
	v_mfma_f32_16x16x32_bf16 v[88:91], v[136:139], v[164:167], v[88:91]
	v_mfma_f32_16x16x32_bf16 v[92:95], v[140:143], v[164:167], v[92:95]
	ds_read_b128 v[212:215], v232 offset:5120
	s_add_u32 m0, s9, 20480
	s_nop 0
	global_load_lds_dwordx4 v229, s[2:3]
	v_mfma_f32_16x16x32_bf16 v[96:99], v[128:131], v[168:171], v[96:99]
	v_mfma_f32_16x16x32_bf16 v[100:103], v[132:135], v[168:171], v[100:103]
	v_mfma_f32_16x16x32_bf16 v[104:107], v[136:139], v[168:171], v[104:107]
	v_mfma_f32_16x16x32_bf16 v[108:111], v[140:143], v[168:171], v[108:111]
	ds_read_b128 v[216:219], v232 offset:6144
	s_cmp_eq_u32 s8, 0
	s_cbranch_scc0 .Lg9_hi0
	s_setprio 0
.Lg9_hi0:
	s_add_u32 s0, s0, 64
	s_addc_u32 s1, s1, 0
	s_add_u32 s2, s2, 64
	s_addc_u32 s3, s3, 0
	s_add_u32 s100, s100, 1
	s_add_u32 s17, s17, 24576
	s_cmp_eq_u32 s17, 73728
	s_cselect_b32 s17, 0, s17
	s_add_u32 s98, s98, 24576
	s_cmp_eq_u32 s98, 73728
	s_cselect_b32 s98, 0, s98
	v_mfma_f32_16x16x32_bf16 v[112:115], v[128:131], v[172:175], v[112:115]
	v_mfma_f32_16x16x32_bf16 v[116:119], v[132:135], v[172:175], v[116:119]
	v_mfma_f32_16x16x32_bf16 v[120:123], v[136:139], v[172:175], v[120:123]
	v_mfma_f32_16x16x32_bf16 v[124:127], v[140:143], v[172:175], v[124:127]
	ds_read_b128 v[220:223], v232 offset:7168
	s_waitcnt vmcnt(6)
	s_waitcnt lgkmcnt(0)
	s_barrier
	v_add_u32_e32 v232, s98, v230
	v_add_u32_e32 v233, s98, v231
	s_add_u32 s9, s17, s101
	s_setprio 1
	v_mfma_f32_16x16x32_bf16 v[0:3], v[176:179], v[192:195], v[0:3]
	v_mfma_f32_16x16x32_bf16 v[4:7], v[180:183], v[192:195], v[4:7]
	v_mfma_f32_16x16x32_bf16 v[8:11], v[184:187], v[192:195], v[8:11]
	v_mfma_f32_16x16x32_bf16 v[12:15], v[188:191], v[192:195], v[12:15]
	ds_read_b128 v[128:131], v233 offset:0
	ds_read_b128 v[132:135], v233 offset:1024
	s_add_u32 m0, s9, 0
	s_nop 0
	global_load_lds_dwordx4 v224, s[0:1]
	v_mfma_f32_16x16x32_bf16 v[16:19], v[176:179], v[196:199], v[16:19]
	v_mfma_f32_16x16x32_bf16 v[20:23], v[180:183], v[196:199], v[20:23]
	v_mfma_f32_16x16x32_bf16 v[24:27], v[184:187], v[196:199], v[24:27]
	v_mfma_f32_16x16x32_bf16 v[28:31], v[188:191], v[196:199], v[28:31]
	ds_read_b128 v[136:139], v233 offset:2048
	ds_read_b128 v[140:143], v233 offset:3072
	s_add_u32 m0, s9, 4096
	s_nop 0
	global_load_lds_dwordx4 v225, s[0:1]
	v_mfma_f32_16x16x32_bf16 v[32:35], v[176:179], v[200:203], v[32:35]
	v_mfma_f32_16x16x32_bf16 v[36:39], v[180:183], v[200:203], v[36:39]
	v_mfma_f32_16x16x32_bf16 v[40:43], v[184:187], v[200:203], v[40:43]
	v_mfma_f32_16x16x32_bf16 v[44:47], v[188:191], v[200:203], v[44:47]
	ds_read_b128 v[144:147], v232 offset:0
	ds_read_b128 v[148:151], v232 offset:1024
	s_add_u32 m0, s9, 8192
	s_nop 0
	global_load_lds_dwordx4 v226, s[0:1]
	v_mfma_f32_16x16x32_bf16 v[48:51], v[176:179], v[204:207], v[48:51]
	v_mfma_f32_16x16x32_bf16 v[52:55], v[180:183], v[204:207], v[52:55]
	v_mfma_f32_16x16x32_bf16 v[56:59], v[184:187], v[204:207], v[56:59]
	v_mfma_f32_16x16x32_bf16 v[60:63], v[188:191], v[204:207], v[60:63]
	ds_read_b128 v[152:155], v232 offset:2048
	ds_read_b128 v[156:159], v232 offset:3072
	s_add_u32 m0, s9, 12288
	s_nop 0
	global_load_lds_dwordx4 v227, s[0:1]
	v_mfma_f32_16x16x32_bf16 v[64:67], v[176:179], v[208:211], v[64:67]
	v_mfma_f32_16x16x32_bf16 v[68:71], v[180:183], v[208:211], v[68:71]
	v_mfma_f32_16x16x32_bf16 v[72:75], v[184:187], v[208:211], v[72:75]
	v_mfma_f32_16x16x32_bf16 v[76:79], v[188:191], v[208:211], v[76:79]
	ds_read_b128 v[160:163], v232 offset:4096
	s_add_u32 m0, s9, 16384
	s_nop 0
	global_load_lds_dwordx4 v228, s[2:3]
	v_mfma_f32_16x16x32_bf16 v[80:83], v[176:179], v[212:215], v[80:83]
	v_mfma_f32_16x16x32_bf16 v[84:87], v[180:183], v[212:215], v[84:87]
	v_mfma_f32_16x16x32_bf16 v[88:91], v[184:187], v[212:215], v[88:91]
	v_mfma_f32_16x16x32_bf16 v[92:95], v[188:191], v[212:215], v[92:95]
	ds_read_b128 v[164:167], v232 offset:5120
	s_add_u32 m0, s9, 20480
	s_nop 0
	global_load_lds_dwordx4 v229, s[2:3]
	v_mfma_f32_16x16x32_bf16 v[96:99], v[176:179], v[216:219], v[96:99]
	v_mfma_f32_16x16x32_bf16 v[100:103], v[180:183], v[216:219], v[100:103]
	v_mfma_f32_16x16x32_bf16 v[104:107], v[184:187], v[216:219], v[104:107]
	v_mfma_f32_16x16x32_bf16 v[108:111], v[188:191], v[216:219], v[108:111]
	ds_read_b128 v[168:171], v232 offset:6144
	s_cmp_eq_u32 s8, 0
	s_cbranch_scc0 .Lg9_hi1
	s_setprio 0
; #define LWRITE(S, buf) do { bf16_t* sA_ = sbase + (buf) * BUF; bf16_t* sB_ = sA_ + 256 * PITCH; \
;     _Pragma("unroll") for (int i_ = 0; i_ < 4; ++i_) *(u32x4*)(sA_ + (sr + i_ * 64) * PITCH + scv * 8) = ra[S][i_]; \
;     _Pragma("unroll") for (int i_ = 0; i_ < 2; ++i_) *(u32x4*)(sB_ + (sr + i_ * 64) * PITCH + scv * 8) = rb[S][i_]; } while (0)
; template <class Epi>
; DI void gemm_tile(char* smem, const bf16_t* __restrict__ A0, int lda0, int ksplit, const bf16_t* __restrict__ A1, int lda1,
;                   const bf16_t* __restrict__ Bt, int K, int row0, int col0, const Epi& epi, int tid) {
;     ...
;     for (int kt = 0; kt < nk; kt += 2) {
;       LWRITE(1, 1);
;       __builtin_amdgcn_sched_barrier(0);
;       GLOAD(1, (kt + 3 < last ? kt + 3 : last));
;       __builtin_amdgcn_sched_barrier(0);
;       COMPUTE(0);
;       __syncthreads();
;       LWRITE(0, 0);
;       __builtin_amdgcn_sched_barrier(0);
;       GLOAD(0, (kt + 4 < last ? kt + 4 : last));
;       __builtin_amdgcn_sched_barrier(0);
;       COMPUTE(1);
;       __syncthreads();
;     }
.Lg9_hi1:
	s_add_u32 s0, s0, 64
	s_addc_u32 s1, s1, 0
	s_add_u32 s2, s2, 64
	s_addc_u32 s3, s3, 0
	s_add_u32 s100, s100, 1
	s_add_u32 s17, s17, 24576
	s_cmp_eq_u32 s17, 73728
	s_cselect_b32 s17, 0, s17
	s_add_u32 s98, s98, 24576
	s_cmp_eq_u32 s98, 73728
	s_cselect_b32 s98, 0, s98
	v_mfma_f32_16x16x32_bf16 v[112:115], v[176:179], v[220:223], v[112:115]
	v_mfma_f32_16x16x32_bf16 v[116:119], v[180:183], v[220:223], v[116:119]
	v_mfma_f32_16x16x32_bf16 v[120:123], v[184:187], v[220:223], v[120:123]
	v_mfma_f32_16x16x32_bf16 v[124:127], v[188:191], v[220:223], v[124:127]
	ds_read_b128 v[172:175], v232 offset:7168
	s_add_u32 s99, s99, 2
	s_cmp_lt_u32 s99, 124
	s_cbranch_scc1 .Lg9_kloop
	s_waitcnt vmcnt(6)
	s_waitcnt lgkmcnt(0)
	s_barrier
	v_add_u32_e32 v232, s98, v230
	v_add_u32_e32 v233, s98, v231
	s_add_u32 s9, s17, s101
	s_setprio 1
	v_mfma_f32_16x16x32_bf16 v[0:3], v[128:131], v[144:147], v[0:3]
	v_mfma_f32_16x16x32_bf16 v[4:7], v[132:135], v[144:147], v[4:7]
	v_mfma_f32_16x16x32_bf16 v[8:11], v[136:139], v[144:147], v[8:11]
	v_mfma_f32_16x16x32_bf16 v[12:15], v[140:143], v[144:147], v[12:15]
	ds_read_b128 v[176:179], v233 offset:0
	ds_read_b128 v[180:183], v233 offset:1024
	s_add_u32 m0, s9, 0
	s_nop 0
	global_load_lds_dwordx4 v224, s[0:1]
	v_mfma_f32_16x16x32_bf16 v[16:19], v[128:131], v[148:151], v[16:19]
	v_mfma_f32_16x16x32_bf16 v[20:23], v[132:135], v[148:151], v[20:23]
	v_mfma_f32_16x16x32_bf16 v[24:27], v[136:139], v[148:151], v[24:27]
	v_mfma_f32_16x16x32_bf16 v[28:31], v[140:143], v[148:151], v[28:31]
	ds_read_b128 v[184:187], v233 offset:2048
	ds_read_b128 v[188:191], v233 offset:3072
	s_add_u32 m0, s9, 4096
	s_nop 0
	global_load_lds_dwordx4 v225, s[0:1]
	v_mfma_f32_16x16x32_bf16 v[32:35], v[128:131], v[152:155], v[32:35]
	v_mfma_f32_16x16x32_bf16 v[36:39], v[132:135], v[152:155], v[36:39]
	v_mfma_f32_16x16x32_bf16 v[40:43], v[136:139], v[152:155], v[40:43]
	v_mfma_f32_16x16x32_bf16 v[44:47], v[140:143], v[152:155], v[44:47]
	ds_read_b128 v[192:195], v232 offset:0
	ds_read_b128 v[196:199], v232 offset:1024
	s_add_u32 m0, s9, 8192
	s_nop 0
	global_load_lds_dwordx4 v226, s[0:1]
	v_mfma_f32_16x16x32_bf16 v[48:51], v[128:131], v[156:159], v[48:51]
	v_mfma_f32_16x16x32_bf16 v[52:55], v[132:135], v[156:159], v[52:55]
	v_mfma_f32_16x16x32_bf16 v[56:59], v[136:139], v[156:159], v[56:59]
	v_mfma_f32_16x16x32_bf16 v[60:63], v[140:143], v[156:159], v[60:63]
	ds_read_b128 v[200:203], v232 offset:2048
	ds_read_b128 v[204:207], v232 offset:3072
	s_add_u32 m0, s9, 12288
	s_nop 0
	global_load_lds_dwordx4 v227, s[0:1]
	v_mfma_f32_16x16x32_bf16 v[64:67], v[128:131], v[160:163], v[64:67]
	v_mfma_f32_16x16x32_bf16 v[68:71], v[132:135], v[160:163], v[68:71]
	v_mfma_f32_16x16x32_bf16 v[72:75], v[136:139], v[160:163], v[72:75]
	v_mfma_f32_16x16x32_bf16 v[76:79], v[140:143], v[160:163], v[76:79]
	ds_read_b128 v[208:211], v232 offset:4096
	s_add_u32 m0, s9, 16384
	s_nop 0
	global_load_lds_dwordx4 v228, s[2:3]
	v_mfma_f32_16x16x32_bf16 v[80:83], v[128:131], v[164:167], v[80:83]
	v_mfma_f32_16x16x32_bf16 v[84:87], v[132:135], v[164:167], v[84:87]
	v_mfma_f32_16x16x32_bf16 v[88:91], v[136:139], v[164:167], v[88:91]
	v_mfma_f32_16x16x32_bf16 v[92:95], v[140:143], v[164:167], v[92:95]
	ds_read_b128 v[212:215], v232 offset:5120
	s_add_u32 m0, s9, 20480
	s_nop 0
	global_load_lds_dwordx4 v229, s[2:3]
	v_mfma_f32_16x16x32_bf16 v[96:99], v[128:131], v[168:171], v[96:99]
	v_mfma_f32_16x16x32_bf16 v[100:103], v[132:135], v[168:171], v[100:103]
	v_mfma_f32_16x16x32_bf16 v[104:107], v[136:139], v[168:171], v[104:107]
	v_mfma_f32_16x16x32_bf16 v[108:111], v[140:143], v[168:171], v[108:111]
	ds_read_b128 v[216:219], v232 offset:6144
	s_cmp_eq_u32 s8, 0
	s_cbranch_scc0 .Lg9_hi2
	s_setprio 0
.Lg9_hi2:
	s_add_u32 s0, s0, 64
	s_addc_u32 s1, s1, 0
	s_add_u32 s2, s2, 64
	s_addc_u32 s3, s3, 0
	s_add_u32 s100, s100, 1
	s_add_u32 s17, s17, 24576
	s_cmp_eq_u32 s17, 73728
	s_cselect_b32 s17, 0, s17
	s_add_u32 s98, s98, 24576
	s_cmp_eq_u32 s98, 73728
	s_cselect_b32 s98, 0, s98
	v_mfma_f32_16x16x32_bf16 v[112:115], v[128:131], v[172:175], v[112:115]
	v_mfma_f32_16x16x32_bf16 v[116:119], v[132:135], v[172:175], v[116:119]
	v_mfma_f32_16x16x32_bf16 v[120:123], v[136:139], v[172:175], v[120:123]
	v_mfma_f32_16x16x32_bf16 v[124:127], v[140:143], v[172:175], v[124:127]
	ds_read_b128 v[220:223], v232 offset:7168
	s_waitcnt vmcnt(6)
	s_waitcnt lgkmcnt(0)
	s_barrier
	v_add_u32_e32 v232, s98, v230
	v_add_u32_e32 v233, s98, v231
	s_setprio 1
	v_mfma_f32_16x16x32_bf16 v[0:3], v[176:179], v[192:195], v[0:3]
	v_mfma_f32_16x16x32_bf16 v[4:7], v[180:183], v[192:195], v[4:7]
	v_mfma_f32_16x16x32_bf16 v[8:11], v[184:187], v[192:195], v[8:11]
	v_mfma_f32_16x16x32_bf16 v[12:15], v[188:191], v[192:195], v[12:15]
	ds_read_b128 v[128:131], v233 offset:0
	ds_read_b128 v[132:135], v233 offset:1024
	v_mfma_f32_16x16x32_bf16 v[16:19], v[176:179], v[196:199], v[16:19]
	v_mfma_f32_16x16x32_bf16 v[20:23], v[180:183], v[196:199], v[20:23]
	v_mfma_f32_16x16x32_bf16 v[24:27], v[184:187], v[196:199], v[24:27]
	v_mfma_f32_16x16x32_bf16 v[28:31], v[188:191], v[196:199], v[28:31]
	ds_read_b128 v[136:139], v233 offset:2048
	ds_read_b128 v[140:143], v233 offset:3072
	v_mfma_f32_16x16x32_bf16 v[32:35], v[176:179], v[200:203], v[32:35]
	v_mfma_f32_16x16x32_bf16 v[36:39], v[180:183], v[200:203], v[36:39]
	v_mfma_f32_16x16x32_bf16 v[40:43], v[184:187], v[200:203], v[40:43]
	v_mfma_f32_16x16x32_bf16 v[44:47], v[188:191], v[200:203], v[44:47]
	ds_read_b128 v[144:147], v232 offset:0
	ds_read_b128 v[148:151], v232 offset:1024
	v_mfma_f32_16x16x32_bf16 v[48:51], v[176:179], v[204:207], v[48:51]
	v_mfma_f32_16x16x32_bf16 v[52:55], v[180:183], v[204:207], v[52:55]
	v_mfma_f32_16x16x32_bf16 v[56:59], v[184:187], v[204:207], v[56:59]
	v_mfma_f32_16x16x32_bf16 v[60:63], v[188:191], v[204:207], v[60:63]
	ds_read_b128 v[152:155], v232 offset:2048
	ds_read_b128 v[156:159], v232 offset:3072
	v_mfma_f32_16x16x32_bf16 v[64:67], v[176:179], v[208:211], v[64:67]
	v_mfma_f32_16x16x32_bf16 v[68:71], v[180:183], v[208:211], v[68:71]
	v_mfma_f32_16x16x32_bf16 v[72:75], v[184:187], v[208:211], v[72:75]
	v_mfma_f32_16x16x32_bf16 v[76:79], v[188:191], v[208:211], v[76:79]
	ds_read_b128 v[160:163], v232 offset:4096
	v_mfma_f32_16x16x32_bf16 v[80:83], v[176:179], v[212:215], v[80:83]
	v_mfma_f32_16x16x32_bf16 v[84:87], v[180:183], v[212:215], v[84:87]
	v_mfma_f32_16x16x32_bf16 v[88:91], v[184:187], v[212:215], v[88:91]
	v_mfma_f32_16x16x32_bf16 v[92:95], v[188:191], v[212:215], v[92:95]
	ds_read_b128 v[164:167], v232 offset:5120
	v_mfma_f32_16x16x32_bf16 v[96:99], v[176:179], v[216:219], v[96:99]
	v_mfma_f32_16x16x32_bf16 v[100:103], v[180:183], v[216:219], v[100:103]
	v_mfma_f32_16x16x32_bf16 v[104:107], v[184:187], v[216:219], v[104:107]
	v_mfma_f32_16x16x32_bf16 v[108:111], v[188:191], v[216:219], v[108:111]
	ds_read_b128 v[168:171], v232 offset:6144
	s_cmp_eq_u32 s8, 0
	s_cbranch_scc0 .Lg9_hi3
	s_setprio 0
.Lg9_hi3:
	s_add_u32 s98, s98, 24576
	s_cmp_eq_u32 s98, 73728
	s_cselect_b32 s98, 0, s98
	v_mfma_f32_16x16x32_bf16 v[112:115], v[176:179], v[220:223], v[112:115]
	v_mfma_f32_16x16x32_bf16 v[116:119], v[180:183], v[220:223], v[116:119]
	v_mfma_f32_16x16x32_bf16 v[120:123], v[184:187], v[220:223], v[120:123]
	v_mfma_f32_16x16x32_bf16 v[124:127], v[188:191], v[220:223], v[124:127]
	ds_read_b128 v[172:175], v232 offset:7168
	s_waitcnt vmcnt(0)
	s_waitcnt lgkmcnt(0)
	s_barrier
	v_add_u32_e32 v232, s98, v230
	v_add_u32_e32 v233, s98, v231
	s_setprio 1
	v_mfma_f32_16x16x32_bf16 v[0:3], v[128:131], v[144:147], v[0:3]
	v_mfma_f32_16x16x32_bf16 v[4:7], v[132:135], v[144:147], v[4:7]
	v_mfma_f32_16x16x32_bf16 v[8:11], v[136:139], v[144:147], v[8:11]
	v_mfma_f32_16x16x32_bf16 v[12:15], v[140:143], v[144:147], v[12:15]
	ds_read_b128 v[176:179], v233 offset:0
	ds_read_b128 v[180:183], v233 offset:1024
	v_mfma_f32_16x16x32_bf16 v[16:19], v[128:131], v[148:151], v[16:19]
	v_mfma_f32_16x16x32_bf16 v[20:23], v[132:135], v[148:151], v[20:23]
	v_mfma_f32_16x16x32_bf16 v[24:27], v[136:139], v[148:151], v[24:27]
	v_mfma_f32_16x16x32_bf16 v[28:31], v[140:143], v[148:151], v[28:31]
	ds_read_b128 v[184:187], v233 offset:2048
	ds_read_b128 v[188:191], v233 offset:3072
	v_mfma_f32_16x16x32_bf16 v[32:35], v[128:131], v[152:155], v[32:35]
	v_mfma_f32_16x16x32_bf16 v[36:39], v[132:135], v[152:155], v[36:39]
	v_mfma_f32_16x16x32_bf16 v[40:43], v[136:139], v[152:155], v[40:43]
	v_mfma_f32_16x16x32_bf16 v[44:47], v[140:143], v[152:155], v[44:47]
	ds_read_b128 v[192:195], v232 offset:0
	ds_read_b128 v[196:199], v232 offset:1024
	v_mfma_f32_16x16x32_bf16 v[48:51], v[128:131], v[156:159], v[48:51]
	v_mfma_f32_16x16x32_bf16 v[52:55], v[132:135], v[156:159], v[52:55]
	v_mfma_f32_16x16x32_bf16 v[56:59], v[136:139], v[156:159], v[56:59]
	v_mfma_f32_16x16x32_bf16 v[60:63], v[140:143], v[156:159], v[60:63]
	ds_read_b128 v[200:203], v232 offset:2048
	ds_read_b128 v[204:207], v232 offset:3072
	v_mfma_f32_16x16x32_bf16 v[64:67], v[128:131], v[160:163], v[64:67]
	v_mfma_f32_16x16x32_bf16 v[68:71], v[132:135], v[160:163], v[68:71]
	v_mfma_f32_16x16x32_bf16 v[72:75], v[136:139], v[160:163], v[72:75]
	v_mfma_f32_16x16x32_bf16 v[76:79], v[140:143], v[160:163], v[76:79]
	ds_read_b128 v[208:211], v232 offset:4096
	v_mfma_f32_16x16x32_bf16 v[80:83], v[128:131], v[164:167], v[80:83]
	v_mfma_f32_16x16x32_bf16 v[84:87], v[132:135], v[164:167], v[84:87]
	v_mfma_f32_16x16x32_bf16 v[88:91], v[136:139], v[164:167], v[88:91]
	v_mfma_f32_16x16x32_bf16 v[92:95], v[140:143], v[164:167], v[92:95]
	ds_read_b128 v[212:215], v232 offset:5120
	v_mfma_f32_16x16x32_bf16 v[96:99], v[128:131], v[168:171], v[96:99]
	v_mfma_f32_16x16x32_bf16 v[100:103], v[132:135], v[168:171], v[100:103]
	v_mfma_f32_16x16x32_bf16 v[104:107], v[136:139], v[168:171], v[104:107]
	v_mfma_f32_16x16x32_bf16 v[108:111], v[140:143], v[168:171], v[108:111]
	ds_read_b128 v[216:219], v232 offset:6144
	s_cmp_eq_u32 s8, 0
	s_cbranch_scc0 .Lg9_hi4
	s_setprio 0
.Lg9_hi4:
	s_add_u32 s98, s98, 24576
	s_cmp_eq_u32 s98, 73728
	s_cselect_b32 s98, 0, s98
	v_mfma_f32_16x16x32_bf16 v[112:115], v[128:131], v[172:175], v[112:115]
	v_mfma_f32_16x16x32_bf16 v[116:119], v[132:135], v[172:175], v[116:119]
	v_mfma_f32_16x16x32_bf16 v[120:123], v[136:139], v[172:175], v[120:123]
	v_mfma_f32_16x16x32_bf16 v[124:127], v[140:143], v[172:175], v[124:127]
	ds_read_b128 v[220:223], v232 offset:7168
	s_waitcnt lgkmcnt(0)
	s_barrier
	s_setprio 1
	v_mfma_f32_16x16x32_bf16 v[0:3], v[176:179], v[192:195], v[0:3]
	v_mfma_f32_16x16x32_bf16 v[4:7], v[180:183], v[192:195], v[4:7]
	v_mfma_f32_16x16x32_bf16 v[8:11], v[184:187], v[192:195], v[8:11]
	v_mfma_f32_16x16x32_bf16 v[12:15], v[188:191], v[192:195], v[12:15]
	v_mfma_f32_16x16x32_bf16 v[16:19], v[176:179], v[196:199], v[16:19]
	v_mfma_f32_16x16x32_bf16 v[20:23], v[180:183], v[196:199], v[20:23]
	v_mfma_f32_16x16x32_bf16 v[24:27], v[184:187], v[196:199], v[24:27]
	v_mfma_f32_16x16x32_bf16 v[28:31], v[188:191], v[196:199], v[28:31]
	v_mfma_f32_16x16x32_bf16 v[32:35], v[176:179], v[200:203], v[32:35]
	v_mfma_f32_16x16x32_bf16 v[36:39], v[180:183], v[200:203], v[36:39]
	v_mfma_f32_16x16x32_bf16 v[40:43], v[184:187], v[200:203], v[40:43]
	v_mfma_f32_16x16x32_bf16 v[44:47], v[188:191], v[200:203], v[44:47]
	v_mfma_f32_16x16x32_bf16 v[48:51], v[176:179], v[204:207], v[48:51]
	v_mfma_f32_16x16x32_bf16 v[52:55], v[180:183], v[204:207], v[52:55]
	v_mfma_f32_16x16x32_bf16 v[56:59], v[184:187], v[204:207], v[56:59]
	v_mfma_f32_16x16x32_bf16 v[60:63], v[188:191], v[204:207], v[60:63]
	v_mfma_f32_16x16x32_bf16 v[64:67], v[176:179], v[208:211], v[64:67]
	v_mfma_f32_16x16x32_bf16 v[68:71], v[180:183], v[208:211], v[68:71]
	v_mfma_f32_16x16x32_bf16 v[72:75], v[184:187], v[208:211], v[72:75]
	v_mfma_f32_16x16x32_bf16 v[76:79], v[188:191], v[208:211], v[76:79]
	v_mfma_f32_16x16x32_bf16 v[80:83], v[176:179], v[212:215], v[80:83]
	v_mfma_f32_16x16x32_bf16 v[84:87], v[180:183], v[212:215], v[84:87]
	v_mfma_f32_16x16x32_bf16 v[88:91], v[184:187], v[212:215], v[88:91]
	v_mfma_f32_16x16x32_bf16 v[92:95], v[188:191], v[212:215], v[92:95]
	v_mfma_f32_16x16x32_bf16 v[96:99], v[176:179], v[216:219], v[96:99]
	v_mfma_f32_16x16x32_bf16 v[100:103], v[180:183], v[216:219], v[100:103]
	v_mfma_f32_16x16x32_bf16 v[104:107], v[184:187], v[216:219], v[104:107]
	v_mfma_f32_16x16x32_bf16 v[108:111], v[188:191], v[216:219], v[108:111]
	s_cmp_eq_u32 s8, 0
	s_cbranch_scc0 .Lg9_hi5
	s_setprio 0

; #define LWRITE(S, buf) do { bf16_t* sA_ = sbase + (buf) * BUF; bf16_t* sB_ = sA_ + 256 * PITCH; \
;     _Pragma("unroll") for (int i_ = 0; i_ < 4; ++i_) *(u32x4*)(sA_ + (sr + i_ * 64) * PITCH + scv * 8) = ra[S][i_]; \
;     _Pragma("unroll") for (int i_ = 0; i_ < 2; ++i_) *(u32x4*)(sB_ + (sr + i_ * 64) * PITCH + scv * 8) = rb[S][i_]; } while (0)
; template <class Epi>
; DI void gemm_tile(char* smem, const bf16_t* __restrict__ A0, int lda0, int ksplit, const bf16_t* __restrict__ A1, int lda1,
;                   const bf16_t* __restrict__ Bt, int K, int row0, int col0, const Epi& epi, int tid) {
;     ...
;     for (int kt = 0; kt < nk; kt += 2) {
;       LWRITE(1, 1);
;       __builtin_amdgcn_sched_barrier(0);
;       GLOAD(1, (kt + 3 < last ? kt + 3 : last));
;       __builtin_amdgcn_sched_barrier(0);
;       COMPUTE(0);
;       __syncthreads();
;       LWRITE(0, 0);
;       __builtin_amdgcn_sched_barrier(0);
;       GLOAD(0, (kt + 4 < last ? kt + 4 : last));
;       __builtin_amdgcn_sched_barrier(0);
;       COMPUTE(1);
;       __syncthreads();
;     }
.Lg11_kloop:
	s_waitcnt vmcnt(6)
	s_waitcnt lgkmcnt(0)
	s_barrier
	v_add_u32_e32 v232, s30, v230
	v_add_u32_e32 v233, s30, v231
	s_add_u32 s25, s29, s99
	s_setprio 1
	v_mfma_f32_16x16x32_bf16 v[0:3], v[128:131], v[144:147], v[0:3]
	v_mfma_f32_16x16x32_bf16 v[4:7], v[132:135], v[144:147], v[4:7]
	v_mfma_f32_16x16x32_bf16 v[8:11], v[136:139], v[144:147], v[8:11]
	v_mfma_f32_16x16x32_bf16 v[12:15], v[140:143], v[144:147], v[12:15]
	ds_read_b128 v[176:179], v233 offset:0
	ds_read_b128 v[180:183], v233 offset:1024
	s_add_u32 m0, s25, 0
	s_nop 0
	global_load_lds_dwordx4 v224, s[0:1]
	v_mfma_f32_16x16x32_bf16 v[16:19], v[128:131], v[148:151], v[16:19]
	v_mfma_f32_16x16x32_bf16 v[20:23], v[132:135], v[148:151], v[20:23]
	v_mfma_f32_16x16x32_bf16 v[24:27], v[136:139], v[148:151], v[24:27]
	v_mfma_f32_16x16x32_bf16 v[28:31], v[140:143], v[148:151], v[28:31]
	ds_read_b128 v[184:187], v233 offset:2048
	ds_read_b128 v[188:191], v233 offset:3072
	s_add_u32 m0, s25, 4096
	s_nop 0
	global_load_lds_dwordx4 v225, s[0:1]
	v_mfma_f32_16x16x32_bf16 v[32:35], v[128:131], v[152:155], v[32:35]
	v_mfma_f32_16x16x32_bf16 v[36:39], v[132:135], v[152:155], v[36:39]
	v_mfma_f32_16x16x32_bf16 v[40:43], v[136:139], v[152:155], v[40:43]
	v_mfma_f32_16x16x32_bf16 v[44:47], v[140:143], v[152:155], v[44:47]
	ds_read_b128 v[192:195], v232 offset:0
	ds_read_b128 v[196:199], v232 offset:1024
	s_add_u32 m0, s25, 8192
	s_nop 0
	global_load_lds_dwordx4 v226, s[0:1]
	v_mfma_f32_16x16x32_bf16 v[48:51], v[128:131], v[156:159], v[48:51]
	v_mfma_f32_16x16x32_bf16 v[52:55], v[132:135], v[156:159], v[52:55]
	v_mfma_f32_16x16x32_bf16 v[56:59], v[136:139], v[156:159], v[56:59]
	v_mfma_f32_16x16x32_bf16 v[60:63], v[140:143], v[156:159], v[60:63]
	ds_read_b128 v[200:203], v232 offset:2048
	ds_read_b128 v[204:207], v232 offset:3072
	s_add_u32 m0, s25, 12288
	s_nop 0
	global_load_lds_dwordx4 v227, s[0:1]
	v_mfma_f32_16x16x32_bf16 v[64:67], v[128:131], v[160:163], v[64:67]
	v_mfma_f32_16x16x32_bf16 v[68:71], v[132:135], v[160:163], v[68:71]
	v_mfma_f32_16x16x32_bf16 v[72:75], v[136:139], v[160:163], v[72:75]
	v_mfma_f32_16x16x32_bf16 v[76:79], v[140:143], v[160:163], v[76:79]
	ds_read_b128 v[208:211], v232 offset:4096
	s_add_u32 m0, s25, 16384
	s_nop 0
	global_load_lds_dwordx4 v228, s[2:3]
	v_mfma_f32_16x16x32_bf16 v[80:83], v[128:131], v[164:167], v[80:83]
	v_mfma_f32_16x16x32_bf16 v[84:87], v[132:135], v[164:167], v[84:87]
	v_mfma_f32_16x16x32_bf16 v[88:91], v[136:139], v[164:167], v[88:91]
	v_mfma_f32_16x16x32_bf16 v[92:95], v[140:143], v[164:167], v[92:95]
	ds_read_b128 v[212:215], v232 offset:5120
	s_add_u32 m0, s25, 20480
	s_nop 0
	global_load_lds_dwordx4 v229, s[2:3]
	v_mfma_f32_16x16x32_bf16 v[96:99], v[128:131], v[168:171], v[96:99]
	v_mfma_f32_16x16x32_bf16 v[100:103], v[132:135], v[168:171], v[100:103]
	v_mfma_f32_16x16x32_bf16 v[104:107], v[136:139], v[168:171], v[104:107]
	v_mfma_f32_16x16x32_bf16 v[108:111], v[140:143], v[168:171], v[108:111]
	ds_read_b128 v[216:219], v232 offset:6144
	s_cmp_eq_u32 s24, 0
	s_cbranch_scc0 .Lg11_hi0
	s_setprio 0
.Lg11_hi0:
	s_add_u32 s0, s0, 64
	s_addc_u32 s1, s1, 0
	s_add_u32 s2, s2, 64
	s_addc_u32 s3, s3, 0
	s_add_u32 s98, s98, 1
	s_add_u32 s29, s29, 24576
	s_cmp_eq_u32 s29, 73728
	s_cselect_b32 s29, 0, s29
	s_add_u32 s30, s30, 24576
	s_cmp_eq_u32 s30, 73728
	s_cselect_b32 s30, 0, s30
	v_mfma_f32_16x16x32_bf16 v[112:115], v[128:131], v[172:175], v[112:115]
	v_mfma_f32_16x16x32_bf16 v[116:119], v[132:135], v[172:175], v[116:119]
	v_mfma_f32_16x16x32_bf16 v[120:123], v[136:139], v[172:175], v[120:123]
	v_mfma_f32_16x16x32_bf16 v[124:127], v[140:143], v[172:175], v[124:127]
	ds_read_b128 v[220:223], v232 offset:7168
	s_waitcnt vmcnt(6)
	s_waitcnt lgkmcnt(0)
	s_barrier
	v_add_u32_e32 v232, s30, v230
	v_add_u32_e32 v233, s30, v231
	s_add_u32 s25, s29, s99
	s_setprio 1
	v_mfma_f32_16x16x32_bf16 v[0:3], v[176:179], v[192:195], v[0:3]
	v_mfma_f32_16x16x32_bf16 v[4:7], v[180:183], v[192:195], v[4:7]
	v_mfma_f32_16x16x32_bf16 v[8:11], v[184:187], v[192:195], v[8:11]
	v_mfma_f32_16x16x32_bf16 v[12:15], v[188:191], v[192:195], v[12:15]
	ds_read_b128 v[128:131], v233 offset:0
	ds_read_b128 v[132:135], v233 offset:1024
	s_add_u32 m0, s25, 0
	s_nop 0
	global_load_lds_dwordx4 v224, s[0:1]
	v_mfma_f32_16x16x32_bf16 v[16:19], v[176:179], v[196:199], v[16:19]
	v_mfma_f32_16x16x32_bf16 v[20:23], v[180:183], v[196:199], v[20:23]
	v_mfma_f32_16x16x32_bf16 v[24:27], v[184:187], v[196:199], v[24:27]
	v_mfma_f32_16x16x32_bf16 v[28:31], v[188:191], v[196:199], v[28:31]
	ds_read_b128 v[136:139], v233 offset:2048
	ds_read_b128 v[140:143], v233 offset:3072
	s_add_u32 m0, s25, 4096
	s_nop 0
	global_load_lds_dwordx4 v225, s[0:1]
	v_mfma_f32_16x16x32_bf16 v[32:35], v[176:179], v[200:203], v[32:35]
	v_mfma_f32_16x16x32_bf16 v[36:39], v[180:183], v[200:203], v[36:39]
	v_mfma_f32_16x16x32_bf16 v[40:43], v[184:187], v[200:203], v[40:43]
	v_mfma_f32_16x16x32_bf16 v[44:47], v[188:191], v[200:203], v[44:47]
	ds_read_b128 v[144:147], v232 offset:0
	ds_read_b128 v[148:151], v232 offset:1024
	s_add_u32 m0, s25, 8192
	s_nop 0
	global_load_lds_dwordx4 v226, s[0:1]
	v_mfma_f32_16x16x32_bf16 v[48:51], v[176:179], v[204:207], v[48:51]
	v_mfma_f32_16x16x32_bf16 v[52:55], v[180:183], v[204:207], v[52:55]
	v_mfma_f32_16x16x32_bf16 v[56:59], v[184:187], v[204:207], v[56:59]
	v_mfma_f32_16x16x32_bf16 v[60:63], v[188:191], v[204:207], v[60:63]
	ds_read_b128 v[152:155], v232 offset:2048
	ds_read_b128 v[156:159], v232 offset:3072
	s_add_u32 m0, s25, 12288
	s_nop 0
	global_load_lds_dwordx4 v227, s[0:1]
	v_mfma_f32_16x16x32_bf16 v[64:67], v[176:179], v[208:211], v[64:67]
	v_mfma_f32_16x16x32_bf16 v[68:71], v[180:183], v[208:211], v[68:71]
	v_mfma_f32_16x16x32_bf16 v[72:75], v[184:187], v[208:211], v[72:75]
	v_mfma_f32_16x16x32_bf16 v[76:79], v[188:191], v[208:211], v[76:79]
	ds_read_b128 v[160:163], v232 offset:4096
	s_add_u32 m0, s25, 16384
	s_nop 0
	global_load_lds_dwordx4 v228, s[2:3]
	v_mfma_f32_16x16x32_bf16 v[80:83], v[176:179], v[212:215], v[80:83]
	v_mfma_f32_16x16x32_bf16 v[84:87], v[180:183], v[212:215], v[84:87]
	v_mfma_f32_16x16x32_bf16 v[88:91], v[184:187], v[212:215], v[88:91]
	v_mfma_f32_16x16x32_bf16 v[92:95], v[188:191], v[212:215], v[92:95]
	ds_read_b128 v[164:167], v232 offset:5120
	s_add_u32 m0, s25, 20480
	s_nop 0
	global_load_lds_dwordx4 v229, s[2:3]
	v_mfma_f32_16x16x32_bf16 v[96:99], v[176:179], v[216:219], v[96:99]
	v_mfma_f32_16x16x32_bf16 v[100:103], v[180:183], v[216:219], v[100:103]
	v_mfma_f32_16x16x32_bf16 v[104:107], v[184:187], v[216:219], v[104:107]
	v_mfma_f32_16x16x32_bf16 v[108:111], v[188:191], v[216:219], v[108:111]
	ds_read_b128 v[168:171], v232 offset:6144
	s_cmp_eq_u32 s24, 0
	s_cbranch_scc0 .Lg11_hi1
	s_setprio 0
; #define LWRITE(S, buf) do { bf16_t* sA_ = sbase + (buf) * BUF; bf16_t* sB_ = sA_ + 256 * PITCH; \
;     _Pragma("unroll") for (int i_ = 0; i_ < 4; ++i_) *(u32x4*)(sA_ + (sr + i_ * 64) * PITCH + scv * 8) = ra[S][i_]; \
;     _Pragma("unroll") for (int i_ = 0; i_ < 2; ++i_) *(u32x4*)(sB_ + (sr + i_ * 64) * PITCH + scv * 8) = rb[S][i_]; } while (0)
; template <class Epi>
; DI void gemm_tile(char* smem, const bf16_t* __restrict__ A0, int lda0, int ksplit, const bf16_t* __restrict__ A1, int lda1,
;                   const bf16_t* __restrict__ Bt, int K, int row0, int col0, const Epi& epi, int tid) {
;     ...
;     for (int kt = 0; kt < nk; kt += 2) {
;       LWRITE(1, 1);
;       __builtin_amdgcn_sched_barrier(0);
;       GLOAD(1, (kt + 3 < last ? kt + 3 : last));
;       __builtin_amdgcn_sched_barrier(0);
;       COMPUTE(0);
;       __syncthreads();
;       LWRITE(0, 0);
;       __builtin_amdgcn_sched_barrier(0);
;       GLOAD(0, (kt + 4 < last ? kt + 4 : last));
;       __builtin_amdgcn_sched_barrier(0);
;       COMPUTE(1);
;       __syncthreads();
;     }
.Lg11_hi1:
	s_add_u32 s0, s0, 64
	s_addc_u32 s1, s1, 0
	s_add_u32 s2, s2, 64
	s_addc_u32 s3, s3, 0
	s_add_u32 s98, s98, 1
	s_add_u32 s29, s29, 24576
	s_cmp_eq_u32 s29, 73728
	s_cselect_b32 s29, 0, s29
	s_add_u32 s30, s30, 24576
	s_cmp_eq_u32 s30, 73728
	s_cselect_b32 s30, 0, s30
	v_mfma_f32_16x16x32_bf16 v[112:115], v[176:179], v[220:223], v[112:115]
	v_mfma_f32_16x16x32_bf16 v[116:119], v[180:183], v[220:223], v[116:119]
	v_mfma_f32_16x16x32_bf16 v[120:123], v[184:187], v[220:223], v[120:123]
	v_mfma_f32_16x16x32_bf16 v[124:127], v[188:191], v[220:223], v[124:127]
	ds_read_b128 v[172:175], v232 offset:7168
	s_add_u32 s31, s31, 2
	s_cmp_lt_u32 s31, 28
	s_cbranch_scc1 .Lg11_kloop
	s_waitcnt vmcnt(6)
	s_waitcnt lgkmcnt(0)
	s_barrier
	v_add_u32_e32 v232, s30, v230
	v_add_u32_e32 v233, s30, v231
	s_add_u32 s25, s29, s99
	s_setprio 1
	v_mfma_f32_16x16x32_bf16 v[0:3], v[128:131], v[144:147], v[0:3]
	v_mfma_f32_16x16x32_bf16 v[4:7], v[132:135], v[144:147], v[4:7]
	v_mfma_f32_16x16x32_bf16 v[8:11], v[136:139], v[144:147], v[8:11]
	v_mfma_f32_16x16x32_bf16 v[12:15], v[140:143], v[144:147], v[12:15]
	ds_read_b128 v[176:179], v233 offset:0
	ds_read_b128 v[180:183], v233 offset:1024
	s_add_u32 m0, s25, 0
	s_nop 0
	global_load_lds_dwordx4 v224, s[0:1]
	v_mfma_f32_16x16x32_bf16 v[16:19], v[128:131], v[148:151], v[16:19]
	v_mfma_f32_16x16x32_bf16 v[20:23], v[132:135], v[148:151], v[20:23]
	v_mfma_f32_16x16x32_bf16 v[24:27], v[136:139], v[148:151], v[24:27]
	v_mfma_f32_16x16x32_bf16 v[28:31], v[140:143], v[148:151], v[28:31]
	ds_read_b128 v[184:187], v233 offset:2048
	ds_read_b128 v[188:191], v233 offset:3072
	s_add_u32 m0, s25, 4096
	s_nop 0
	global_load_lds_dwordx4 v225, s[0:1]
	v_mfma_f32_16x16x32_bf16 v[32:35], v[128:131], v[152:155], v[32:35]
	v_mfma_f32_16x16x32_bf16 v[36:39], v[132:135], v[152:155], v[36:39]
	v_mfma_f32_16x16x32_bf16 v[40:43], v[136:139], v[152:155], v[40:43]
	v_mfma_f32_16x16x32_bf16 v[44:47], v[140:143], v[152:155], v[44:47]
	ds_read_b128 v[192:195], v232 offset:0
	ds_read_b128 v[196:199], v232 offset:1024
	s_add_u32 m0, s25, 8192
	s_nop 0
	global_load_lds_dwordx4 v226, s[0:1]
	v_mfma_f32_16x16x32_bf16 v[48:51], v[128:131], v[156:159], v[48:51]
	v_mfma_f32_16x16x32_bf16 v[52:55], v[132:135], v[156:159], v[52:55]
	v_mfma_f32_16x16x32_bf16 v[56:59], v[136:139], v[156:159], v[56:59]
	v_mfma_f32_16x16x32_bf16 v[60:63], v[140:143], v[156:159], v[60:63]
	ds_read_b128 v[200:203], v232 offset:2048
	ds_read_b128 v[204:207], v232 offset:3072
	s_add_u32 m0, s25, 12288
	s_nop 0
	global_load_lds_dwordx4 v227, s[0:1]
	v_mfma_f32_16x16x32_bf16 v[64:67], v[128:131], v[160:163], v[64:67]
	v_mfma_f32_16x16x32_bf16 v[68:71], v[132:135], v[160:163], v[68:71]
	v_mfma_f32_16x16x32_bf16 v[72:75], v[136:139], v[160:163], v[72:75]
	v_mfma_f32_16x16x32_bf16 v[76:79], v[140:143], v[160:163], v[76:79]
	ds_read_b128 v[208:211], v232 offset:4096
	s_add_u32 m0, s25, 16384
	s_nop 0
	global_load_lds_dwordx4 v228, s[2:3]
	v_mfma_f32_16x16x32_bf16 v[80:83], v[128:131], v[164:167], v[80:83]
	v_mfma_f32_16x16x32_bf16 v[84:87], v[132:135], v[164:167], v[84:87]
	v_mfma_f32_16x16x32_bf16 v[88:91], v[136:139], v[164:167], v[88:91]
	v_mfma_f32_16x16x32_bf16 v[92:95], v[140:143], v[164:167], v[92:95]
	ds_read_b128 v[212:215], v232 offset:5120
	s_add_u32 m0, s25, 20480
	s_nop 0
	global_load_lds_dwordx4 v229, s[2:3]
	v_mfma_f32_16x16x32_bf16 v[96:99], v[128:131], v[168:171], v[96:99]
	v_mfma_f32_16x16x32_bf16 v[100:103], v[132:135], v[168:171], v[100:103]
	v_mfma_f32_16x16x32_bf16 v[104:107], v[136:139], v[168:171], v[104:107]
	v_mfma_f32_16x16x32_bf16 v[108:111], v[140:143], v[168:171], v[108:111]
	ds_read_b128 v[216:219], v232 offset:6144
	s_cmp_eq_u32 s24, 0
	s_cbranch_scc0 .Lg11_hi2
	s_setprio 0
.Lg11_hi2:
	s_add_u32 s0, s0, 64
	s_addc_u32 s1, s1, 0
	s_add_u32 s2, s2, 64
	s_addc_u32 s3, s3, 0
	s_add_u32 s98, s98, 1
	s_add_u32 s29, s29, 24576
	s_cmp_eq_u32 s29, 73728
	s_cselect_b32 s29, 0, s29
	s_add_u32 s30, s30, 24576
	s_cmp_eq_u32 s30, 73728
	s_cselect_b32 s30, 0, s30
	v_mfma_f32_16x16x32_bf16 v[112:115], v[128:131], v[172:175], v[112:115]
	v_mfma_f32_16x16x32_bf16 v[116:119], v[132:135], v[172:175], v[116:119]
	v_mfma_f32_16x16x32_bf16 v[120:123], v[136:139], v[172:175], v[120:123]
	v_mfma_f32_16x16x32_bf16 v[124:127], v[140:143], v[172:175], v[124:127]
	ds_read_b128 v[220:223], v232 offset:7168
	s_waitcnt vmcnt(6)
	s_waitcnt lgkmcnt(0)
	s_barrier
	v_add_u32_e32 v232, s30, v230
	v_add_u32_e32 v233, s30, v231
	s_setprio 1
	v_mfma_f32_16x16x32_bf16 v[0:3], v[176:179], v[192:195], v[0:3]
	v_mfma_f32_16x16x32_bf16 v[4:7], v[180:183], v[192:195], v[4:7]
	v_mfma_f32_16x16x32_bf16 v[8:11], v[184:187], v[192:195], v[8:11]
	v_mfma_f32_16x16x32_bf16 v[12:15], v[188:191], v[192:195], v[12:15]
	ds_read_b128 v[128:131], v233 offset:0
	ds_read_b128 v[132:135], v233 offset:1024
	v_mfma_f32_16x16x32_bf16 v[16:19], v[176:179], v[196:199], v[16:19]
	v_mfma_f32_16x16x32_bf16 v[20:23], v[180:183], v[196:199], v[20:23]
	v_mfma_f32_16x16x32_bf16 v[24:27], v[184:187], v[196:199], v[24:27]
	v_mfma_f32_16x16x32_bf16 v[28:31], v[188:191], v[196:199], v[28:31]
	ds_read_b128 v[136:139], v233 offset:2048
	ds_read_b128 v[140:143], v233 offset:3072
	v_mfma_f32_16x16x32_bf16 v[32:35], v[176:179], v[200:203], v[32:35]
	v_mfma_f32_16x16x32_bf16 v[36:39], v[180:183], v[200:203], v[36:39]
	v_mfma_f32_16x16x32_bf16 v[40:43], v[184:187], v[200:203], v[40:43]
	v_mfma_f32_16x16x32_bf16 v[44:47], v[188:191], v[200:203], v[44:47]
	ds_read_b128 v[144:147], v232 offset:0
	ds_read_b128 v[148:151], v232 offset:1024
	v_mfma_f32_16x16x32_bf16 v[48:51], v[176:179], v[204:207], v[48:51]
	v_mfma_f32_16x16x32_bf16 v[52:55], v[180:183], v[204:207], v[52:55]
	v_mfma_f32_16x16x32_bf16 v[56:59], v[184:187], v[204:207], v[56:59]
	v_mfma_f32_16x16x32_bf16 v[60:63], v[188:191], v[204:207], v[60:63]
	ds_read_b128 v[152:155], v232 offset:2048
	ds_read_b128 v[156:159], v232 offset:3072
	v_mfma_f32_16x16x32_bf16 v[64:67], v[176:179], v[208:211], v[64:67]
	v_mfma_f32_16x16x32_bf16 v[68:71], v[180:183], v[208:211], v[68:71]
	v_mfma_f32_16x16x32_bf16 v[72:75], v[184:187], v[208:211], v[72:75]
	v_mfma_f32_16x16x32_bf16 v[76:79], v[188:191], v[208:211], v[76:79]
	ds_read_b128 v[160:163], v232 offset:4096
	v_mfma_f32_16x16x32_bf16 v[80:83], v[176:179], v[212:215], v[80:83]
	v_mfma_f32_16x16x32_bf16 v[84:87], v[180:183], v[212:215], v[84:87]
	v_mfma_f32_16x16x32_bf16 v[88:91], v[184:187], v[212:215], v[88:91]
	v_mfma_f32_16x16x32_bf16 v[92:95], v[188:191], v[212:215], v[92:95]
	ds_read_b128 v[164:167], v232 offset:5120
	v_mfma_f32_16x16x32_bf16 v[96:99], v[176:179], v[216:219], v[96:99]
	v_mfma_f32_16x16x32_bf16 v[100:103], v[180:183], v[216:219], v[100:103]
	v_mfma_f32_16x16x32_bf16 v[104:107], v[184:187], v[216:219], v[104:107]
	v_mfma_f32_16x16x32_bf16 v[108:111], v[188:191], v[216:219], v[108:111]
	ds_read_b128 v[168:171], v232 offset:6144
	s_cmp_eq_u32 s24, 0
	s_cbranch_scc0 .Lg11_hi3
	s_setprio 0
.Lg11_hi3:
	s_add_u32 s30, s30, 24576
	s_cmp_eq_u32 s30, 73728
	s_cselect_b32 s30, 0, s30
	v_mfma_f32_16x16x32_bf16 v[112:115], v[176:179], v[220:223], v[112:115]
	v_mfma_f32_16x16x32_bf16 v[116:119], v[180:183], v[220:223], v[116:119]
	v_mfma_f32_16x16x32_bf16 v[120:123], v[184:187], v[220:223], v[120:123]
	v_mfma_f32_16x16x32_bf16 v[124:127], v[188:191], v[220:223], v[124:127]
	ds_read_b128 v[172:175], v232 offset:7168
	s_waitcnt vmcnt(0)
	s_waitcnt lgkmcnt(0)
	s_barrier
	v_add_u32_e32 v232, s30, v230
	v_add_u32_e32 v233, s30, v231
	s_setprio 1
	v_mfma_f32_16x16x32_bf16 v[0:3], v[128:131], v[144:147], v[0:3]
	v_mfma_f32_16x16x32_bf16 v[4:7], v[132:135], v[144:147], v[4:7]
	v_mfma_f32_16x16x32_bf16 v[8:11], v[136:139], v[144:147], v[8:11]
	v_mfma_f32_16x16x32_bf16 v[12:15], v[140:143], v[144:147], v[12:15]
	ds_read_b128 v[176:179], v233 offset:0
	ds_read_b128 v[180:183], v233 offset:1024
	v_mfma_f32_16x16x32_bf16 v[16:19], v[128:131], v[148:151], v[16:19]
	v_mfma_f32_16x16x32_bf16 v[20:23], v[132:135], v[148:151], v[20:23]
	v_mfma_f32_16x16x32_bf16 v[24:27], v[136:139], v[148:151], v[24:27]
	v_mfma_f32_16x16x32_bf16 v[28:31], v[140:143], v[148:151], v[28:31]
	ds_read_b128 v[184:187], v233 offset:2048
	ds_read_b128 v[188:191], v233 offset:3072
	v_mfma_f32_16x16x32_bf16 v[32:35], v[128:131], v[152:155], v[32:35]
	v_mfma_f32_16x16x32_bf16 v[36:39], v[132:135], v[152:155], v[36:39]
	v_mfma_f32_16x16x32_bf16 v[40:43], v[136:139], v[152:155], v[40:43]
	v_mfma_f32_16x16x32_bf16 v[44:47], v[140:143], v[152:155], v[44:47]
	ds_read_b128 v[192:195], v232 offset:0
	ds_read_b128 v[196:199], v232 offset:1024
	v_mfma_f32_16x16x32_bf16 v[48:51], v[128:131], v[156:159], v[48:51]
	v_mfma_f32_16x16x32_bf16 v[52:55], v[132:135], v[156:159], v[52:55]
	v_mfma_f32_16x16x32_bf16 v[56:59], v[136:139], v[156:159], v[56:59]
	v_mfma_f32_16x16x32_bf16 v[60:63], v[140:143], v[156:159], v[60:63]
	ds_read_b128 v[200:203], v232 offset:2048
	ds_read_b128 v[204:207], v232 offset:3072
	v_mfma_f32_16x16x32_bf16 v[64:67], v[128:131], v[160:163], v[64:67]
	v_mfma_f32_16x16x32_bf16 v[68:71], v[132:135], v[160:163], v[68:71]
	v_mfma_f32_16x16x32_bf16 v[72:75], v[136:139], v[160:163], v[72:75]
	v_mfma_f32_16x16x32_bf16 v[76:79], v[140:143], v[160:163], v[76:79]
	ds_read_b128 v[208:211], v232 offset:4096
	v_mfma_f32_16x16x32_bf16 v[80:83], v[128:131], v[164:167], v[80:83]
	v_mfma_f32_16x16x32_bf16 v[84:87], v[132:135], v[164:167], v[84:87]
	v_mfma_f32_16x16x32_bf16 v[88:91], v[136:139], v[164:167], v[88:91]
	v_mfma_f32_16x16x32_bf16 v[92:95], v[140:143], v[164:167], v[92:95]
	ds_read_b128 v[212:215], v232 offset:5120
	v_mfma_f32_16x16x32_bf16 v[96:99], v[128:131], v[168:171], v[96:99]
	v_mfma_f32_16x16x32_bf16 v[100:103], v[132:135], v[168:171], v[100:103]
	v_mfma_f32_16x16x32_bf16 v[104:107], v[136:139], v[168:171], v[104:107]
	v_mfma_f32_16x16x32_bf16 v[108:111], v[140:143], v[168:171], v[108:111]
	ds_read_b128 v[216:219], v232 offset:6144
	s_cmp_eq_u32 s24, 0
	s_cbranch_scc0 .Lg11_hi4
	s_setprio 0
.Lg11_hi4:
	s_add_u32 s30, s30, 24576
	s_cmp_eq_u32 s30, 73728
	s_cselect_b32 s30, 0, s30
	v_mfma_f32_16x16x32_bf16 v[112:115], v[128:131], v[172:175], v[112:115]
	v_mfma_f32_16x16x32_bf16 v[116:119], v[132:135], v[172:175], v[116:119]
	v_mfma_f32_16x16x32_bf16 v[120:123], v[136:139], v[172:175], v[120:123]
	v_mfma_f32_16x16x32_bf16 v[124:127], v[140:143], v[172:175], v[124:127]
	ds_read_b128 v[220:223], v232 offset:7168
	s_waitcnt lgkmcnt(0)
	s_barrier
	s_setprio 1
	v_mfma_f32_16x16x32_bf16 v[0:3], v[176:179], v[192:195], v[0:3]
	v_mfma_f32_16x16x32_bf16 v[4:7], v[180:183], v[192:195], v[4:7]
	v_mfma_f32_16x16x32_bf16 v[8:11], v[184:187], v[192:195], v[8:11]
	v_mfma_f32_16x16x32_bf16 v[12:15], v[188:191], v[192:195], v[12:15]
	v_mfma_f32_16x16x32_bf16 v[16:19], v[176:179], v[196:199], v[16:19]
	v_mfma_f32_16x16x32_bf16 v[20:23], v[180:183], v[196:199], v[20:23]
	v_mfma_f32_16x16x32_bf16 v[24:27], v[184:187], v[196:199], v[24:27]
	v_mfma_f32_16x16x32_bf16 v[28:31], v[188:191], v[196:199], v[28:31]
	v_mfma_f32_16x16x32_bf16 v[32:35], v[176:179], v[200:203], v[32:35]
	v_mfma_f32_16x16x32_bf16 v[36:39], v[180:183], v[200:203], v[36:39]
	v_mfma_f32_16x16x32_bf16 v[40:43], v[184:187], v[200:203], v[40:43]
	v_mfma_f32_16x16x32_bf16 v[44:47], v[188:191], v[200:203], v[44:47]
	v_mfma_f32_16x16x32_bf16 v[48:51], v[176:179], v[204:207], v[48:51]
	v_mfma_f32_16x16x32_bf16 v[52:55], v[180:183], v[204:207], v[52:55]
	v_mfma_f32_16x16x32_bf16 v[56:59], v[184:187], v[204:207], v[56:59]
	v_mfma_f32_16x16x32_bf16 v[60:63], v[188:191], v[204:207], v[60:63]
	v_mfma_f32_16x16x32_bf16 v[64:67], v[176:179], v[208:211], v[64:67]
	v_mfma_f32_16x16x32_bf16 v[68:71], v[180:183], v[208:211], v[68:71]
	v_mfma_f32_16x16x32_bf16 v[72:75], v[184:187], v[208:211], v[72:75]
	v_mfma_f32_16x16x32_bf16 v[76:79], v[188:191], v[208:211], v[76:79]
	v_mfma_f32_16x16x32_bf16 v[80:83], v[176:179], v[212:215], v[80:83]
	v_mfma_f32_16x16x32_bf16 v[84:87], v[180:183], v[212:215], v[84:87]
	v_mfma_f32_16x16x32_bf16 v[88:91], v[184:187], v[212:215], v[88:91]
	v_mfma_f32_16x16x32_bf16 v[92:95], v[188:191], v[212:215], v[92:95]
	v_mfma_f32_16x16x32_bf16 v[96:99], v[176:179], v[216:219], v[96:99]
	v_mfma_f32_16x16x32_bf16 v[100:103], v[180:183], v[216:219], v[100:103]
	v_mfma_f32_16x16x32_bf16 v[104:107], v[184:187], v[216:219], v[104:107]
	v_mfma_f32_16x16x32_bf16 v[108:111], v[188:191], v[216:219], v[108:111]
	s_cmp_eq_u32 s24, 0
	s_cbranch_scc0 .Lg11_hi5
	s_setprio 0

; #define LWRITE(S, buf) do { bf16_t* sA_ = sbase + (buf) * BUF; bf16_t* sB_ = sA_ + 256 * PITCH; \
;     _Pragma("unroll") for (int i_ = 0; i_ < 4; ++i_) *(u32x4*)(sA_ + (sr + i_ * 64) * PITCH + scv * 8) = ra[S][i_]; \
;     _Pragma("unroll") for (int i_ = 0; i_ < 2; ++i_) *(u32x4*)(sB_ + (sr + i_ * 64) * PITCH + scv * 8) = rb[S][i_]; } while (0)
; template <class Epi>
; DI void gemm_tile(char* smem, const bf16_t* __restrict__ A0, int lda0, int ksplit, const bf16_t* __restrict__ A1, int lda1,
;                   const bf16_t* __restrict__ Bt, int K, int row0, int col0, const Epi& epi, int tid) {
;     ...
;     for (int kt = 0; kt < nk; kt += 2) {
;       LWRITE(1, 1);
;       __builtin_amdgcn_sched_barrier(0);
;       GLOAD(1, (kt + 3 < last ? kt + 3 : last));
;       __builtin_amdgcn_sched_barrier(0);
;       COMPUTE(0);
;       __syncthreads();
;       LWRITE(0, 0);
;       __builtin_amdgcn_sched_barrier(0);
;       GLOAD(0, (kt + 4 < last ? kt + 4 : last));
;       __builtin_amdgcn_sched_barrier(0);
;       COMPUTE(1);
;       __syncthreads();
;     }
.Lg14_hi1:
	s_add_u32 s0, s0, 64
	s_addc_u32 s1, s1, 0
	s_add_u32 s2, s2, 64
	s_addc_u32 s3, s3, 0
	s_add_u32 s100, s100, 1
	s_add_u32 s19, s19, 24576
	s_cmp_eq_u32 s19, 73728
	s_cselect_b32 s19, 0, s19
	s_add_u32 s98, s98, 24576
	s_cmp_eq_u32 s98, 73728
	s_cselect_b32 s98, 0, s98
	v_mfma_f32_16x16x32_bf16 v[112:115], v[176:179], v[220:223], v[112:115]
	v_mfma_f32_16x16x32_bf16 v[116:119], v[180:183], v[220:223], v[116:119]
	v_mfma_f32_16x16x32_bf16 v[120:123], v[184:187], v[220:223], v[120:123]
	v_mfma_f32_16x16x32_bf16 v[124:127], v[188:191], v[220:223], v[124:127]
	ds_read_b128 v[172:175], v232 offset:7168
	s_add_u32 s99, s99, 2
	s_cmp_lt_u32 s99, 12
	s_cbranch_scc1 .Lg14_kloop
	s_waitcnt vmcnt(6)
	s_waitcnt lgkmcnt(0)
	s_barrier
	v_add_u32_e32 v232, s98, v230
	v_add_u32_e32 v233, s98, v231
	s_add_u32 s11, s19, s101
	s_setprio 1
	v_mfma_f32_16x16x32_bf16 v[0:3], v[128:131], v[144:147], v[0:3]
	v_mfma_f32_16x16x32_bf16 v[4:7], v[132:135], v[144:147], v[4:7]
	v_mfma_f32_16x16x32_bf16 v[8:11], v[136:139], v[144:147], v[8:11]
	v_mfma_f32_16x16x32_bf16 v[12:15], v[140:143], v[144:147], v[12:15]
	ds_read_b128 v[176:179], v233 offset:0
	ds_read_b128 v[180:183], v233 offset:1024
	s_add_u32 m0, s11, 0
	s_nop 0
	global_load_lds_dwordx4 v224, s[0:1]
	v_mfma_f32_16x16x32_bf16 v[16:19], v[128:131], v[148:151], v[16:19]
	v_mfma_f32_16x16x32_bf16 v[20:23], v[132:135], v[148:151], v[20:23]
	v_mfma_f32_16x16x32_bf16 v[24:27], v[136:139], v[148:151], v[24:27]
	v_mfma_f32_16x16x32_bf16 v[28:31], v[140:143], v[148:151], v[28:31]
	ds_read_b128 v[184:187], v233 offset:2048
	ds_read_b128 v[188:191], v233 offset:3072
	s_add_u32 m0, s11, 4096
	s_nop 0
	global_load_lds_dwordx4 v225, s[0:1]
	v_mfma_f32_16x16x32_bf16 v[32:35], v[128:131], v[152:155], v[32:35]
	v_mfma_f32_16x16x32_bf16 v[36:39], v[132:135], v[152:155], v[36:39]
	v_mfma_f32_16x16x32_bf16 v[40:43], v[136:139], v[152:155], v[40:43]
	v_mfma_f32_16x16x32_bf16 v[44:47], v[140:143], v[152:155], v[44:47]
	ds_read_b128 v[192:195], v232 offset:0
	ds_read_b128 v[196:199], v232 offset:1024
	s_add_u32 m0, s11, 8192
	s_nop 0
	global_load_lds_dwordx4 v226, s[0:1]
	v_mfma_f32_16x16x32_bf16 v[48:51], v[128:131], v[156:159], v[48:51]
	v_mfma_f32_16x16x32_bf16 v[52:55], v[132:135], v[156:159], v[52:55]
	v_mfma_f32_16x16x32_bf16 v[56:59], v[136:139], v[156:159], v[56:59]
	v_mfma_f32_16x16x32_bf16 v[60:63], v[140:143], v[156:159], v[60:63]
	ds_read_b128 v[200:203], v232 offset:2048
	ds_read_b128 v[204:207], v232 offset:3072
	s_add_u32 m0, s11, 12288
	s_nop 0
	global_load_lds_dwordx4 v227, s[0:1]
	v_mfma_f32_16x16x32_bf16 v[64:67], v[128:131], v[160:163], v[64:67]
	v_mfma_f32_16x16x32_bf16 v[68:71], v[132:135], v[160:163], v[68:71]
	v_mfma_f32_16x16x32_bf16 v[72:75], v[136:139], v[160:163], v[72:75]
	v_mfma_f32_16x16x32_bf16 v[76:79], v[140:143], v[160:163], v[76:79]
	ds_read_b128 v[208:211], v232 offset:4096
	s_add_u32 m0, s11, 16384
	s_nop 0
	global_load_lds_dwordx4 v228, s[2:3]
	v_mfma_f32_16x16x32_bf16 v[80:83], v[128:131], v[164:167], v[80:83]
	v_mfma_f32_16x16x32_bf16 v[84:87], v[132:135], v[164:167], v[84:87]
	v_mfma_f32_16x16x32_bf16 v[88:91], v[136:139], v[164:167], v[88:91]
	v_mfma_f32_16x16x32_bf16 v[92:95], v[140:143], v[164:167], v[92:95]
	ds_read_b128 v[212:215], v232 offset:5120
	s_add_u32 m0, s11, 20480
	s_nop 0
	global_load_lds_dwordx4 v229, s[2:3]
	v_mfma_f32_16x16x32_bf16 v[96:99], v[128:131], v[168:171], v[96:99]
	v_mfma_f32_16x16x32_bf16 v[100:103], v[132:135], v[168:171], v[100:103]
	v_mfma_f32_16x16x32_bf16 v[104:107], v[136:139], v[168:171], v[104:107]
	v_mfma_f32_16x16x32_bf16 v[108:111], v[140:143], v[168:171], v[108:111]
	ds_read_b128 v[216:219], v232 offset:6144
	s_cmp_eq_u32 s10, 0
	s_cbranch_scc0 .Lg14_hi2
	s_setprio 0
